# mixer0: batched row loads, 4-token interleaved LN/gated-conv, packed-fma conv31
# speedup vs baseline: 1.0036x; 1.0036x over previous
; #define LAS __attribute__((address_space(3)))
; __device__ __forceinline__ v4u pack8(const float (&f)[8]) { v4u w; w.x = pk2(f[0], f[1]); w.y = pk2(f[2], f[3]); w.z = pk2(f[4], f[5]); w.w = pk2(f[6], f[7]); return w; }
; __device__ __forceinline__ void phase_mixer0(const Params& p, LAS unsigned char* lds) {
;     ...
;         for (int j = wave; j < (samp ? 38 : 62); j += 8) {
;             const int tt = t0 - 30 + j;
;             float v[8];
;             if (j < nout + 30 && tt >= 0) {
;                 unpack8(*(const v4u*)(Z + (rowbase + (tt - t0)) * NZ1 + 1024 + c8), v);
;             } else if (samp && j < 30) {
;                 load8f(st_b + ((size_t)seq * 30 + j) * 512 + c8, v);
;             } else {
; #pragma unroll
;                 for (int i = 0; i < 8; ++i) v[i] = 0.f;
;             }
;             *(LAS v4u*)(ub + j * 512 + c8) = pack8(v);
;             if (!samp) { if (tt >= SEQ - 30) store8f(o_cb_p + ((size_t)seq * 30 + (tt - (SEQ - 30))) * 512 + c8, v); }
;             else if (j >= 8 && j < 38) store8f(o_cb_s + ((size_t)seq * 30 + (j - 8)) * 512 + c8, v);
;         }
.LBB0_240:
	s_and_b64 s[2:3], s[0:1], exec
	s_cselect_b32 s56, 8, 32
	s_cselect_b32 s77, 0, s53
	s_cmp_ge_i32 s54, s9
	s_cbranch_scc1 .LBB0_259
	s_waitcnt vmcnt(1)
	v_mad_u64_u32 v[8:9], s[2:3], s55, v121, v[76:77]
	s_mul_i32 s13, s76, 30
	s_add_i32 s2, s52, s77
	s_add_i32 s12, s56, 30
	s_ashr_i32 s14, s13, 31
	s_ashr_i32 s3, s2, 31
	s_add_u32 s2, s42, s2
	s_addc_u32 s3, s43, s3
	s_sub_u32 s2, s2, s77
	s_subb_u32 s3, s3, 0
	s_mul_i32 s6, s3, 0xc00
	v_mad_u64_u32 v[10:11], s[2:3], s2, v122, v[78:79]
	v_add_u32_e32 v11, s6, v11
	s_xor_b64 s[2:3], s[0:1], -1
	v_mov_b32_e32 v12, v119
	s_mov_b32 s15, s54
	s_and_b64 vcc, exec, s[78:79]
	s_cbranch_vccz .LBB0_243
	s_add_i32 s15, s77, s54
	s_sub_i32 s15, s15, 30
	s_sub_i32 s16, 30, s54
	s_mulk_i32 s16, 0xc00
	s_mov_b32 s19, 0
	s_add_i32 s17, s15, 0
	s_cmp_lt_i32 s17, 0
	s_cselect_b32 s18, s16, 0x0
	v_lshl_add_u64 v[0:1], v[10:11], 0, s[18:19]
	global_load_dwordx4 v[16:19], v[0:1], off
	s_add_i32 s17, s15, 8
	s_cmp_lt_i32 s17, 0
	s_cselect_b32 s18, s16, 0x6000
	v_lshl_add_u64 v[0:1], v[10:11], 0, s[18:19]
	global_load_dwordx4 v[20:23], v[0:1], off
	s_add_i32 s17, s15, 16
	s_cmp_lt_i32 s17, 0
	s_cselect_b32 s18, s16, 0xc000
	v_lshl_add_u64 v[0:1], v[10:11], 0, s[18:19]
	global_load_dwordx4 v[24:27], v[0:1], off
	s_add_i32 s17, s15, 24
	s_cmp_lt_i32 s17, 0
	s_cselect_b32 s18, s16, 0x12000
	v_lshl_add_u64 v[0:1], v[10:11], 0, s[18:19]
	global_load_dwordx4 v[28:31], v[0:1], off
	s_add_i32 s17, s15, 32
	s_cmp_lt_i32 s17, 0
	s_cselect_b32 s18, s16, 0x18000
	v_lshl_add_u64 v[0:1], v[10:11], 0, s[18:19]
	global_load_dwordx4 v[32:35], v[0:1], off
	s_add_i32 s17, s15, 40
	s_cmp_lt_i32 s17, 0
	s_cselect_b32 s18, s16, 0x1e000
	v_lshl_add_u64 v[0:1], v[10:11], 0, s[18:19]
	global_load_dwordx4 v[36:39], v[0:1], off
	s_add_i32 s17, s15, 48
	s_cmp_lt_i32 s17, 0
	s_cselect_b32 s18, s16, 0x24000
	v_lshl_add_u64 v[0:1], v[10:11], 0, s[18:19]
	global_load_dwordx4 v[40:43], v[0:1], off
	s_add_i32 s17, s15, 56
	s_cmp_lt_i32 s17, 0
	s_cselect_b32 s18, s16, 0x2a000
	s_cmp_gt_i32 s54, 5
	s_cselect_b32 s18, s16, s18
	v_lshl_add_u64 v[0:1], v[10:11], 0, s[18:19]
	global_load_dwordx4 v[44:47], v[0:1], off
	v_mov_b32_e32 v4, 0
	v_mov_b32_e32 v5, 0
	v_mov_b32_e32 v6, 0
	v_mov_b32_e32 v7, 0
	s_add_i32 s17, s15, 0
	s_waitcnt vmcnt(7)
	s_cmp_lt_i32 s17, 0
	s_cbranch_scc1 .Lmx0_f1_z0
	ds_write_b128 v12, v[16:19]
	s_cmpk_lt_i32 s17, 0x7e2
	s_cbranch_scc1 .Lmx0_f1_n0
	s_mul_i32 s6, s76, 30
	s_add_i32 s6, s6, s17
	s_sub_i32 s6, s6, 0x7e2
	s_ashr_i32 s7, s6, 31
	s_lshl_b64 s[6:7], s[6:7], 11
	s_add_u32 s6, s6, 0x4488000
	s_addc_u32 s7, s7, 0
	v_lshl_add_u64 v[2:3], v[68:69], 0, s[6:7]
	v_lshlrev_b32_e32 v48, 16, v16
	v_and_b32_e32 v49, 0xffff0000, v16
	v_lshlrev_b32_e32 v50, 16, v17
	v_and_b32_e32 v51, 0xffff0000, v17
	v_lshlrev_b32_e32 v52, 16, v18
	v_and_b32_e32 v53, 0xffff0000, v18
	v_lshlrev_b32_e32 v54, 16, v19
	v_and_b32_e32 v55, 0xffff0000, v19
	global_store_dwordx4 v[2:3], v[48:51], off
	global_store_dwordx4 v[2:3], v[52:55], off offset:16
	s_branch .Lmx0_f1_n0
.Lmx0_f1_z0:
	ds_write_b128 v12, v[4:7]
.Lmx0_f1_n0:
	s_add_i32 s17, s15, 8
	s_waitcnt vmcnt(6)
	s_cmp_lt_i32 s17, 0
	s_cbranch_scc1 .Lmx0_f1_z1
	ds_write_b128 v12, v[20:23] offset:8192
	s_cmpk_lt_i32 s17, 0x7e2
	s_cbranch_scc1 .Lmx0_f1_n1
	s_mul_i32 s6, s76, 30
	s_add_i32 s6, s6, s17
	s_sub_i32 s6, s6, 0x7e2
	s_ashr_i32 s7, s6, 31
	s_lshl_b64 s[6:7], s[6:7], 11
	s_add_u32 s6, s6, 0x4488000
	s_addc_u32 s7, s7, 0
	v_lshl_add_u64 v[2:3], v[68:69], 0, s[6:7]
	v_lshlrev_b32_e32 v48, 16, v20
	v_and_b32_e32 v49, 0xffff0000, v20
	v_lshlrev_b32_e32 v50, 16, v21
	v_and_b32_e32 v51, 0xffff0000, v21
	v_lshlrev_b32_e32 v52, 16, v22
	v_and_b32_e32 v53, 0xffff0000, v22
	v_lshlrev_b32_e32 v54, 16, v23
	v_and_b32_e32 v55, 0xffff0000, v23
	global_store_dwordx4 v[2:3], v[48:51], off
	global_store_dwordx4 v[2:3], v[52:55], off offset:16
	s_branch .Lmx0_f1_n1
.Lmx0_f1_z1:
	ds_write_b128 v12, v[4:7] offset:8192
.Lmx0_f1_n1:
	s_add_i32 s17, s15, 16
	s_waitcnt vmcnt(5)
	s_cmp_lt_i32 s17, 0
	s_cbranch_scc1 .Lmx0_f1_z2
	ds_write_b128 v12, v[24:27] offset:16384
	s_cmpk_lt_i32 s17, 0x7e2
	s_cbranch_scc1 .Lmx0_f1_n2
	s_mul_i32 s6, s76, 30
	s_add_i32 s6, s6, s17
	s_sub_i32 s6, s6, 0x7e2
	s_ashr_i32 s7, s6, 31
	s_lshl_b64 s[6:7], s[6:7], 11
	s_add_u32 s6, s6, 0x4488000
	s_addc_u32 s7, s7, 0
	v_lshl_add_u64 v[2:3], v[68:69], 0, s[6:7]
	v_lshlrev_b32_e32 v48, 16, v24
	v_and_b32_e32 v49, 0xffff0000, v24
	v_lshlrev_b32_e32 v50, 16, v25
	v_and_b32_e32 v51, 0xffff0000, v25
	v_lshlrev_b32_e32 v52, 16, v26
	v_and_b32_e32 v53, 0xffff0000, v26
	v_lshlrev_b32_e32 v54, 16, v27
	v_and_b32_e32 v55, 0xffff0000, v27
	global_store_dwordx4 v[2:3], v[48:51], off
	global_store_dwordx4 v[2:3], v[52:55], off offset:16
	s_branch .Lmx0_f1_n2
; #define LAS __attribute__((address_space(3)))
; __device__ __forceinline__ v4u pack8(const float (&f)[8]) { v4u w; w.x = pk2(f[0], f[1]); w.y = pk2(f[2], f[3]); w.z = pk2(f[4], f[5]); w.w = pk2(f[6], f[7]); return w; }
; __device__ __forceinline__ void phase_mixer0(const Params& p, LAS unsigned char* lds) {
;     ...
;         for (int j = wave; j < (samp ? 38 : 62); j += 8) {
;             const int tt = t0 - 30 + j;
;             float v[8];
;             if (j < nout + 30 && tt >= 0) {
;                 unpack8(*(const v4u*)(Z + (rowbase + (tt - t0)) * NZ1 + 1024 + c8), v);
;             } else if (samp && j < 30) {
;                 load8f(st_b + ((size_t)seq * 30 + j) * 512 + c8, v);
;             } else {
; #pragma unroll
;                 for (int i = 0; i < 8; ++i) v[i] = 0.f;
;             }
;             *(LAS v4u*)(ub + j * 512 + c8) = pack8(v);
;             if (!samp) { if (tt >= SEQ - 30) store8f(o_cb_p + ((size_t)seq * 30 + (tt - (SEQ - 30))) * 512 + c8, v); }
;             else if (j >= 8 && j < 38) store8f(o_cb_s + ((size_t)seq * 30 + (j - 8)) * 512 + c8, v);
;         }
.Lmx0_f1_z2:
	ds_write_b128 v12, v[4:7] offset:16384
.Lmx0_f1_n2:
	s_add_i32 s17, s15, 24
	s_waitcnt vmcnt(4)
	s_cmp_lt_i32 s17, 0
	s_cbranch_scc1 .Lmx0_f1_z3
	ds_write_b128 v12, v[28:31] offset:24576
	s_cmpk_lt_i32 s17, 0x7e2
	s_cbranch_scc1 .Lmx0_f1_n3
	s_mul_i32 s6, s76, 30
	s_add_i32 s6, s6, s17
	s_sub_i32 s6, s6, 0x7e2
	s_ashr_i32 s7, s6, 31
	s_lshl_b64 s[6:7], s[6:7], 11
	s_add_u32 s6, s6, 0x4488000
	s_addc_u32 s7, s7, 0
	v_lshl_add_u64 v[2:3], v[68:69], 0, s[6:7]
	v_lshlrev_b32_e32 v48, 16, v28
	v_and_b32_e32 v49, 0xffff0000, v28
	v_lshlrev_b32_e32 v50, 16, v29
	v_and_b32_e32 v51, 0xffff0000, v29
	v_lshlrev_b32_e32 v52, 16, v30
	v_and_b32_e32 v53, 0xffff0000, v30
	v_lshlrev_b32_e32 v54, 16, v31
	v_and_b32_e32 v55, 0xffff0000, v31
	global_store_dwordx4 v[2:3], v[48:51], off
	global_store_dwordx4 v[2:3], v[52:55], off offset:16
	s_branch .Lmx0_f1_n3
.Lmx0_f1_z3:
	ds_write_b128 v12, v[4:7] offset:24576
.Lmx0_f1_n3:
	s_add_i32 s17, s15, 32
	s_waitcnt vmcnt(3)
	s_cmp_lt_i32 s17, 0
	s_cbranch_scc1 .Lmx0_f1_z4
	ds_write_b128 v12, v[32:35] offset:32768
	s_cmpk_lt_i32 s17, 0x7e2
	s_cbranch_scc1 .Lmx0_f1_n4
	s_mul_i32 s6, s76, 30
	s_add_i32 s6, s6, s17
	s_sub_i32 s6, s6, 0x7e2
	s_ashr_i32 s7, s6, 31
	s_lshl_b64 s[6:7], s[6:7], 11
	s_add_u32 s6, s6, 0x4488000
	s_addc_u32 s7, s7, 0
	v_lshl_add_u64 v[2:3], v[68:69], 0, s[6:7]
	v_lshlrev_b32_e32 v48, 16, v32
	v_and_b32_e32 v49, 0xffff0000, v32
	v_lshlrev_b32_e32 v50, 16, v33
	v_and_b32_e32 v51, 0xffff0000, v33
	v_lshlrev_b32_e32 v52, 16, v34
	v_and_b32_e32 v53, 0xffff0000, v34
	v_lshlrev_b32_e32 v54, 16, v35
	v_and_b32_e32 v55, 0xffff0000, v35
	global_store_dwordx4 v[2:3], v[48:51], off
	global_store_dwordx4 v[2:3], v[52:55], off offset:16
	s_branch .Lmx0_f1_n4
.Lmx0_f1_z4:
	ds_write_b128 v12, v[4:7] offset:32768
.Lmx0_f1_n4:
	s_add_i32 s17, s15, 40
	s_waitcnt vmcnt(2)
	s_cmp_lt_i32 s17, 0
	s_cbranch_scc1 .Lmx0_f1_z5
	ds_write_b128 v12, v[36:39] offset:40960
	s_cmpk_lt_i32 s17, 0x7e2
	s_cbranch_scc1 .Lmx0_f1_n5
	s_mul_i32 s6, s76, 30
	s_add_i32 s6, s6, s17
	s_sub_i32 s6, s6, 0x7e2
	s_ashr_i32 s7, s6, 31
	s_lshl_b64 s[6:7], s[6:7], 11
	s_add_u32 s6, s6, 0x4488000
	s_addc_u32 s7, s7, 0
	v_lshl_add_u64 v[2:3], v[68:69], 0, s[6:7]
	v_lshlrev_b32_e32 v48, 16, v36
	v_and_b32_e32 v49, 0xffff0000, v36
	v_lshlrev_b32_e32 v50, 16, v37
	v_and_b32_e32 v51, 0xffff0000, v37
	v_lshlrev_b32_e32 v52, 16, v38
	v_and_b32_e32 v53, 0xffff0000, v38
	v_lshlrev_b32_e32 v54, 16, v39
	v_and_b32_e32 v55, 0xffff0000, v39
	global_store_dwordx4 v[2:3], v[48:51], off
	global_store_dwordx4 v[2:3], v[52:55], off offset:16
	s_branch .Lmx0_f1_n5
.Lmx0_f1_z5:
	ds_write_b128 v12, v[4:7] offset:40960
.Lmx0_f1_n5:
	s_add_i32 s17, s15, 48
	s_waitcnt vmcnt(1)
	s_cmp_lt_i32 s17, 0
	s_cbranch_scc1 .Lmx0_f1_z6
	ds_write_b128 v12, v[40:43] offset:49152
	s_cmpk_lt_i32 s17, 0x7e2
	s_cbranch_scc1 .Lmx0_f1_n6
	s_mul_i32 s6, s76, 30
	s_add_i32 s6, s6, s17
	s_sub_i32 s6, s6, 0x7e2
	s_ashr_i32 s7, s6, 31
	s_lshl_b64 s[6:7], s[6:7], 11
	s_add_u32 s6, s6, 0x4488000
	s_addc_u32 s7, s7, 0
	v_lshl_add_u64 v[2:3], v[68:69], 0, s[6:7]
	v_lshlrev_b32_e32 v48, 16, v40
	v_and_b32_e32 v49, 0xffff0000, v40
	v_lshlrev_b32_e32 v50, 16, v41
	v_and_b32_e32 v51, 0xffff0000, v41
	v_lshlrev_b32_e32 v52, 16, v42
	v_and_b32_e32 v53, 0xffff0000, v42
	v_lshlrev_b32_e32 v54, 16, v43
	v_and_b32_e32 v55, 0xffff0000, v43
	global_store_dwordx4 v[2:3], v[48:51], off
	global_store_dwordx4 v[2:3], v[52:55], off offset:16
	s_branch .Lmx0_f1_n6
.Lmx0_f1_z6:
	ds_write_b128 v12, v[4:7] offset:49152
.Lmx0_f1_n6:
	s_add_i32 s17, s15, 56
	s_waitcnt vmcnt(0)
	s_cmp_gt_i32 s54, 5
	s_cbranch_scc1 .Lmx0_f1_done
	s_cmp_lt_i32 s17, 0
	s_cbranch_scc1 .Lmx0_f1_z7
	ds_write_b128 v12, v[44:47] offset:57344
	s_cmpk_lt_i32 s17, 0x7e2
	s_cbranch_scc1 .Lmx0_f1_n7
	s_mul_i32 s6, s76, 30
	s_add_i32 s6, s6, s17
	s_sub_i32 s6, s6, 0x7e2
	s_ashr_i32 s7, s6, 31
	s_lshl_b64 s[6:7], s[6:7], 11
	s_add_u32 s6, s6, 0x4488000
	s_addc_u32 s7, s7, 0
	v_lshl_add_u64 v[2:3], v[68:69], 0, s[6:7]
	v_lshlrev_b32_e32 v48, 16, v44
	v_and_b32_e32 v49, 0xffff0000, v44
	v_lshlrev_b32_e32 v50, 16, v45
	v_and_b32_e32 v51, 0xffff0000, v45
	v_lshlrev_b32_e32 v52, 16, v46
	v_and_b32_e32 v53, 0xffff0000, v46
	v_lshlrev_b32_e32 v54, 16, v47
	v_and_b32_e32 v55, 0xffff0000, v47
	global_store_dwordx4 v[2:3], v[48:51], off
	global_store_dwordx4 v[2:3], v[52:55], off offset:16
	s_branch .Lmx0_f1_n7
.Lmx0_f1_z7:
	ds_write_b128 v12, v[4:7] offset:57344
.Lmx0_f1_n7:
.Lmx0_f1_done:
	s_branch .LBB0_259
	s_branch .LBB0_243

; __device__ __forceinline__ void phase_mixer0(const Params& p, LAS unsigned char* lds) {
;     ...
;         if (!samp) {
;             float acc[32];
; #pragma unroll
;             for (int t = 0; t < 32; ++t) acc[t] = bias;
; #pragma unroll
;             for (int j = 0; j < 62; ++j) {
;                 const float v = __uint_as_float((unsigned)ub[j * 512 + tid] << 16);
; #pragma unroll
;                 for (int t = 0; t < 32; ++t) { if (j - t >= 0 && j - t <= 30) acc[t] += v * wb[j - t]; }
;             }
; #pragma unroll
;             for (int t = 0; t < 32; ++t) cb[t * 512 + tid] = acc[t];
.LBB0_259:
	s_waitcnt lgkmcnt(0)
	s_barrier
	s_waitcnt vmcnt(0)
	v_mov_b32_e32 v143, v84
	v_mov_b32_e32 v144, v85
	v_mov_b32_e32 v145, v86
	v_mov_b32_e32 v146, v87
	v_mov_b32_e32 v147, v88
	v_mov_b32_e32 v148, v89
	v_mov_b32_e32 v149, v90
	v_mov_b32_e32 v150, v91
	v_mov_b32_e32 v151, v92
	v_mov_b32_e32 v152, v93
	v_mov_b32_e32 v153, v94
	v_mov_b32_e32 v154, v95
	v_mov_b32_e32 v155, v96
	v_mov_b32_e32 v156, v97
	v_mov_b32_e32 v157, v98
	v_mov_b32_e32 v158, v99
	v_mov_b32_e32 v159, v100
	v_mov_b32_e32 v160, v101
	v_mov_b32_e32 v161, v102
	v_mov_b32_e32 v162, v103
	v_mov_b32_e32 v163, v104
	v_mov_b32_e32 v164, v105
	v_mov_b32_e32 v165, v106
	v_mov_b32_e32 v166, v107
	v_mov_b32_e32 v167, v108
	v_mov_b32_e32 v168, v109
	v_mov_b32_e32 v169, v110
	v_mov_b32_e32 v170, v111
	v_mov_b32_e32 v171, v112
	v_mov_b32_e32 v172, v113
	v_mov_b32_e32 v173, v114
	s_and_b64 vcc, exec, s[78:79]
	s_cbranch_vccz .Lmx0_conv_s
	ds_read_u16 v34, v116
	ds_read_u16 v35, v116 offset:1024
	ds_read_u16 v36, v116 offset:2048
	ds_read_u16 v37, v116 offset:3072
	ds_read_u16 v38, v116 offset:4096
	ds_read_u16 v39, v116 offset:5120
	ds_read_u16 v40, v116 offset:6144
	ds_read_u16 v41, v116 offset:7168
	s_waitcnt lgkmcnt(7)
	v_lshlrev_b32_e32 v32, 16, v34
	ds_read_u16 v34, v116 offset:8192
	v_fma_f32 v0, v32, v84, v115
	v_mov_b32_e32 v1, v115
	s_waitcnt lgkmcnt(7)
	v_lshlrev_b32_e32 v32, 16, v35
	ds_read_u16 v35, v116 offset:9216
	v_pk_fma_f32 v[0:1], v[32:33], v[84:85], v[0:1] op_sel:[0,1,0] op_sel_hi:[0,0,1]
	s_waitcnt lgkmcnt(7)
	v_lshlrev_b32_e32 v32, 16, v36
	ds_read_u16 v36, v116 offset:10240
	v_pk_fma_f32 v[0:1], v[32:33], v[144:145], v[0:1] op_sel:[0,1,0] op_sel_hi:[0,0,1]
	v_fma_f32 v2, v32, v84, v115
	v_mov_b32_e32 v3, v115
	s_waitcnt lgkmcnt(7)
	v_lshlrev_b32_e32 v32, 16, v37
	ds_read_u16 v37, v116 offset:11264
	v_pk_fma_f32 v[0:1], v[32:33], v[86:87], v[0:1] op_sel:[0,1,0] op_sel_hi:[0,0,1]
	v_pk_fma_f32 v[2:3], v[32:33], v[84:85], v[2:3] op_sel:[0,1,0] op_sel_hi:[0,0,1]
	s_waitcnt lgkmcnt(7)
	v_lshlrev_b32_e32 v32, 16, v38
	ds_read_u16 v38, v116 offset:12288
	v_pk_fma_f32 v[0:1], v[32:33], v[146:147], v[0:1] op_sel:[0,1,0] op_sel_hi:[0,0,1]
	v_pk_fma_f32 v[2:3], v[32:33], v[144:145], v[2:3] op_sel:[0,1,0] op_sel_hi:[0,0,1]
	v_fma_f32 v4, v32, v84, v115
	v_mov_b32_e32 v5, v115
	s_waitcnt lgkmcnt(7)
	v_lshlrev_b32_e32 v32, 16, v39
	ds_read_u16 v39, v116 offset:13312
	v_pk_fma_f32 v[0:1], v[32:33], v[88:89], v[0:1] op_sel:[0,1,0] op_sel_hi:[0,0,1]
	v_pk_fma_f32 v[2:3], v[32:33], v[86:87], v[2:3] op_sel:[0,1,0] op_sel_hi:[0,0,1]
	v_pk_fma_f32 v[4:5], v[32:33], v[84:85], v[4:5] op_sel:[0,1,0] op_sel_hi:[0,0,1]
	s_waitcnt lgkmcnt(7)
	v_lshlrev_b32_e32 v32, 16, v40
	ds_read_u16 v40, v116 offset:14336
	v_pk_fma_f32 v[0:1], v[32:33], v[148:149], v[0:1] op_sel:[0,1,0] op_sel_hi:[0,0,1]
	v_pk_fma_f32 v[2:3], v[32:33], v[146:147], v[2:3] op_sel:[0,1,0] op_sel_hi:[0,0,1]
	v_pk_fma_f32 v[4:5], v[32:33], v[144:145], v[4:5] op_sel:[0,1,0] op_sel_hi:[0,0,1]
	v_fma_f32 v6, v32, v84, v115
	v_mov_b32_e32 v7, v115
	s_waitcnt lgkmcnt(7)
	v_lshlrev_b32_e32 v32, 16, v41
	ds_read_u16 v41, v116 offset:15360
	v_pk_fma_f32 v[0:1], v[32:33], v[90:91], v[0:1] op_sel:[0,1,0] op_sel_hi:[0,0,1]
	v_pk_fma_f32 v[2:3], v[32:33], v[88:89], v[2:3] op_sel:[0,1,0] op_sel_hi:[0,0,1]
	v_pk_fma_f32 v[4:5], v[32:33], v[86:87], v[4:5] op_sel:[0,1,0] op_sel_hi:[0,0,1]
	v_pk_fma_f32 v[6:7], v[32:33], v[84:85], v[6:7] op_sel:[0,1,0] op_sel_hi:[0,0,1]
	s_waitcnt lgkmcnt(7)
	v_lshlrev_b32_e32 v32, 16, v34
	ds_read_u16 v34, v116 offset:16384
	v_pk_fma_f32 v[0:1], v[32:33], v[150:151], v[0:1] op_sel:[0,1,0] op_sel_hi:[0,0,1]
	v_pk_fma_f32 v[2:3], v[32:33], v[148:149], v[2:3] op_sel:[0,1,0] op_sel_hi:[0,0,1]
	v_pk_fma_f32 v[4:5], v[32:33], v[146:147], v[4:5] op_sel:[0,1,0] op_sel_hi:[0,0,1]
	v_pk_fma_f32 v[6:7], v[32:33], v[144:145], v[6:7] op_sel:[0,1,0] op_sel_hi:[0,0,1]
	v_fma_f32 v8, v32, v84, v115
	v_mov_b32_e32 v9, v115
	s_waitcnt lgkmcnt(7)
	v_lshlrev_b32_e32 v32, 16, v35
	ds_read_u16 v35, v116 offset:17408
	v_pk_fma_f32 v[0:1], v[32:33], v[92:93], v[0:1] op_sel:[0,1,0] op_sel_hi:[0,0,1]
	v_pk_fma_f32 v[2:3], v[32:33], v[90:91], v[2:3] op_sel:[0,1,0] op_sel_hi:[0,0,1]
	v_pk_fma_f32 v[4:5], v[32:33], v[88:89], v[4:5] op_sel:[0,1,0] op_sel_hi:[0,0,1]
	v_pk_fma_f32 v[6:7], v[32:33], v[86:87], v[6:7] op_sel:[0,1,0] op_sel_hi:[0,0,1]
	v_pk_fma_f32 v[8:9], v[32:33], v[84:85], v[8:9] op_sel:[0,1,0] op_sel_hi:[0,0,1]
	s_waitcnt lgkmcnt(7)
	v_lshlrev_b32_e32 v32, 16, v36
	ds_read_u16 v36, v116 offset:18432
	v_pk_fma_f32 v[0:1], v[32:33], v[152:153], v[0:1] op_sel:[0,1,0] op_sel_hi:[0,0,1]
	v_pk_fma_f32 v[2:3], v[32:33], v[150:151], v[2:3] op_sel:[0,1,0] op_sel_hi:[0,0,1]
	v_pk_fma_f32 v[4:5], v[32:33], v[148:149], v[4:5] op_sel:[0,1,0] op_sel_hi:[0,0,1]
	v_pk_fma_f32 v[6:7], v[32:33], v[146:147], v[6:7] op_sel:[0,1,0] op_sel_hi:[0,0,1]
	v_pk_fma_f32 v[8:9], v[32:33], v[144:145], v[8:9] op_sel:[0,1,0] op_sel_hi:[0,0,1]
	v_fma_f32 v10, v32, v84, v115
	v_mov_b32_e32 v11, v115
	s_waitcnt lgkmcnt(7)
	v_lshlrev_b32_e32 v32, 16, v37
	ds_read_u16 v37, v116 offset:19456
	v_pk_fma_f32 v[0:1], v[32:33], v[94:95], v[0:1] op_sel:[0,1,0] op_sel_hi:[0,0,1]
	v_pk_fma_f32 v[2:3], v[32:33], v[92:93], v[2:3] op_sel:[0,1,0] op_sel_hi:[0,0,1]
	v_pk_fma_f32 v[4:5], v[32:33], v[90:91], v[4:5] op_sel:[0,1,0] op_sel_hi:[0,0,1]
	v_pk_fma_f32 v[6:7], v[32:33], v[88:89], v[6:7] op_sel:[0,1,0] op_sel_hi:[0,0,1]
	v_pk_fma_f32 v[8:9], v[32:33], v[86:87], v[8:9] op_sel:[0,1,0] op_sel_hi:[0,0,1]
	v_pk_fma_f32 v[10:11], v[32:33], v[84:85], v[10:11] op_sel:[0,1,0] op_sel_hi:[0,0,1]
	s_waitcnt lgkmcnt(7)
; __device__ __forceinline__ void phase_mixer0(const Params& p, LAS unsigned char* lds) {
;     ...
;             float acc[32];
; #pragma unroll
;             for (int t = 0; t < 32; ++t) acc[t] = bias;
; #pragma unroll
;             for (int j = 0; j < 62; ++j) {
;                 const float v = __uint_as_float((unsigned)ub[j * 512 + tid] << 16);
; #pragma unroll
;                 for (int t = 0; t < 32; ++t) { if (j - t >= 0 && j - t <= 30) acc[t] += v * wb[j - t]; }
;             }
; #pragma unroll
;             for (int t = 0; t < 32; ++t) cb[t * 512 + tid] = acc[t];
	v_lshlrev_b32_e32 v32, 16, v38
	ds_read_u16 v38, v116 offset:20480
	v_pk_fma_f32 v[0:1], v[32:33], v[154:155], v[0:1] op_sel:[0,1,0] op_sel_hi:[0,0,1]
	v_pk_fma_f32 v[2:3], v[32:33], v[152:153], v[2:3] op_sel:[0,1,0] op_sel_hi:[0,0,1]
	v_pk_fma_f32 v[4:5], v[32:33], v[150:151], v[4:5] op_sel:[0,1,0] op_sel_hi:[0,0,1]
	v_pk_fma_f32 v[6:7], v[32:33], v[148:149], v[6:7] op_sel:[0,1,0] op_sel_hi:[0,0,1]
	v_pk_fma_f32 v[8:9], v[32:33], v[146:147], v[8:9] op_sel:[0,1,0] op_sel_hi:[0,0,1]
	v_pk_fma_f32 v[10:11], v[32:33], v[144:145], v[10:11] op_sel:[0,1,0] op_sel_hi:[0,0,1]
	v_fma_f32 v12, v32, v84, v115
	v_mov_b32_e32 v13, v115
	s_waitcnt lgkmcnt(7)
	v_lshlrev_b32_e32 v32, 16, v39
	ds_read_u16 v39, v116 offset:21504
	v_pk_fma_f32 v[0:1], v[32:33], v[96:97], v[0:1] op_sel:[0,1,0] op_sel_hi:[0,0,1]
	v_pk_fma_f32 v[2:3], v[32:33], v[94:95], v[2:3] op_sel:[0,1,0] op_sel_hi:[0,0,1]
	v_pk_fma_f32 v[4:5], v[32:33], v[92:93], v[4:5] op_sel:[0,1,0] op_sel_hi:[0,0,1]
	v_pk_fma_f32 v[6:7], v[32:33], v[90:91], v[6:7] op_sel:[0,1,0] op_sel_hi:[0,0,1]
	v_pk_fma_f32 v[8:9], v[32:33], v[88:89], v[8:9] op_sel:[0,1,0] op_sel_hi:[0,0,1]
	v_pk_fma_f32 v[10:11], v[32:33], v[86:87], v[10:11] op_sel:[0,1,0] op_sel_hi:[0,0,1]
	v_pk_fma_f32 v[12:13], v[32:33], v[84:85], v[12:13] op_sel:[0,1,0] op_sel_hi:[0,0,1]
	s_waitcnt lgkmcnt(7)
	v_lshlrev_b32_e32 v32, 16, v40
	ds_read_u16 v40, v116 offset:22528
	v_pk_fma_f32 v[0:1], v[32:33], v[156:157], v[0:1] op_sel:[0,1,0] op_sel_hi:[0,0,1]
	v_pk_fma_f32 v[2:3], v[32:33], v[154:155], v[2:3] op_sel:[0,1,0] op_sel_hi:[0,0,1]
	v_pk_fma_f32 v[4:5], v[32:33], v[152:153], v[4:5] op_sel:[0,1,0] op_sel_hi:[0,0,1]
	v_pk_fma_f32 v[6:7], v[32:33], v[150:151], v[6:7] op_sel:[0,1,0] op_sel_hi:[0,0,1]
	v_pk_fma_f32 v[8:9], v[32:33], v[148:149], v[8:9] op_sel:[0,1,0] op_sel_hi:[0,0,1]
	v_pk_fma_f32 v[10:11], v[32:33], v[146:147], v[10:11] op_sel:[0,1,0] op_sel_hi:[0,0,1]
	v_pk_fma_f32 v[12:13], v[32:33], v[144:145], v[12:13] op_sel:[0,1,0] op_sel_hi:[0,0,1]
	v_fma_f32 v14, v32, v84, v115
	v_mov_b32_e32 v15, v115
	s_waitcnt lgkmcnt(7)
	v_lshlrev_b32_e32 v32, 16, v41
	ds_read_u16 v41, v116 offset:23552
	v_pk_fma_f32 v[0:1], v[32:33], v[98:99], v[0:1] op_sel:[0,1,0] op_sel_hi:[0,0,1]
	v_pk_fma_f32 v[2:3], v[32:33], v[96:97], v[2:3] op_sel:[0,1,0] op_sel_hi:[0,0,1]
	v_pk_fma_f32 v[4:5], v[32:33], v[94:95], v[4:5] op_sel:[0,1,0] op_sel_hi:[0,0,1]
	v_pk_fma_f32 v[6:7], v[32:33], v[92:93], v[6:7] op_sel:[0,1,0] op_sel_hi:[0,0,1]
	v_pk_fma_f32 v[8:9], v[32:33], v[90:91], v[8:9] op_sel:[0,1,0] op_sel_hi:[0,0,1]
	v_pk_fma_f32 v[10:11], v[32:33], v[88:89], v[10:11] op_sel:[0,1,0] op_sel_hi:[0,0,1]
	v_pk_fma_f32 v[12:13], v[32:33], v[86:87], v[12:13] op_sel:[0,1,0] op_sel_hi:[0,0,1]
	v_pk_fma_f32 v[14:15], v[32:33], v[84:85], v[14:15] op_sel:[0,1,0] op_sel_hi:[0,0,1]
	s_waitcnt lgkmcnt(7)
	v_lshlrev_b32_e32 v32, 16, v34
	ds_read_u16 v34, v116 offset:24576
	v_pk_fma_f32 v[0:1], v[32:33], v[158:159], v[0:1] op_sel:[0,1,0] op_sel_hi:[0,0,1]
	v_pk_fma_f32 v[2:3], v[32:33], v[156:157], v[2:3] op_sel:[0,1,0] op_sel_hi:[0,0,1]
	v_pk_fma_f32 v[4:5], v[32:33], v[154:155], v[4:5] op_sel:[0,1,0] op_sel_hi:[0,0,1]
	v_pk_fma_f32 v[6:7], v[32:33], v[152:153], v[6:7] op_sel:[0,1,0] op_sel_hi:[0,0,1]
	v_pk_fma_f32 v[8:9], v[32:33], v[150:151], v[8:9] op_sel:[0,1,0] op_sel_hi:[0,0,1]
	v_pk_fma_f32 v[10:11], v[32:33], v[148:149], v[10:11] op_sel:[0,1,0] op_sel_hi:[0,0,1]
	v_pk_fma_f32 v[12:13], v[32:33], v[146:147], v[12:13] op_sel:[0,1,0] op_sel_hi:[0,0,1]
	v_pk_fma_f32 v[14:15], v[32:33], v[144:145], v[14:15] op_sel:[0,1,0] op_sel_hi:[0,0,1]
	v_fma_f32 v16, v32, v84, v115
	v_mov_b32_e32 v17, v115
	s_waitcnt lgkmcnt(7)
	v_lshlrev_b32_e32 v32, 16, v35
	ds_read_u16 v35, v116 offset:25600
	v_pk_fma_f32 v[0:1], v[32:33], v[100:101], v[0:1] op_sel:[0,1,0] op_sel_hi:[0,0,1]
	v_pk_fma_f32 v[2:3], v[32:33], v[98:99], v[2:3] op_sel:[0,1,0] op_sel_hi:[0,0,1]
	v_pk_fma_f32 v[4:5], v[32:33], v[96:97], v[4:5] op_sel:[0,1,0] op_sel_hi:[0,0,1]
	v_pk_fma_f32 v[6:7], v[32:33], v[94:95], v[6:7] op_sel:[0,1,0] op_sel_hi:[0,0,1]
	v_pk_fma_f32 v[8:9], v[32:33], v[92:93], v[8:9] op_sel:[0,1,0] op_sel_hi:[0,0,1]
	v_pk_fma_f32 v[10:11], v[32:33], v[90:91], v[10:11] op_sel:[0,1,0] op_sel_hi:[0,0,1]
	v_pk_fma_f32 v[12:13], v[32:33], v[88:89], v[12:13] op_sel:[0,1,0] op_sel_hi:[0,0,1]
	v_pk_fma_f32 v[14:15], v[32:33], v[86:87], v[14:15] op_sel:[0,1,0] op_sel_hi:[0,0,1]
	v_pk_fma_f32 v[16:17], v[32:33], v[84:85], v[16:17] op_sel:[0,1,0] op_sel_hi:[0,0,1]
	s_waitcnt lgkmcnt(7)
	v_lshlrev_b32_e32 v32, 16, v36
	ds_read_u16 v36, v116 offset:26624
	v_pk_fma_f32 v[0:1], v[32:33], v[160:161], v[0:1] op_sel:[0,1,0] op_sel_hi:[0,0,1]
	v_pk_fma_f32 v[2:3], v[32:33], v[158:159], v[2:3] op_sel:[0,1,0] op_sel_hi:[0,0,1]
	v_pk_fma_f32 v[4:5], v[32:33], v[156:157], v[4:5] op_sel:[0,1,0] op_sel_hi:[0,0,1]
	v_pk_fma_f32 v[6:7], v[32:33], v[154:155], v[6:7] op_sel:[0,1,0] op_sel_hi:[0,0,1]
	v_pk_fma_f32 v[8:9], v[32:33], v[152:153], v[8:9] op_sel:[0,1,0] op_sel_hi:[0,0,1]
	v_pk_fma_f32 v[10:11], v[32:33], v[150:151], v[10:11] op_sel:[0,1,0] op_sel_hi:[0,0,1]
	v_pk_fma_f32 v[12:13], v[32:33], v[148:149], v[12:13] op_sel:[0,1,0] op_sel_hi:[0,0,1]
	v_pk_fma_f32 v[14:15], v[32:33], v[146:147], v[14:15] op_sel:[0,1,0] op_sel_hi:[0,0,1]
	v_pk_fma_f32 v[16:17], v[32:33], v[144:145], v[16:17] op_sel:[0,1,0] op_sel_hi:[0,0,1]
	v_fma_f32 v18, v32, v84, v115
	v_mov_b32_e32 v19, v115
	s_waitcnt lgkmcnt(7)
; __device__ __forceinline__ void phase_mixer0(const Params& p, LAS unsigned char* lds) {
;     ...
;             float acc[32];
; #pragma unroll
;             for (int t = 0; t < 32; ++t) acc[t] = bias;
; #pragma unroll
;             for (int j = 0; j < 62; ++j) {
;                 const float v = __uint_as_float((unsigned)ub[j * 512 + tid] << 16);
; #pragma unroll
;                 for (int t = 0; t < 32; ++t) { if (j - t >= 0 && j - t <= 30) acc[t] += v * wb[j - t]; }
;             }
; #pragma unroll
;             for (int t = 0; t < 32; ++t) cb[t * 512 + tid] = acc[t];
	v_lshlrev_b32_e32 v32, 16, v37
	ds_read_u16 v37, v116 offset:27648
	v_pk_fma_f32 v[0:1], v[32:33], v[102:103], v[0:1] op_sel:[0,1,0] op_sel_hi:[0,0,1]
	v_pk_fma_f32 v[2:3], v[32:33], v[100:101], v[2:3] op_sel:[0,1,0] op_sel_hi:[0,0,1]
	v_pk_fma_f32 v[4:5], v[32:33], v[98:99], v[4:5] op_sel:[0,1,0] op_sel_hi:[0,0,1]
	v_pk_fma_f32 v[6:7], v[32:33], v[96:97], v[6:7] op_sel:[0,1,0] op_sel_hi:[0,0,1]
	v_pk_fma_f32 v[8:9], v[32:33], v[94:95], v[8:9] op_sel:[0,1,0] op_sel_hi:[0,0,1]
	v_pk_fma_f32 v[10:11], v[32:33], v[92:93], v[10:11] op_sel:[0,1,0] op_sel_hi:[0,0,1]
	v_pk_fma_f32 v[12:13], v[32:33], v[90:91], v[12:13] op_sel:[0,1,0] op_sel_hi:[0,0,1]
	v_pk_fma_f32 v[14:15], v[32:33], v[88:89], v[14:15] op_sel:[0,1,0] op_sel_hi:[0,0,1]
	v_pk_fma_f32 v[16:17], v[32:33], v[86:87], v[16:17] op_sel:[0,1,0] op_sel_hi:[0,0,1]
	v_pk_fma_f32 v[18:19], v[32:33], v[84:85], v[18:19] op_sel:[0,1,0] op_sel_hi:[0,0,1]
	s_waitcnt lgkmcnt(7)
	v_lshlrev_b32_e32 v32, 16, v38
	ds_read_u16 v38, v116 offset:28672
	v_pk_fma_f32 v[0:1], v[32:33], v[162:163], v[0:1] op_sel:[0,1,0] op_sel_hi:[0,0,1]
	v_pk_fma_f32 v[2:3], v[32:33], v[160:161], v[2:3] op_sel:[0,1,0] op_sel_hi:[0,0,1]
	v_pk_fma_f32 v[4:5], v[32:33], v[158:159], v[4:5] op_sel:[0,1,0] op_sel_hi:[0,0,1]
	v_pk_fma_f32 v[6:7], v[32:33], v[156:157], v[6:7] op_sel:[0,1,0] op_sel_hi:[0,0,1]
	v_pk_fma_f32 v[8:9], v[32:33], v[154:155], v[8:9] op_sel:[0,1,0] op_sel_hi:[0,0,1]
	v_pk_fma_f32 v[10:11], v[32:33], v[152:153], v[10:11] op_sel:[0,1,0] op_sel_hi:[0,0,1]
	v_pk_fma_f32 v[12:13], v[32:33], v[150:151], v[12:13] op_sel:[0,1,0] op_sel_hi:[0,0,1]
	v_pk_fma_f32 v[14:15], v[32:33], v[148:149], v[14:15] op_sel:[0,1,0] op_sel_hi:[0,0,1]
	v_pk_fma_f32 v[16:17], v[32:33], v[146:147], v[16:17] op_sel:[0,1,0] op_sel_hi:[0,0,1]
	v_pk_fma_f32 v[18:19], v[32:33], v[144:145], v[18:19] op_sel:[0,1,0] op_sel_hi:[0,0,1]
	v_fma_f32 v20, v32, v84, v115
	v_mov_b32_e32 v21, v115
	s_waitcnt lgkmcnt(7)
	v_lshlrev_b32_e32 v32, 16, v39
	ds_read_u16 v39, v116 offset:29696
	v_pk_fma_f32 v[0:1], v[32:33], v[104:105], v[0:1] op_sel:[0,1,0] op_sel_hi:[0,0,1]
	v_pk_fma_f32 v[2:3], v[32:33], v[102:103], v[2:3] op_sel:[0,1,0] op_sel_hi:[0,0,1]
	v_pk_fma_f32 v[4:5], v[32:33], v[100:101], v[4:5] op_sel:[0,1,0] op_sel_hi:[0,0,1]
	v_pk_fma_f32 v[6:7], v[32:33], v[98:99], v[6:7] op_sel:[0,1,0] op_sel_hi:[0,0,1]
	v_pk_fma_f32 v[8:9], v[32:33], v[96:97], v[8:9] op_sel:[0,1,0] op_sel_hi:[0,0,1]
	v_pk_fma_f32 v[10:11], v[32:33], v[94:95], v[10:11] op_sel:[0,1,0] op_sel_hi:[0,0,1]
	v_pk_fma_f32 v[12:13], v[32:33], v[92:93], v[12:13] op_sel:[0,1,0] op_sel_hi:[0,0,1]
	v_pk_fma_f32 v[14:15], v[32:33], v[90:91], v[14:15] op_sel:[0,1,0] op_sel_hi:[0,0,1]
	v_pk_fma_f32 v[16:17], v[32:33], v[88:89], v[16:17] op_sel:[0,1,0] op_sel_hi:[0,0,1]
	v_pk_fma_f32 v[18:19], v[32:33], v[86:87], v[18:19] op_sel:[0,1,0] op_sel_hi:[0,0,1]
	v_pk_fma_f32 v[20:21], v[32:33], v[84:85], v[20:21] op_sel:[0,1,0] op_sel_hi:[0,0,1]
	s_waitcnt lgkmcnt(7)
	v_lshlrev_b32_e32 v32, 16, v40
	ds_read_u16 v40, v116 offset:30720
	v_pk_fma_f32 v[0:1], v[32:33], v[164:165], v[0:1] op_sel:[0,1,0] op_sel_hi:[0,0,1]
	v_pk_fma_f32 v[2:3], v[32:33], v[162:163], v[2:3] op_sel:[0,1,0] op_sel_hi:[0,0,1]
	v_pk_fma_f32 v[4:5], v[32:33], v[160:161], v[4:5] op_sel:[0,1,0] op_sel_hi:[0,0,1]
	v_pk_fma_f32 v[6:7], v[32:33], v[158:159], v[6:7] op_sel:[0,1,0] op_sel_hi:[0,0,1]
	v_pk_fma_f32 v[8:9], v[32:33], v[156:157], v[8:9] op_sel:[0,1,0] op_sel_hi:[0,0,1]
	v_pk_fma_f32 v[10:11], v[32:33], v[154:155], v[10:11] op_sel:[0,1,0] op_sel_hi:[0,0,1]
	v_pk_fma_f32 v[12:13], v[32:33], v[152:153], v[12:13] op_sel:[0,1,0] op_sel_hi:[0,0,1]
	v_pk_fma_f32 v[14:15], v[32:33], v[150:151], v[14:15] op_sel:[0,1,0] op_sel_hi:[0,0,1]
	v_pk_fma_f32 v[16:17], v[32:33], v[148:149], v[16:17] op_sel:[0,1,0] op_sel_hi:[0,0,1]
	v_pk_fma_f32 v[18:19], v[32:33], v[146:147], v[18:19] op_sel:[0,1,0] op_sel_hi:[0,0,1]
	v_pk_fma_f32 v[20:21], v[32:33], v[144:145], v[20:21] op_sel:[0,1,0] op_sel_hi:[0,0,1]
	v_fma_f32 v22, v32, v84, v115
	v_mov_b32_e32 v23, v115
	s_waitcnt lgkmcnt(7)
	v_lshlrev_b32_e32 v32, 16, v41
	ds_read_u16 v41, v116 offset:31744
	v_pk_fma_f32 v[0:1], v[32:33], v[106:107], v[0:1] op_sel:[0,1,0] op_sel_hi:[0,0,1]
	v_pk_fma_f32 v[2:3], v[32:33], v[104:105], v[2:3] op_sel:[0,1,0] op_sel_hi:[0,0,1]
	v_pk_fma_f32 v[4:5], v[32:33], v[102:103], v[4:5] op_sel:[0,1,0] op_sel_hi:[0,0,1]
	v_pk_fma_f32 v[6:7], v[32:33], v[100:101], v[6:7] op_sel:[0,1,0] op_sel_hi:[0,0,1]
	v_pk_fma_f32 v[8:9], v[32:33], v[98:99], v[8:9] op_sel:[0,1,0] op_sel_hi:[0,0,1]
	v_pk_fma_f32 v[10:11], v[32:33], v[96:97], v[10:11] op_sel:[0,1,0] op_sel_hi:[0,0,1]
	v_pk_fma_f32 v[12:13], v[32:33], v[94:95], v[12:13] op_sel:[0,1,0] op_sel_hi:[0,0,1]
	v_pk_fma_f32 v[14:15], v[32:33], v[92:93], v[14:15] op_sel:[0,1,0] op_sel_hi:[0,0,1]
	v_pk_fma_f32 v[16:17], v[32:33], v[90:91], v[16:17] op_sel:[0,1,0] op_sel_hi:[0,0,1]
	v_pk_fma_f32 v[18:19], v[32:33], v[88:89], v[18:19] op_sel:[0,1,0] op_sel_hi:[0,0,1]
	v_pk_fma_f32 v[20:21], v[32:33], v[86:87], v[20:21] op_sel:[0,1,0] op_sel_hi:[0,0,1]
	v_pk_fma_f32 v[22:23], v[32:33], v[84:85], v[22:23] op_sel:[0,1,0] op_sel_hi:[0,0,1]
	s_waitcnt lgkmcnt(7)
; __device__ __forceinline__ void phase_mixer0(const Params& p, LAS unsigned char* lds) {
;     ...
;             float acc[32];
; #pragma unroll
;             for (int t = 0; t < 32; ++t) acc[t] = bias;
; #pragma unroll
;             for (int j = 0; j < 62; ++j) {
;                 const float v = __uint_as_float((unsigned)ub[j * 512 + tid] << 16);
; #pragma unroll
;                 for (int t = 0; t < 32; ++t) { if (j - t >= 0 && j - t <= 30) acc[t] += v * wb[j - t]; }
;             }
; #pragma unroll
;             for (int t = 0; t < 32; ++t) cb[t * 512 + tid] = acc[t];
	v_lshlrev_b32_e32 v32, 16, v34
	ds_read_u16 v34, v116 offset:32768
	v_pk_fma_f32 v[0:1], v[32:33], v[166:167], v[0:1] op_sel:[0,1,0] op_sel_hi:[0,0,1]
	v_pk_fma_f32 v[2:3], v[32:33], v[164:165], v[2:3] op_sel:[0,1,0] op_sel_hi:[0,0,1]
	v_pk_fma_f32 v[4:5], v[32:33], v[162:163], v[4:5] op_sel:[0,1,0] op_sel_hi:[0,0,1]
	v_pk_fma_f32 v[6:7], v[32:33], v[160:161], v[6:7] op_sel:[0,1,0] op_sel_hi:[0,0,1]
	v_pk_fma_f32 v[8:9], v[32:33], v[158:159], v[8:9] op_sel:[0,1,0] op_sel_hi:[0,0,1]
	v_pk_fma_f32 v[10:11], v[32:33], v[156:157], v[10:11] op_sel:[0,1,0] op_sel_hi:[0,0,1]
	v_pk_fma_f32 v[12:13], v[32:33], v[154:155], v[12:13] op_sel:[0,1,0] op_sel_hi:[0,0,1]
	v_pk_fma_f32 v[14:15], v[32:33], v[152:153], v[14:15] op_sel:[0,1,0] op_sel_hi:[0,0,1]
	v_pk_fma_f32 v[16:17], v[32:33], v[150:151], v[16:17] op_sel:[0,1,0] op_sel_hi:[0,0,1]
	v_pk_fma_f32 v[18:19], v[32:33], v[148:149], v[18:19] op_sel:[0,1,0] op_sel_hi:[0,0,1]
	v_pk_fma_f32 v[20:21], v[32:33], v[146:147], v[20:21] op_sel:[0,1,0] op_sel_hi:[0,0,1]
	v_pk_fma_f32 v[22:23], v[32:33], v[144:145], v[22:23] op_sel:[0,1,0] op_sel_hi:[0,0,1]
	v_fma_f32 v24, v32, v84, v115
	v_mov_b32_e32 v25, v115
	s_waitcnt lgkmcnt(7)
	v_lshlrev_b32_e32 v32, 16, v35
	ds_read_u16 v35, v116 offset:33792
	v_pk_fma_f32 v[0:1], v[32:33], v[108:109], v[0:1] op_sel:[0,1,0] op_sel_hi:[0,0,1]
	v_pk_fma_f32 v[2:3], v[32:33], v[106:107], v[2:3] op_sel:[0,1,0] op_sel_hi:[0,0,1]
	v_pk_fma_f32 v[4:5], v[32:33], v[104:105], v[4:5] op_sel:[0,1,0] op_sel_hi:[0,0,1]
	v_pk_fma_f32 v[6:7], v[32:33], v[102:103], v[6:7] op_sel:[0,1,0] op_sel_hi:[0,0,1]
	v_pk_fma_f32 v[8:9], v[32:33], v[100:101], v[8:9] op_sel:[0,1,0] op_sel_hi:[0,0,1]
	v_pk_fma_f32 v[10:11], v[32:33], v[98:99], v[10:11] op_sel:[0,1,0] op_sel_hi:[0,0,1]
	v_pk_fma_f32 v[12:13], v[32:33], v[96:97], v[12:13] op_sel:[0,1,0] op_sel_hi:[0,0,1]
	v_pk_fma_f32 v[14:15], v[32:33], v[94:95], v[14:15] op_sel:[0,1,0] op_sel_hi:[0,0,1]
	v_pk_fma_f32 v[16:17], v[32:33], v[92:93], v[16:17] op_sel:[0,1,0] op_sel_hi:[0,0,1]
	v_pk_fma_f32 v[18:19], v[32:33], v[90:91], v[18:19] op_sel:[0,1,0] op_sel_hi:[0,0,1]
	v_pk_fma_f32 v[20:21], v[32:33], v[88:89], v[20:21] op_sel:[0,1,0] op_sel_hi:[0,0,1]
	v_pk_fma_f32 v[22:23], v[32:33], v[86:87], v[22:23] op_sel:[0,1,0] op_sel_hi:[0,0,1]
	v_pk_fma_f32 v[24:25], v[32:33], v[84:85], v[24:25] op_sel:[0,1,0] op_sel_hi:[0,0,1]
	s_waitcnt lgkmcnt(7)
	v_lshlrev_b32_e32 v32, 16, v36
	ds_read_u16 v36, v116 offset:34816
	v_pk_fma_f32 v[0:1], v[32:33], v[168:169], v[0:1] op_sel:[0,1,0] op_sel_hi:[0,0,1]
	v_pk_fma_f32 v[2:3], v[32:33], v[166:167], v[2:3] op_sel:[0,1,0] op_sel_hi:[0,0,1]
	v_pk_fma_f32 v[4:5], v[32:33], v[164:165], v[4:5] op_sel:[0,1,0] op_sel_hi:[0,0,1]
	v_pk_fma_f32 v[6:7], v[32:33], v[162:163], v[6:7] op_sel:[0,1,0] op_sel_hi:[0,0,1]
	v_pk_fma_f32 v[8:9], v[32:33], v[160:161], v[8:9] op_sel:[0,1,0] op_sel_hi:[0,0,1]
	v_pk_fma_f32 v[10:11], v[32:33], v[158:159], v[10:11] op_sel:[0,1,0] op_sel_hi:[0,0,1]
	v_pk_fma_f32 v[12:13], v[32:33], v[156:157], v[12:13] op_sel:[0,1,0] op_sel_hi:[0,0,1]
	v_pk_fma_f32 v[14:15], v[32:33], v[154:155], v[14:15] op_sel:[0,1,0] op_sel_hi:[0,0,1]
	v_pk_fma_f32 v[16:17], v[32:33], v[152:153], v[16:17] op_sel:[0,1,0] op_sel_hi:[0,0,1]
	v_pk_fma_f32 v[18:19], v[32:33], v[150:151], v[18:19] op_sel:[0,1,0] op_sel_hi:[0,0,1]
	v_pk_fma_f32 v[20:21], v[32:33], v[148:149], v[20:21] op_sel:[0,1,0] op_sel_hi:[0,0,1]
	v_pk_fma_f32 v[22:23], v[32:33], v[146:147], v[22:23] op_sel:[0,1,0] op_sel_hi:[0,0,1]
	v_pk_fma_f32 v[24:25], v[32:33], v[144:145], v[24:25] op_sel:[0,1,0] op_sel_hi:[0,0,1]
	v_fma_f32 v26, v32, v84, v115
	v_mov_b32_e32 v27, v115
	s_waitcnt lgkmcnt(7)
	v_lshlrev_b32_e32 v32, 16, v37
	ds_read_u16 v37, v116 offset:35840
	v_pk_fma_f32 v[0:1], v[32:33], v[110:111], v[0:1] op_sel:[0,1,0] op_sel_hi:[0,0,1]
	v_pk_fma_f32 v[2:3], v[32:33], v[108:109], v[2:3] op_sel:[0,1,0] op_sel_hi:[0,0,1]
	v_pk_fma_f32 v[4:5], v[32:33], v[106:107], v[4:5] op_sel:[0,1,0] op_sel_hi:[0,0,1]
	v_pk_fma_f32 v[6:7], v[32:33], v[104:105], v[6:7] op_sel:[0,1,0] op_sel_hi:[0,0,1]
	v_pk_fma_f32 v[8:9], v[32:33], v[102:103], v[8:9] op_sel:[0,1,0] op_sel_hi:[0,0,1]
	v_pk_fma_f32 v[10:11], v[32:33], v[100:101], v[10:11] op_sel:[0,1,0] op_sel_hi:[0,0,1]
	v_pk_fma_f32 v[12:13], v[32:33], v[98:99], v[12:13] op_sel:[0,1,0] op_sel_hi:[0,0,1]
	v_pk_fma_f32 v[14:15], v[32:33], v[96:97], v[14:15] op_sel:[0,1,0] op_sel_hi:[0,0,1]
	v_pk_fma_f32 v[16:17], v[32:33], v[94:95], v[16:17] op_sel:[0,1,0] op_sel_hi:[0,0,1]
	v_pk_fma_f32 v[18:19], v[32:33], v[92:93], v[18:19] op_sel:[0,1,0] op_sel_hi:[0,0,1]
	v_pk_fma_f32 v[20:21], v[32:33], v[90:91], v[20:21] op_sel:[0,1,0] op_sel_hi:[0,0,1]
	v_pk_fma_f32 v[22:23], v[32:33], v[88:89], v[22:23] op_sel:[0,1,0] op_sel_hi:[0,0,1]
	v_pk_fma_f32 v[24:25], v[32:33], v[86:87], v[24:25] op_sel:[0,1,0] op_sel_hi:[0,0,1]
	v_pk_fma_f32 v[26:27], v[32:33], v[84:85], v[26:27] op_sel:[0,1,0] op_sel_hi:[0,0,1]
	s_waitcnt lgkmcnt(7)
	v_lshlrev_b32_e32 v32, 16, v38
	ds_read_u16 v38, v116 offset:36864
	v_pk_fma_f32 v[0:1], v[32:33], v[170:171], v[0:1] op_sel:[0,1,0] op_sel_hi:[0,0,1]
	v_pk_fma_f32 v[2:3], v[32:33], v[168:169], v[2:3] op_sel:[0,1,0] op_sel_hi:[0,0,1]
	v_pk_fma_f32 v[4:5], v[32:33], v[166:167], v[4:5] op_sel:[0,1,0] op_sel_hi:[0,0,1]
	v_pk_fma_f32 v[6:7], v[32:33], v[164:165], v[6:7] op_sel:[0,1,0] op_sel_hi:[0,0,1]
	v_pk_fma_f32 v[8:9], v[32:33], v[162:163], v[8:9] op_sel:[0,1,0] op_sel_hi:[0,0,1]
	v_pk_fma_f32 v[10:11], v[32:33], v[160:161], v[10:11] op_sel:[0,1,0] op_sel_hi:[0,0,1]
	v_pk_fma_f32 v[12:13], v[32:33], v[158:159], v[12:13] op_sel:[0,1,0] op_sel_hi:[0,0,1]
	v_pk_fma_f32 v[14:15], v[32:33], v[156:157], v[14:15] op_sel:[0,1,0] op_sel_hi:[0,0,1]
	v_pk_fma_f32 v[16:17], v[32:33], v[154:155], v[16:17] op_sel:[0,1,0] op_sel_hi:[0,0,1]
	v_pk_fma_f32 v[18:19], v[32:33], v[152:153], v[18:19] op_sel:[0,1,0] op_sel_hi:[0,0,1]
	v_pk_fma_f32 v[20:21], v[32:33], v[150:151], v[20:21] op_sel:[0,1,0] op_sel_hi:[0,0,1]
	v_pk_fma_f32 v[22:23], v[32:33], v[148:149], v[22:23] op_sel:[0,1,0] op_sel_hi:[0,0,1]
	v_pk_fma_f32 v[24:25], v[32:33], v[146:147], v[24:25] op_sel:[0,1,0] op_sel_hi:[0,0,1]
	v_pk_fma_f32 v[26:27], v[32:33], v[144:145], v[26:27] op_sel:[0,1,0] op_sel_hi:[0,0,1]
	v_fma_f32 v28, v32, v84, v115
	v_mov_b32_e32 v29, v115
	s_waitcnt lgkmcnt(7)
; __device__ __forceinline__ void phase_mixer0(const Params& p, LAS unsigned char* lds) {
;     ...
;             float acc[32];
; #pragma unroll
;             for (int t = 0; t < 32; ++t) acc[t] = bias;
; #pragma unroll
;             for (int j = 0; j < 62; ++j) {
;                 const float v = __uint_as_float((unsigned)ub[j * 512 + tid] << 16);
; #pragma unroll
;                 for (int t = 0; t < 32; ++t) { if (j - t >= 0 && j - t <= 30) acc[t] += v * wb[j - t]; }
;             }
; #pragma unroll
;             for (int t = 0; t < 32; ++t) cb[t * 512 + tid] = acc[t];
	v_lshlrev_b32_e32 v32, 16, v39
	ds_read_u16 v39, v116 offset:37888
	v_pk_fma_f32 v[0:1], v[32:33], v[112:113], v[0:1] op_sel:[0,1,0] op_sel_hi:[0,0,1]
	v_pk_fma_f32 v[2:3], v[32:33], v[110:111], v[2:3] op_sel:[0,1,0] op_sel_hi:[0,0,1]
	v_pk_fma_f32 v[4:5], v[32:33], v[108:109], v[4:5] op_sel:[0,1,0] op_sel_hi:[0,0,1]
	v_pk_fma_f32 v[6:7], v[32:33], v[106:107], v[6:7] op_sel:[0,1,0] op_sel_hi:[0,0,1]
	v_pk_fma_f32 v[8:9], v[32:33], v[104:105], v[8:9] op_sel:[0,1,0] op_sel_hi:[0,0,1]
	v_pk_fma_f32 v[10:11], v[32:33], v[102:103], v[10:11] op_sel:[0,1,0] op_sel_hi:[0,0,1]
	v_pk_fma_f32 v[12:13], v[32:33], v[100:101], v[12:13] op_sel:[0,1,0] op_sel_hi:[0,0,1]
	v_pk_fma_f32 v[14:15], v[32:33], v[98:99], v[14:15] op_sel:[0,1,0] op_sel_hi:[0,0,1]
	v_pk_fma_f32 v[16:17], v[32:33], v[96:97], v[16:17] op_sel:[0,1,0] op_sel_hi:[0,0,1]
	v_pk_fma_f32 v[18:19], v[32:33], v[94:95], v[18:19] op_sel:[0,1,0] op_sel_hi:[0,0,1]
	v_pk_fma_f32 v[20:21], v[32:33], v[92:93], v[20:21] op_sel:[0,1,0] op_sel_hi:[0,0,1]
	v_pk_fma_f32 v[22:23], v[32:33], v[90:91], v[22:23] op_sel:[0,1,0] op_sel_hi:[0,0,1]
	v_pk_fma_f32 v[24:25], v[32:33], v[88:89], v[24:25] op_sel:[0,1,0] op_sel_hi:[0,0,1]
	v_pk_fma_f32 v[26:27], v[32:33], v[86:87], v[26:27] op_sel:[0,1,0] op_sel_hi:[0,0,1]
	v_pk_fma_f32 v[28:29], v[32:33], v[84:85], v[28:29] op_sel:[0,1,0] op_sel_hi:[0,0,1]
	s_waitcnt lgkmcnt(7)
	v_lshlrev_b32_e32 v32, 16, v40
	ds_read_u16 v40, v116 offset:38912
	v_pk_fma_f32 v[0:1], v[32:33], v[172:173], v[0:1] op_sel:[0,1,0] op_sel_hi:[0,0,1]
	v_pk_fma_f32 v[2:3], v[32:33], v[170:171], v[2:3] op_sel:[0,1,0] op_sel_hi:[0,0,1]
	v_pk_fma_f32 v[4:5], v[32:33], v[168:169], v[4:5] op_sel:[0,1,0] op_sel_hi:[0,0,1]
	v_pk_fma_f32 v[6:7], v[32:33], v[166:167], v[6:7] op_sel:[0,1,0] op_sel_hi:[0,0,1]
	v_pk_fma_f32 v[8:9], v[32:33], v[164:165], v[8:9] op_sel:[0,1,0] op_sel_hi:[0,0,1]
	v_pk_fma_f32 v[10:11], v[32:33], v[162:163], v[10:11] op_sel:[0,1,0] op_sel_hi:[0,0,1]
	v_pk_fma_f32 v[12:13], v[32:33], v[160:161], v[12:13] op_sel:[0,1,0] op_sel_hi:[0,0,1]
	v_pk_fma_f32 v[14:15], v[32:33], v[158:159], v[14:15] op_sel:[0,1,0] op_sel_hi:[0,0,1]
	v_pk_fma_f32 v[16:17], v[32:33], v[156:157], v[16:17] op_sel:[0,1,0] op_sel_hi:[0,0,1]
	v_pk_fma_f32 v[18:19], v[32:33], v[154:155], v[18:19] op_sel:[0,1,0] op_sel_hi:[0,0,1]
	v_pk_fma_f32 v[20:21], v[32:33], v[152:153], v[20:21] op_sel:[0,1,0] op_sel_hi:[0,0,1]
	v_pk_fma_f32 v[22:23], v[32:33], v[150:151], v[22:23] op_sel:[0,1,0] op_sel_hi:[0,0,1]
	v_pk_fma_f32 v[24:25], v[32:33], v[148:149], v[24:25] op_sel:[0,1,0] op_sel_hi:[0,0,1]
	v_pk_fma_f32 v[26:27], v[32:33], v[146:147], v[26:27] op_sel:[0,1,0] op_sel_hi:[0,0,1]
	v_pk_fma_f32 v[28:29], v[32:33], v[144:145], v[28:29] op_sel:[0,1,0] op_sel_hi:[0,0,1]
	v_fma_f32 v30, v32, v84, v115
	v_mov_b32_e32 v31, v115
	s_waitcnt lgkmcnt(7)
	v_lshlrev_b32_e32 v32, 16, v41
	ds_read_u16 v41, v116 offset:39936
	v_fmac_f32_e32 v1, v32, v114
	v_pk_fma_f32 v[2:3], v[32:33], v[112:113], v[2:3] op_sel:[0,1,0] op_sel_hi:[0,0,1]
	v_pk_fma_f32 v[4:5], v[32:33], v[110:111], v[4:5] op_sel:[0,1,0] op_sel_hi:[0,0,1]
	v_pk_fma_f32 v[6:7], v[32:33], v[108:109], v[6:7] op_sel:[0,1,0] op_sel_hi:[0,0,1]
	v_pk_fma_f32 v[8:9], v[32:33], v[106:107], v[8:9] op_sel:[0,1,0] op_sel_hi:[0,0,1]
	v_pk_fma_f32 v[10:11], v[32:33], v[104:105], v[10:11] op_sel:[0,1,0] op_sel_hi:[0,0,1]
	v_pk_fma_f32 v[12:13], v[32:33], v[102:103], v[12:13] op_sel:[0,1,0] op_sel_hi:[0,0,1]
	v_pk_fma_f32 v[14:15], v[32:33], v[100:101], v[14:15] op_sel:[0,1,0] op_sel_hi:[0,0,1]
	v_pk_fma_f32 v[16:17], v[32:33], v[98:99], v[16:17] op_sel:[0,1,0] op_sel_hi:[0,0,1]
	v_pk_fma_f32 v[18:19], v[32:33], v[96:97], v[18:19] op_sel:[0,1,0] op_sel_hi:[0,0,1]
	v_pk_fma_f32 v[20:21], v[32:33], v[94:95], v[20:21] op_sel:[0,1,0] op_sel_hi:[0,0,1]
	v_pk_fma_f32 v[22:23], v[32:33], v[92:93], v[22:23] op_sel:[0,1,0] op_sel_hi:[0,0,1]
	v_pk_fma_f32 v[24:25], v[32:33], v[90:91], v[24:25] op_sel:[0,1,0] op_sel_hi:[0,0,1]
	v_pk_fma_f32 v[26:27], v[32:33], v[88:89], v[26:27] op_sel:[0,1,0] op_sel_hi:[0,0,1]
	v_pk_fma_f32 v[28:29], v[32:33], v[86:87], v[28:29] op_sel:[0,1,0] op_sel_hi:[0,0,1]
	v_pk_fma_f32 v[30:31], v[32:33], v[84:85], v[30:31] op_sel:[0,1,0] op_sel_hi:[0,0,1]
	s_waitcnt lgkmcnt(7)
	v_lshlrev_b32_e32 v32, 16, v34
	ds_read_u16 v34, v116 offset:40960
	v_pk_fma_f32 v[2:3], v[32:33], v[172:173], v[2:3] op_sel:[0,1,0] op_sel_hi:[0,0,1]
	v_pk_fma_f32 v[4:5], v[32:33], v[170:171], v[4:5] op_sel:[0,1,0] op_sel_hi:[0,0,1]
	v_pk_fma_f32 v[6:7], v[32:33], v[168:169], v[6:7] op_sel:[0,1,0] op_sel_hi:[0,0,1]
	v_pk_fma_f32 v[8:9], v[32:33], v[166:167], v[8:9] op_sel:[0,1,0] op_sel_hi:[0,0,1]
	v_pk_fma_f32 v[10:11], v[32:33], v[164:165], v[10:11] op_sel:[0,1,0] op_sel_hi:[0,0,1]
	v_pk_fma_f32 v[12:13], v[32:33], v[162:163], v[12:13] op_sel:[0,1,0] op_sel_hi:[0,0,1]
	v_pk_fma_f32 v[14:15], v[32:33], v[160:161], v[14:15] op_sel:[0,1,0] op_sel_hi:[0,0,1]
	v_pk_fma_f32 v[16:17], v[32:33], v[158:159], v[16:17] op_sel:[0,1,0] op_sel_hi:[0,0,1]
	v_pk_fma_f32 v[18:19], v[32:33], v[156:157], v[18:19] op_sel:[0,1,0] op_sel_hi:[0,0,1]
	v_pk_fma_f32 v[20:21], v[32:33], v[154:155], v[20:21] op_sel:[0,1,0] op_sel_hi:[0,0,1]
	v_pk_fma_f32 v[22:23], v[32:33], v[152:153], v[22:23] op_sel:[0,1,0] op_sel_hi:[0,0,1]
	v_pk_fma_f32 v[24:25], v[32:33], v[150:151], v[24:25] op_sel:[0,1,0] op_sel_hi:[0,0,1]
	v_pk_fma_f32 v[26:27], v[32:33], v[148:149], v[26:27] op_sel:[0,1,0] op_sel_hi:[0,0,1]
	v_pk_fma_f32 v[28:29], v[32:33], v[146:147], v[28:29] op_sel:[0,1,0] op_sel_hi:[0,0,1]
	v_pk_fma_f32 v[30:31], v[32:33], v[144:145], v[30:31] op_sel:[0,1,0] op_sel_hi:[0,0,1]
	s_waitcnt lgkmcnt(7)
; __device__ __forceinline__ void phase_mixer0(const Params& p, LAS unsigned char* lds) {
;     ...
;             float acc[32];
; #pragma unroll
;             for (int t = 0; t < 32; ++t) acc[t] = bias;
; #pragma unroll
;             for (int j = 0; j < 62; ++j) {
;                 const float v = __uint_as_float((unsigned)ub[j * 512 + tid] << 16);
; #pragma unroll
;                 for (int t = 0; t < 32; ++t) { if (j - t >= 0 && j - t <= 30) acc[t] += v * wb[j - t]; }
;             }
; #pragma unroll
;             for (int t = 0; t < 32; ++t) cb[t * 512 + tid] = acc[t];
	v_lshlrev_b32_e32 v32, 16, v35
	ds_read_u16 v35, v116 offset:41984
	v_fmac_f32_e32 v3, v32, v114
	v_pk_fma_f32 v[4:5], v[32:33], v[112:113], v[4:5] op_sel:[0,1,0] op_sel_hi:[0,0,1]
	v_pk_fma_f32 v[6:7], v[32:33], v[110:111], v[6:7] op_sel:[0,1,0] op_sel_hi:[0,0,1]
	v_pk_fma_f32 v[8:9], v[32:33], v[108:109], v[8:9] op_sel:[0,1,0] op_sel_hi:[0,0,1]
	v_pk_fma_f32 v[10:11], v[32:33], v[106:107], v[10:11] op_sel:[0,1,0] op_sel_hi:[0,0,1]
	v_pk_fma_f32 v[12:13], v[32:33], v[104:105], v[12:13] op_sel:[0,1,0] op_sel_hi:[0,0,1]
	v_pk_fma_f32 v[14:15], v[32:33], v[102:103], v[14:15] op_sel:[0,1,0] op_sel_hi:[0,0,1]
	v_pk_fma_f32 v[16:17], v[32:33], v[100:101], v[16:17] op_sel:[0,1,0] op_sel_hi:[0,0,1]
	v_pk_fma_f32 v[18:19], v[32:33], v[98:99], v[18:19] op_sel:[0,1,0] op_sel_hi:[0,0,1]
	v_pk_fma_f32 v[20:21], v[32:33], v[96:97], v[20:21] op_sel:[0,1,0] op_sel_hi:[0,0,1]
	v_pk_fma_f32 v[22:23], v[32:33], v[94:95], v[22:23] op_sel:[0,1,0] op_sel_hi:[0,0,1]
	v_pk_fma_f32 v[24:25], v[32:33], v[92:93], v[24:25] op_sel:[0,1,0] op_sel_hi:[0,0,1]
	v_pk_fma_f32 v[26:27], v[32:33], v[90:91], v[26:27] op_sel:[0,1,0] op_sel_hi:[0,0,1]
	v_pk_fma_f32 v[28:29], v[32:33], v[88:89], v[28:29] op_sel:[0,1,0] op_sel_hi:[0,0,1]
	v_pk_fma_f32 v[30:31], v[32:33], v[86:87], v[30:31] op_sel:[0,1,0] op_sel_hi:[0,0,1]
	s_waitcnt lgkmcnt(7)
	v_lshlrev_b32_e32 v32, 16, v36
	ds_read_u16 v36, v116 offset:43008
	v_pk_fma_f32 v[4:5], v[32:33], v[172:173], v[4:5] op_sel:[0,1,0] op_sel_hi:[0,0,1]
	v_pk_fma_f32 v[6:7], v[32:33], v[170:171], v[6:7] op_sel:[0,1,0] op_sel_hi:[0,0,1]
	v_pk_fma_f32 v[8:9], v[32:33], v[168:169], v[8:9] op_sel:[0,1,0] op_sel_hi:[0,0,1]
	v_pk_fma_f32 v[10:11], v[32:33], v[166:167], v[10:11] op_sel:[0,1,0] op_sel_hi:[0,0,1]
	v_pk_fma_f32 v[12:13], v[32:33], v[164:165], v[12:13] op_sel:[0,1,0] op_sel_hi:[0,0,1]
	v_pk_fma_f32 v[14:15], v[32:33], v[162:163], v[14:15] op_sel:[0,1,0] op_sel_hi:[0,0,1]
	v_pk_fma_f32 v[16:17], v[32:33], v[160:161], v[16:17] op_sel:[0,1,0] op_sel_hi:[0,0,1]
	v_pk_fma_f32 v[18:19], v[32:33], v[158:159], v[18:19] op_sel:[0,1,0] op_sel_hi:[0,0,1]
	v_pk_fma_f32 v[20:21], v[32:33], v[156:157], v[20:21] op_sel:[0,1,0] op_sel_hi:[0,0,1]
	v_pk_fma_f32 v[22:23], v[32:33], v[154:155], v[22:23] op_sel:[0,1,0] op_sel_hi:[0,0,1]
	v_pk_fma_f32 v[24:25], v[32:33], v[152:153], v[24:25] op_sel:[0,1,0] op_sel_hi:[0,0,1]
	v_pk_fma_f32 v[26:27], v[32:33], v[150:151], v[26:27] op_sel:[0,1,0] op_sel_hi:[0,0,1]
	v_pk_fma_f32 v[28:29], v[32:33], v[148:149], v[28:29] op_sel:[0,1,0] op_sel_hi:[0,0,1]
	v_pk_fma_f32 v[30:31], v[32:33], v[146:147], v[30:31] op_sel:[0,1,0] op_sel_hi:[0,0,1]
	s_waitcnt lgkmcnt(7)
	v_lshlrev_b32_e32 v32, 16, v37
	ds_read_u16 v37, v116 offset:44032
	v_fmac_f32_e32 v5, v32, v114
	v_pk_fma_f32 v[6:7], v[32:33], v[112:113], v[6:7] op_sel:[0,1,0] op_sel_hi:[0,0,1]
	v_pk_fma_f32 v[8:9], v[32:33], v[110:111], v[8:9] op_sel:[0,1,0] op_sel_hi:[0,0,1]
	v_pk_fma_f32 v[10:11], v[32:33], v[108:109], v[10:11] op_sel:[0,1,0] op_sel_hi:[0,0,1]
	v_pk_fma_f32 v[12:13], v[32:33], v[106:107], v[12:13] op_sel:[0,1,0] op_sel_hi:[0,0,1]
	v_pk_fma_f32 v[14:15], v[32:33], v[104:105], v[14:15] op_sel:[0,1,0] op_sel_hi:[0,0,1]
	v_pk_fma_f32 v[16:17], v[32:33], v[102:103], v[16:17] op_sel:[0,1,0] op_sel_hi:[0,0,1]
	v_pk_fma_f32 v[18:19], v[32:33], v[100:101], v[18:19] op_sel:[0,1,0] op_sel_hi:[0,0,1]
	v_pk_fma_f32 v[20:21], v[32:33], v[98:99], v[20:21] op_sel:[0,1,0] op_sel_hi:[0,0,1]
	v_pk_fma_f32 v[22:23], v[32:33], v[96:97], v[22:23] op_sel:[0,1,0] op_sel_hi:[0,0,1]
	v_pk_fma_f32 v[24:25], v[32:33], v[94:95], v[24:25] op_sel:[0,1,0] op_sel_hi:[0,0,1]
	v_pk_fma_f32 v[26:27], v[32:33], v[92:93], v[26:27] op_sel:[0,1,0] op_sel_hi:[0,0,1]
	v_pk_fma_f32 v[28:29], v[32:33], v[90:91], v[28:29] op_sel:[0,1,0] op_sel_hi:[0,0,1]
	v_pk_fma_f32 v[30:31], v[32:33], v[88:89], v[30:31] op_sel:[0,1,0] op_sel_hi:[0,0,1]
	s_waitcnt lgkmcnt(7)
	v_lshlrev_b32_e32 v32, 16, v38
	ds_read_u16 v38, v116 offset:45056
	v_pk_fma_f32 v[6:7], v[32:33], v[172:173], v[6:7] op_sel:[0,1,0] op_sel_hi:[0,0,1]
	v_pk_fma_f32 v[8:9], v[32:33], v[170:171], v[8:9] op_sel:[0,1,0] op_sel_hi:[0,0,1]
	v_pk_fma_f32 v[10:11], v[32:33], v[168:169], v[10:11] op_sel:[0,1,0] op_sel_hi:[0,0,1]
	v_pk_fma_f32 v[12:13], v[32:33], v[166:167], v[12:13] op_sel:[0,1,0] op_sel_hi:[0,0,1]
	v_pk_fma_f32 v[14:15], v[32:33], v[164:165], v[14:15] op_sel:[0,1,0] op_sel_hi:[0,0,1]
	v_pk_fma_f32 v[16:17], v[32:33], v[162:163], v[16:17] op_sel:[0,1,0] op_sel_hi:[0,0,1]
	v_pk_fma_f32 v[18:19], v[32:33], v[160:161], v[18:19] op_sel:[0,1,0] op_sel_hi:[0,0,1]
	v_pk_fma_f32 v[20:21], v[32:33], v[158:159], v[20:21] op_sel:[0,1,0] op_sel_hi:[0,0,1]
	v_pk_fma_f32 v[22:23], v[32:33], v[156:157], v[22:23] op_sel:[0,1,0] op_sel_hi:[0,0,1]
	v_pk_fma_f32 v[24:25], v[32:33], v[154:155], v[24:25] op_sel:[0,1,0] op_sel_hi:[0,0,1]
	v_pk_fma_f32 v[26:27], v[32:33], v[152:153], v[26:27] op_sel:[0,1,0] op_sel_hi:[0,0,1]
	v_pk_fma_f32 v[28:29], v[32:33], v[150:151], v[28:29] op_sel:[0,1,0] op_sel_hi:[0,0,1]
	v_pk_fma_f32 v[30:31], v[32:33], v[148:149], v[30:31] op_sel:[0,1,0] op_sel_hi:[0,0,1]
	s_waitcnt lgkmcnt(7)
; __device__ __forceinline__ void phase_mixer0(const Params& p, LAS unsigned char* lds) {
;     ...
;             float acc[32];
; #pragma unroll
;             for (int t = 0; t < 32; ++t) acc[t] = bias;
; #pragma unroll
;             for (int j = 0; j < 62; ++j) {
;                 const float v = __uint_as_float((unsigned)ub[j * 512 + tid] << 16);
; #pragma unroll
;                 for (int t = 0; t < 32; ++t) { if (j - t >= 0 && j - t <= 30) acc[t] += v * wb[j - t]; }
;             }
; #pragma unroll
;             for (int t = 0; t < 32; ++t) cb[t * 512 + tid] = acc[t];
	v_lshlrev_b32_e32 v32, 16, v39
	ds_read_u16 v39, v116 offset:46080
	v_fmac_f32_e32 v7, v32, v114
	v_pk_fma_f32 v[8:9], v[32:33], v[112:113], v[8:9] op_sel:[0,1,0] op_sel_hi:[0,0,1]
	v_pk_fma_f32 v[10:11], v[32:33], v[110:111], v[10:11] op_sel:[0,1,0] op_sel_hi:[0,0,1]
	v_pk_fma_f32 v[12:13], v[32:33], v[108:109], v[12:13] op_sel:[0,1,0] op_sel_hi:[0,0,1]
	v_pk_fma_f32 v[14:15], v[32:33], v[106:107], v[14:15] op_sel:[0,1,0] op_sel_hi:[0,0,1]
	v_pk_fma_f32 v[16:17], v[32:33], v[104:105], v[16:17] op_sel:[0,1,0] op_sel_hi:[0,0,1]
	v_pk_fma_f32 v[18:19], v[32:33], v[102:103], v[18:19] op_sel:[0,1,0] op_sel_hi:[0,0,1]
	v_pk_fma_f32 v[20:21], v[32:33], v[100:101], v[20:21] op_sel:[0,1,0] op_sel_hi:[0,0,1]
	v_pk_fma_f32 v[22:23], v[32:33], v[98:99], v[22:23] op_sel:[0,1,0] op_sel_hi:[0,0,1]
	v_pk_fma_f32 v[24:25], v[32:33], v[96:97], v[24:25] op_sel:[0,1,0] op_sel_hi:[0,0,1]
	v_pk_fma_f32 v[26:27], v[32:33], v[94:95], v[26:27] op_sel:[0,1,0] op_sel_hi:[0,0,1]
	v_pk_fma_f32 v[28:29], v[32:33], v[92:93], v[28:29] op_sel:[0,1,0] op_sel_hi:[0,0,1]
	v_pk_fma_f32 v[30:31], v[32:33], v[90:91], v[30:31] op_sel:[0,1,0] op_sel_hi:[0,0,1]
	s_waitcnt lgkmcnt(7)
	v_lshlrev_b32_e32 v32, 16, v40
	ds_read_u16 v40, v116 offset:47104
	v_pk_fma_f32 v[8:9], v[32:33], v[172:173], v[8:9] op_sel:[0,1,0] op_sel_hi:[0,0,1]
	v_pk_fma_f32 v[10:11], v[32:33], v[170:171], v[10:11] op_sel:[0,1,0] op_sel_hi:[0,0,1]
	v_pk_fma_f32 v[12:13], v[32:33], v[168:169], v[12:13] op_sel:[0,1,0] op_sel_hi:[0,0,1]
	v_pk_fma_f32 v[14:15], v[32:33], v[166:167], v[14:15] op_sel:[0,1,0] op_sel_hi:[0,0,1]
	v_pk_fma_f32 v[16:17], v[32:33], v[164:165], v[16:17] op_sel:[0,1,0] op_sel_hi:[0,0,1]
	v_pk_fma_f32 v[18:19], v[32:33], v[162:163], v[18:19] op_sel:[0,1,0] op_sel_hi:[0,0,1]
	v_pk_fma_f32 v[20:21], v[32:33], v[160:161], v[20:21] op_sel:[0,1,0] op_sel_hi:[0,0,1]
	v_pk_fma_f32 v[22:23], v[32:33], v[158:159], v[22:23] op_sel:[0,1,0] op_sel_hi:[0,0,1]
	v_pk_fma_f32 v[24:25], v[32:33], v[156:157], v[24:25] op_sel:[0,1,0] op_sel_hi:[0,0,1]
	v_pk_fma_f32 v[26:27], v[32:33], v[154:155], v[26:27] op_sel:[0,1,0] op_sel_hi:[0,0,1]
	v_pk_fma_f32 v[28:29], v[32:33], v[152:153], v[28:29] op_sel:[0,1,0] op_sel_hi:[0,0,1]
	v_pk_fma_f32 v[30:31], v[32:33], v[150:151], v[30:31] op_sel:[0,1,0] op_sel_hi:[0,0,1]
	s_waitcnt lgkmcnt(7)
	v_lshlrev_b32_e32 v32, 16, v41
	ds_read_u16 v41, v116 offset:48128
	v_fmac_f32_e32 v9, v32, v114
	v_pk_fma_f32 v[10:11], v[32:33], v[112:113], v[10:11] op_sel:[0,1,0] op_sel_hi:[0,0,1]
	v_pk_fma_f32 v[12:13], v[32:33], v[110:111], v[12:13] op_sel:[0,1,0] op_sel_hi:[0,0,1]
	v_pk_fma_f32 v[14:15], v[32:33], v[108:109], v[14:15] op_sel:[0,1,0] op_sel_hi:[0,0,1]
	v_pk_fma_f32 v[16:17], v[32:33], v[106:107], v[16:17] op_sel:[0,1,0] op_sel_hi:[0,0,1]
	v_pk_fma_f32 v[18:19], v[32:33], v[104:105], v[18:19] op_sel:[0,1,0] op_sel_hi:[0,0,1]
	v_pk_fma_f32 v[20:21], v[32:33], v[102:103], v[20:21] op_sel:[0,1,0] op_sel_hi:[0,0,1]
	v_pk_fma_f32 v[22:23], v[32:33], v[100:101], v[22:23] op_sel:[0,1,0] op_sel_hi:[0,0,1]
	v_pk_fma_f32 v[24:25], v[32:33], v[98:99], v[24:25] op_sel:[0,1,0] op_sel_hi:[0,0,1]
	v_pk_fma_f32 v[26:27], v[32:33], v[96:97], v[26:27] op_sel:[0,1,0] op_sel_hi:[0,0,1]
	v_pk_fma_f32 v[28:29], v[32:33], v[94:95], v[28:29] op_sel:[0,1,0] op_sel_hi:[0,0,1]
	v_pk_fma_f32 v[30:31], v[32:33], v[92:93], v[30:31] op_sel:[0,1,0] op_sel_hi:[0,0,1]
	s_waitcnt lgkmcnt(7)
	v_lshlrev_b32_e32 v32, 16, v34
	ds_read_u16 v34, v116 offset:49152
	v_pk_fma_f32 v[10:11], v[32:33], v[172:173], v[10:11] op_sel:[0,1,0] op_sel_hi:[0,0,1]
	v_pk_fma_f32 v[12:13], v[32:33], v[170:171], v[12:13] op_sel:[0,1,0] op_sel_hi:[0,0,1]
	v_pk_fma_f32 v[14:15], v[32:33], v[168:169], v[14:15] op_sel:[0,1,0] op_sel_hi:[0,0,1]
	v_pk_fma_f32 v[16:17], v[32:33], v[166:167], v[16:17] op_sel:[0,1,0] op_sel_hi:[0,0,1]
	v_pk_fma_f32 v[18:19], v[32:33], v[164:165], v[18:19] op_sel:[0,1,0] op_sel_hi:[0,0,1]
	v_pk_fma_f32 v[20:21], v[32:33], v[162:163], v[20:21] op_sel:[0,1,0] op_sel_hi:[0,0,1]
	v_pk_fma_f32 v[22:23], v[32:33], v[160:161], v[22:23] op_sel:[0,1,0] op_sel_hi:[0,0,1]
	v_pk_fma_f32 v[24:25], v[32:33], v[158:159], v[24:25] op_sel:[0,1,0] op_sel_hi:[0,0,1]
	v_pk_fma_f32 v[26:27], v[32:33], v[156:157], v[26:27] op_sel:[0,1,0] op_sel_hi:[0,0,1]
	v_pk_fma_f32 v[28:29], v[32:33], v[154:155], v[28:29] op_sel:[0,1,0] op_sel_hi:[0,0,1]
	v_pk_fma_f32 v[30:31], v[32:33], v[152:153], v[30:31] op_sel:[0,1,0] op_sel_hi:[0,0,1]
	s_waitcnt lgkmcnt(7)
	v_lshlrev_b32_e32 v32, 16, v35
	ds_read_u16 v35, v116 offset:50176
	v_fmac_f32_e32 v11, v32, v114
	v_pk_fma_f32 v[12:13], v[32:33], v[112:113], v[12:13] op_sel:[0,1,0] op_sel_hi:[0,0,1]
	v_pk_fma_f32 v[14:15], v[32:33], v[110:111], v[14:15] op_sel:[0,1,0] op_sel_hi:[0,0,1]
	v_pk_fma_f32 v[16:17], v[32:33], v[108:109], v[16:17] op_sel:[0,1,0] op_sel_hi:[0,0,1]
	v_pk_fma_f32 v[18:19], v[32:33], v[106:107], v[18:19] op_sel:[0,1,0] op_sel_hi:[0,0,1]
	v_pk_fma_f32 v[20:21], v[32:33], v[104:105], v[20:21] op_sel:[0,1,0] op_sel_hi:[0,0,1]
	v_pk_fma_f32 v[22:23], v[32:33], v[102:103], v[22:23] op_sel:[0,1,0] op_sel_hi:[0,0,1]
	v_pk_fma_f32 v[24:25], v[32:33], v[100:101], v[24:25] op_sel:[0,1,0] op_sel_hi:[0,0,1]
	v_pk_fma_f32 v[26:27], v[32:33], v[98:99], v[26:27] op_sel:[0,1,0] op_sel_hi:[0,0,1]
	v_pk_fma_f32 v[28:29], v[32:33], v[96:97], v[28:29] op_sel:[0,1,0] op_sel_hi:[0,0,1]
	v_pk_fma_f32 v[30:31], v[32:33], v[94:95], v[30:31] op_sel:[0,1,0] op_sel_hi:[0,0,1]
	s_waitcnt lgkmcnt(7)
; __device__ __forceinline__ void phase_mixer0(const Params& p, LAS unsigned char* lds) {
;     ...
;             float acc[32];
; #pragma unroll
;             for (int t = 0; t < 32; ++t) acc[t] = bias;
; #pragma unroll
;             for (int j = 0; j < 62; ++j) {
;                 const float v = __uint_as_float((unsigned)ub[j * 512 + tid] << 16);
; #pragma unroll
;                 for (int t = 0; t < 32; ++t) { if (j - t >= 0 && j - t <= 30) acc[t] += v * wb[j - t]; }
;             }
; #pragma unroll
;             for (int t = 0; t < 32; ++t) cb[t * 512 + tid] = acc[t];
	v_lshlrev_b32_e32 v32, 16, v36
	ds_read_u16 v36, v116 offset:51200
	v_pk_fma_f32 v[12:13], v[32:33], v[172:173], v[12:13] op_sel:[0,1,0] op_sel_hi:[0,0,1]
	v_pk_fma_f32 v[14:15], v[32:33], v[170:171], v[14:15] op_sel:[0,1,0] op_sel_hi:[0,0,1]
	v_pk_fma_f32 v[16:17], v[32:33], v[168:169], v[16:17] op_sel:[0,1,0] op_sel_hi:[0,0,1]
	v_pk_fma_f32 v[18:19], v[32:33], v[166:167], v[18:19] op_sel:[0,1,0] op_sel_hi:[0,0,1]
	v_pk_fma_f32 v[20:21], v[32:33], v[164:165], v[20:21] op_sel:[0,1,0] op_sel_hi:[0,0,1]
	v_pk_fma_f32 v[22:23], v[32:33], v[162:163], v[22:23] op_sel:[0,1,0] op_sel_hi:[0,0,1]
	v_pk_fma_f32 v[24:25], v[32:33], v[160:161], v[24:25] op_sel:[0,1,0] op_sel_hi:[0,0,1]
	v_pk_fma_f32 v[26:27], v[32:33], v[158:159], v[26:27] op_sel:[0,1,0] op_sel_hi:[0,0,1]
	v_pk_fma_f32 v[28:29], v[32:33], v[156:157], v[28:29] op_sel:[0,1,0] op_sel_hi:[0,0,1]
	v_pk_fma_f32 v[30:31], v[32:33], v[154:155], v[30:31] op_sel:[0,1,0] op_sel_hi:[0,0,1]
	s_waitcnt lgkmcnt(7)
	v_lshlrev_b32_e32 v32, 16, v37
	ds_read_u16 v37, v116 offset:52224
	v_fmac_f32_e32 v13, v32, v114
	v_pk_fma_f32 v[14:15], v[32:33], v[112:113], v[14:15] op_sel:[0,1,0] op_sel_hi:[0,0,1]
	v_pk_fma_f32 v[16:17], v[32:33], v[110:111], v[16:17] op_sel:[0,1,0] op_sel_hi:[0,0,1]
	v_pk_fma_f32 v[18:19], v[32:33], v[108:109], v[18:19] op_sel:[0,1,0] op_sel_hi:[0,0,1]
	v_pk_fma_f32 v[20:21], v[32:33], v[106:107], v[20:21] op_sel:[0,1,0] op_sel_hi:[0,0,1]
	v_pk_fma_f32 v[22:23], v[32:33], v[104:105], v[22:23] op_sel:[0,1,0] op_sel_hi:[0,0,1]
	v_pk_fma_f32 v[24:25], v[32:33], v[102:103], v[24:25] op_sel:[0,1,0] op_sel_hi:[0,0,1]
	v_pk_fma_f32 v[26:27], v[32:33], v[100:101], v[26:27] op_sel:[0,1,0] op_sel_hi:[0,0,1]
	v_pk_fma_f32 v[28:29], v[32:33], v[98:99], v[28:29] op_sel:[0,1,0] op_sel_hi:[0,0,1]
	v_pk_fma_f32 v[30:31], v[32:33], v[96:97], v[30:31] op_sel:[0,1,0] op_sel_hi:[0,0,1]
	s_waitcnt lgkmcnt(7)
	v_lshlrev_b32_e32 v32, 16, v38
	ds_read_u16 v38, v116 offset:53248
	v_pk_fma_f32 v[14:15], v[32:33], v[172:173], v[14:15] op_sel:[0,1,0] op_sel_hi:[0,0,1]
	v_pk_fma_f32 v[16:17], v[32:33], v[170:171], v[16:17] op_sel:[0,1,0] op_sel_hi:[0,0,1]
	v_pk_fma_f32 v[18:19], v[32:33], v[168:169], v[18:19] op_sel:[0,1,0] op_sel_hi:[0,0,1]
	v_pk_fma_f32 v[20:21], v[32:33], v[166:167], v[20:21] op_sel:[0,1,0] op_sel_hi:[0,0,1]
	v_pk_fma_f32 v[22:23], v[32:33], v[164:165], v[22:23] op_sel:[0,1,0] op_sel_hi:[0,0,1]
	v_pk_fma_f32 v[24:25], v[32:33], v[162:163], v[24:25] op_sel:[0,1,0] op_sel_hi:[0,0,1]
	v_pk_fma_f32 v[26:27], v[32:33], v[160:161], v[26:27] op_sel:[0,1,0] op_sel_hi:[0,0,1]
	v_pk_fma_f32 v[28:29], v[32:33], v[158:159], v[28:29] op_sel:[0,1,0] op_sel_hi:[0,0,1]
	v_pk_fma_f32 v[30:31], v[32:33], v[156:157], v[30:31] op_sel:[0,1,0] op_sel_hi:[0,0,1]
	s_waitcnt lgkmcnt(7)
	v_lshlrev_b32_e32 v32, 16, v39
	ds_read_u16 v39, v116 offset:54272
	v_fmac_f32_e32 v15, v32, v114
	v_pk_fma_f32 v[16:17], v[32:33], v[112:113], v[16:17] op_sel:[0,1,0] op_sel_hi:[0,0,1]
	v_pk_fma_f32 v[18:19], v[32:33], v[110:111], v[18:19] op_sel:[0,1,0] op_sel_hi:[0,0,1]
	v_pk_fma_f32 v[20:21], v[32:33], v[108:109], v[20:21] op_sel:[0,1,0] op_sel_hi:[0,0,1]
	v_pk_fma_f32 v[22:23], v[32:33], v[106:107], v[22:23] op_sel:[0,1,0] op_sel_hi:[0,0,1]
	v_pk_fma_f32 v[24:25], v[32:33], v[104:105], v[24:25] op_sel:[0,1,0] op_sel_hi:[0,0,1]
	v_pk_fma_f32 v[26:27], v[32:33], v[102:103], v[26:27] op_sel:[0,1,0] op_sel_hi:[0,0,1]
	v_pk_fma_f32 v[28:29], v[32:33], v[100:101], v[28:29] op_sel:[0,1,0] op_sel_hi:[0,0,1]
	v_pk_fma_f32 v[30:31], v[32:33], v[98:99], v[30:31] op_sel:[0,1,0] op_sel_hi:[0,0,1]
	s_waitcnt lgkmcnt(7)
	v_lshlrev_b32_e32 v32, 16, v40
	ds_read_u16 v40, v116 offset:55296
	v_pk_fma_f32 v[16:17], v[32:33], v[172:173], v[16:17] op_sel:[0,1,0] op_sel_hi:[0,0,1]
	v_pk_fma_f32 v[18:19], v[32:33], v[170:171], v[18:19] op_sel:[0,1,0] op_sel_hi:[0,0,1]
	v_pk_fma_f32 v[20:21], v[32:33], v[168:169], v[20:21] op_sel:[0,1,0] op_sel_hi:[0,0,1]
	v_pk_fma_f32 v[22:23], v[32:33], v[166:167], v[22:23] op_sel:[0,1,0] op_sel_hi:[0,0,1]
	v_pk_fma_f32 v[24:25], v[32:33], v[164:165], v[24:25] op_sel:[0,1,0] op_sel_hi:[0,0,1]
	v_pk_fma_f32 v[26:27], v[32:33], v[162:163], v[26:27] op_sel:[0,1,0] op_sel_hi:[0,0,1]
	v_pk_fma_f32 v[28:29], v[32:33], v[160:161], v[28:29] op_sel:[0,1,0] op_sel_hi:[0,0,1]
	v_pk_fma_f32 v[30:31], v[32:33], v[158:159], v[30:31] op_sel:[0,1,0] op_sel_hi:[0,0,1]
	s_waitcnt lgkmcnt(7)
	v_lshlrev_b32_e32 v32, 16, v41
	ds_read_u16 v41, v116 offset:56320
	v_fmac_f32_e32 v17, v32, v114
	v_pk_fma_f32 v[18:19], v[32:33], v[112:113], v[18:19] op_sel:[0,1,0] op_sel_hi:[0,0,1]
	v_pk_fma_f32 v[20:21], v[32:33], v[110:111], v[20:21] op_sel:[0,1,0] op_sel_hi:[0,0,1]
	v_pk_fma_f32 v[22:23], v[32:33], v[108:109], v[22:23] op_sel:[0,1,0] op_sel_hi:[0,0,1]
	v_pk_fma_f32 v[24:25], v[32:33], v[106:107], v[24:25] op_sel:[0,1,0] op_sel_hi:[0,0,1]
	v_pk_fma_f32 v[26:27], v[32:33], v[104:105], v[26:27] op_sel:[0,1,0] op_sel_hi:[0,0,1]
	v_pk_fma_f32 v[28:29], v[32:33], v[102:103], v[28:29] op_sel:[0,1,0] op_sel_hi:[0,0,1]
	v_pk_fma_f32 v[30:31], v[32:33], v[100:101], v[30:31] op_sel:[0,1,0] op_sel_hi:[0,0,1]
	s_waitcnt lgkmcnt(7)
	v_lshlrev_b32_e32 v32, 16, v34
	ds_read_u16 v34, v116 offset:57344
	v_pk_fma_f32 v[18:19], v[32:33], v[172:173], v[18:19] op_sel:[0,1,0] op_sel_hi:[0,0,1]
	v_pk_fma_f32 v[20:21], v[32:33], v[170:171], v[20:21] op_sel:[0,1,0] op_sel_hi:[0,0,1]
	v_pk_fma_f32 v[22:23], v[32:33], v[168:169], v[22:23] op_sel:[0,1,0] op_sel_hi:[0,0,1]
	v_pk_fma_f32 v[24:25], v[32:33], v[166:167], v[24:25] op_sel:[0,1,0] op_sel_hi:[0,0,1]
	v_pk_fma_f32 v[26:27], v[32:33], v[164:165], v[26:27] op_sel:[0,1,0] op_sel_hi:[0,0,1]
	v_pk_fma_f32 v[28:29], v[32:33], v[162:163], v[28:29] op_sel:[0,1,0] op_sel_hi:[0,0,1]
	v_pk_fma_f32 v[30:31], v[32:33], v[160:161], v[30:31] op_sel:[0,1,0] op_sel_hi:[0,0,1]
	s_waitcnt lgkmcnt(7)
; __device__ __forceinline__ void phase_mixer0(const Params& p, LAS unsigned char* lds) {
;     ...
;             float acc[32];
; #pragma unroll
;             for (int t = 0; t < 32; ++t) acc[t] = bias;
; #pragma unroll
;             for (int j = 0; j < 62; ++j) {
;                 const float v = __uint_as_float((unsigned)ub[j * 512 + tid] << 16);
; #pragma unroll
;                 for (int t = 0; t < 32; ++t) { if (j - t >= 0 && j - t <= 30) acc[t] += v * wb[j - t]; }
;             }
; #pragma unroll
;             for (int t = 0; t < 32; ++t) cb[t * 512 + tid] = acc[t];
	v_lshlrev_b32_e32 v32, 16, v35
	ds_read_u16 v35, v116 offset:58368
	v_fmac_f32_e32 v19, v32, v114
	v_pk_fma_f32 v[20:21], v[32:33], v[112:113], v[20:21] op_sel:[0,1,0] op_sel_hi:[0,0,1]
	v_pk_fma_f32 v[22:23], v[32:33], v[110:111], v[22:23] op_sel:[0,1,0] op_sel_hi:[0,0,1]
	v_pk_fma_f32 v[24:25], v[32:33], v[108:109], v[24:25] op_sel:[0,1,0] op_sel_hi:[0,0,1]
	v_pk_fma_f32 v[26:27], v[32:33], v[106:107], v[26:27] op_sel:[0,1,0] op_sel_hi:[0,0,1]
	v_pk_fma_f32 v[28:29], v[32:33], v[104:105], v[28:29] op_sel:[0,1,0] op_sel_hi:[0,0,1]
	v_pk_fma_f32 v[30:31], v[32:33], v[102:103], v[30:31] op_sel:[0,1,0] op_sel_hi:[0,0,1]
	s_waitcnt lgkmcnt(7)
	v_lshlrev_b32_e32 v32, 16, v36
	ds_read_u16 v36, v116 offset:59392
	v_pk_fma_f32 v[20:21], v[32:33], v[172:173], v[20:21] op_sel:[0,1,0] op_sel_hi:[0,0,1]
	v_pk_fma_f32 v[22:23], v[32:33], v[170:171], v[22:23] op_sel:[0,1,0] op_sel_hi:[0,0,1]
	v_pk_fma_f32 v[24:25], v[32:33], v[168:169], v[24:25] op_sel:[0,1,0] op_sel_hi:[0,0,1]
	v_pk_fma_f32 v[26:27], v[32:33], v[166:167], v[26:27] op_sel:[0,1,0] op_sel_hi:[0,0,1]
	v_pk_fma_f32 v[28:29], v[32:33], v[164:165], v[28:29] op_sel:[0,1,0] op_sel_hi:[0,0,1]
	v_pk_fma_f32 v[30:31], v[32:33], v[162:163], v[30:31] op_sel:[0,1,0] op_sel_hi:[0,0,1]
	s_waitcnt lgkmcnt(7)
	v_lshlrev_b32_e32 v32, 16, v37
	ds_read_u16 v37, v116 offset:60416
	v_fmac_f32_e32 v21, v32, v114
	v_pk_fma_f32 v[22:23], v[32:33], v[112:113], v[22:23] op_sel:[0,1,0] op_sel_hi:[0,0,1]
	v_pk_fma_f32 v[24:25], v[32:33], v[110:111], v[24:25] op_sel:[0,1,0] op_sel_hi:[0,0,1]
	v_pk_fma_f32 v[26:27], v[32:33], v[108:109], v[26:27] op_sel:[0,1,0] op_sel_hi:[0,0,1]
	v_pk_fma_f32 v[28:29], v[32:33], v[106:107], v[28:29] op_sel:[0,1,0] op_sel_hi:[0,0,1]
	v_pk_fma_f32 v[30:31], v[32:33], v[104:105], v[30:31] op_sel:[0,1,0] op_sel_hi:[0,0,1]
	s_waitcnt lgkmcnt(7)
	v_lshlrev_b32_e32 v32, 16, v38
	ds_read_u16 v38, v116 offset:61440
	v_pk_fma_f32 v[22:23], v[32:33], v[172:173], v[22:23] op_sel:[0,1,0] op_sel_hi:[0,0,1]
	v_pk_fma_f32 v[24:25], v[32:33], v[170:171], v[24:25] op_sel:[0,1,0] op_sel_hi:[0,0,1]
	v_pk_fma_f32 v[26:27], v[32:33], v[168:169], v[26:27] op_sel:[0,1,0] op_sel_hi:[0,0,1]
	v_pk_fma_f32 v[28:29], v[32:33], v[166:167], v[28:29] op_sel:[0,1,0] op_sel_hi:[0,0,1]
	v_pk_fma_f32 v[30:31], v[32:33], v[164:165], v[30:31] op_sel:[0,1,0] op_sel_hi:[0,0,1]
	s_waitcnt lgkmcnt(7)
	v_lshlrev_b32_e32 v32, 16, v39
	ds_read_u16 v39, v116 offset:62464
	v_fmac_f32_e32 v23, v32, v114
	v_pk_fma_f32 v[24:25], v[32:33], v[112:113], v[24:25] op_sel:[0,1,0] op_sel_hi:[0,0,1]
	v_pk_fma_f32 v[26:27], v[32:33], v[110:111], v[26:27] op_sel:[0,1,0] op_sel_hi:[0,0,1]
	v_pk_fma_f32 v[28:29], v[32:33], v[108:109], v[28:29] op_sel:[0,1,0] op_sel_hi:[0,0,1]
	v_pk_fma_f32 v[30:31], v[32:33], v[106:107], v[30:31] op_sel:[0,1,0] op_sel_hi:[0,0,1]
	s_waitcnt lgkmcnt(7)
	v_lshlrev_b32_e32 v32, 16, v40
	v_pk_fma_f32 v[24:25], v[32:33], v[172:173], v[24:25] op_sel:[0,1,0] op_sel_hi:[0,0,1]
	v_pk_fma_f32 v[26:27], v[32:33], v[170:171], v[26:27] op_sel:[0,1,0] op_sel_hi:[0,0,1]
	v_pk_fma_f32 v[28:29], v[32:33], v[168:169], v[28:29] op_sel:[0,1,0] op_sel_hi:[0,0,1]
	v_pk_fma_f32 v[30:31], v[32:33], v[166:167], v[30:31] op_sel:[0,1,0] op_sel_hi:[0,0,1]
	s_waitcnt lgkmcnt(6)
	v_lshlrev_b32_e32 v32, 16, v41
	v_fmac_f32_e32 v25, v32, v114
	v_pk_fma_f32 v[26:27], v[32:33], v[112:113], v[26:27] op_sel:[0,1,0] op_sel_hi:[0,0,1]
	v_pk_fma_f32 v[28:29], v[32:33], v[110:111], v[28:29] op_sel:[0,1,0] op_sel_hi:[0,0,1]
	v_pk_fma_f32 v[30:31], v[32:33], v[108:109], v[30:31] op_sel:[0,1,0] op_sel_hi:[0,0,1]
	s_waitcnt lgkmcnt(5)
	v_lshlrev_b32_e32 v32, 16, v34
	v_pk_fma_f32 v[26:27], v[32:33], v[172:173], v[26:27] op_sel:[0,1,0] op_sel_hi:[0,0,1]
	v_pk_fma_f32 v[28:29], v[32:33], v[170:171], v[28:29] op_sel:[0,1,0] op_sel_hi:[0,0,1]
	v_pk_fma_f32 v[30:31], v[32:33], v[168:169], v[30:31] op_sel:[0,1,0] op_sel_hi:[0,0,1]
	s_waitcnt lgkmcnt(4)
	v_lshlrev_b32_e32 v32, 16, v35
	v_fmac_f32_e32 v27, v32, v114
	v_pk_fma_f32 v[28:29], v[32:33], v[112:113], v[28:29] op_sel:[0,1,0] op_sel_hi:[0,0,1]
	v_pk_fma_f32 v[30:31], v[32:33], v[110:111], v[30:31] op_sel:[0,1,0] op_sel_hi:[0,0,1]
	s_waitcnt lgkmcnt(3)
	v_lshlrev_b32_e32 v32, 16, v36
	v_pk_fma_f32 v[28:29], v[32:33], v[172:173], v[28:29] op_sel:[0,1,0] op_sel_hi:[0,0,1]
	v_pk_fma_f32 v[30:31], v[32:33], v[170:171], v[30:31] op_sel:[0,1,0] op_sel_hi:[0,0,1]
	s_waitcnt lgkmcnt(2)
	v_lshlrev_b32_e32 v32, 16, v37
	v_fmac_f32_e32 v29, v32, v114
	v_pk_fma_f32 v[30:31], v[32:33], v[112:113], v[30:31] op_sel:[0,1,0] op_sel_hi:[0,0,1]
	s_waitcnt lgkmcnt(1)
	v_lshlrev_b32_e32 v32, 16, v38
	v_pk_fma_f32 v[30:31], v[32:33], v[172:173], v[30:31] op_sel:[0,1,0] op_sel_hi:[0,0,1]
	s_waitcnt lgkmcnt(0)
	v_lshlrev_b32_e32 v32, 16, v39
	v_fmac_f32_e32 v31, v32, v114
	ds_write2st64_b32 v117, v0, v1 offset0:0 offset1:8
	ds_write2st64_b32 v117, v2, v3 offset0:16 offset1:24
	ds_write2st64_b32 v117, v4, v5 offset0:32 offset1:40
	ds_write2st64_b32 v117, v6, v7 offset0:48 offset1:56
	ds_write2st64_b32 v117, v8, v9 offset0:64 offset1:72
	ds_write2st64_b32 v117, v10, v11 offset0:80 offset1:88
	ds_write2st64_b32 v117, v12, v13 offset0:96 offset1:104
	ds_write2st64_b32 v117, v14, v15 offset0:112 offset1:120
	ds_write2st64_b32 v117, v16, v17 offset0:128 offset1:136
	ds_write2st64_b32 v117, v18, v19 offset0:144 offset1:152
	ds_write2st64_b32 v117, v20, v21 offset0:160 offset1:168
	ds_write2st64_b32 v117, v22, v23 offset0:176 offset1:184
	ds_write2st64_b32 v117, v24, v25 offset0:192 offset1:200
	ds_write2st64_b32 v117, v26, v27 offset0:208 offset1:216
	ds_write2st64_b32 v117, v28, v29 offset0:224 offset1:232
	ds_write2st64_b32 v117, v30, v31 offset0:240 offset1:248
	s_branch .LBB0_263
; __device__ __forceinline__ void phase_mixer0(const Params& p, LAS unsigned char* lds) {
;     ...
;             float acc[8];
; #pragma unroll
;             for (int t = 0; t < 8; ++t) acc[t] = bias;
; #pragma unroll
;             for (int j = 0; j < 38; ++j) {
;                 const float v = __uint_as_float((unsigned)ub[j * 512 + tid] << 16);
; #pragma unroll
;                 for (int t = 0; t < 8; ++t) { if (j - t >= 0 && j - t <= 30) acc[t] += v * wb[j - t]; }
;             }
; #pragma unroll
;             for (int t = 0; t < 8; ++t) cb[t * 512 + tid] = acc[t];
.Lmx0_conv_s:
	ds_read_u16 v34, v116
	ds_read_u16 v35, v116 offset:1024
	ds_read_u16 v36, v116 offset:2048
	ds_read_u16 v37, v116 offset:3072
	ds_read_u16 v38, v116 offset:4096
	ds_read_u16 v39, v116 offset:5120
	ds_read_u16 v40, v116 offset:6144
	ds_read_u16 v41, v116 offset:7168
	s_waitcnt lgkmcnt(7)
	v_lshlrev_b32_e32 v32, 16, v34
	ds_read_u16 v34, v116 offset:8192
	v_fma_f32 v0, v32, v84, v115
	v_mov_b32_e32 v1, v115
	s_waitcnt lgkmcnt(7)
	v_lshlrev_b32_e32 v32, 16, v35
	ds_read_u16 v35, v116 offset:9216
	v_pk_fma_f32 v[0:1], v[32:33], v[84:85], v[0:1] op_sel:[0,1,0] op_sel_hi:[0,0,1]
	s_waitcnt lgkmcnt(7)
	v_lshlrev_b32_e32 v32, 16, v36
	ds_read_u16 v36, v116 offset:10240
	v_pk_fma_f32 v[0:1], v[32:33], v[144:145], v[0:1] op_sel:[0,1,0] op_sel_hi:[0,0,1]
	v_fma_f32 v2, v32, v84, v115
	v_mov_b32_e32 v3, v115
	s_waitcnt lgkmcnt(7)
	v_lshlrev_b32_e32 v32, 16, v37
	ds_read_u16 v37, v116 offset:11264
	v_pk_fma_f32 v[0:1], v[32:33], v[86:87], v[0:1] op_sel:[0,1,0] op_sel_hi:[0,0,1]
	v_pk_fma_f32 v[2:3], v[32:33], v[84:85], v[2:3] op_sel:[0,1,0] op_sel_hi:[0,0,1]
	s_waitcnt lgkmcnt(7)
	v_lshlrev_b32_e32 v32, 16, v38
	ds_read_u16 v38, v116 offset:12288
	v_pk_fma_f32 v[0:1], v[32:33], v[146:147], v[0:1] op_sel:[0,1,0] op_sel_hi:[0,0,1]
	v_pk_fma_f32 v[2:3], v[32:33], v[144:145], v[2:3] op_sel:[0,1,0] op_sel_hi:[0,0,1]
	v_fma_f32 v4, v32, v84, v115
	v_mov_b32_e32 v5, v115
	s_waitcnt lgkmcnt(7)
	v_lshlrev_b32_e32 v32, 16, v39
	ds_read_u16 v39, v116 offset:13312
	v_pk_fma_f32 v[0:1], v[32:33], v[88:89], v[0:1] op_sel:[0,1,0] op_sel_hi:[0,0,1]
	v_pk_fma_f32 v[2:3], v[32:33], v[86:87], v[2:3] op_sel:[0,1,0] op_sel_hi:[0,0,1]
	v_pk_fma_f32 v[4:5], v[32:33], v[84:85], v[4:5] op_sel:[0,1,0] op_sel_hi:[0,0,1]
	s_waitcnt lgkmcnt(7)
	v_lshlrev_b32_e32 v32, 16, v40
	ds_read_u16 v40, v116 offset:14336
	v_pk_fma_f32 v[0:1], v[32:33], v[148:149], v[0:1] op_sel:[0,1,0] op_sel_hi:[0,0,1]
	v_pk_fma_f32 v[2:3], v[32:33], v[146:147], v[2:3] op_sel:[0,1,0] op_sel_hi:[0,0,1]
	v_pk_fma_f32 v[4:5], v[32:33], v[144:145], v[4:5] op_sel:[0,1,0] op_sel_hi:[0,0,1]
	v_fma_f32 v6, v32, v84, v115
	v_mov_b32_e32 v7, v115
	s_waitcnt lgkmcnt(7)
	v_lshlrev_b32_e32 v32, 16, v41
	ds_read_u16 v41, v116 offset:15360
	v_pk_fma_f32 v[0:1], v[32:33], v[90:91], v[0:1] op_sel:[0,1,0] op_sel_hi:[0,0,1]
	v_pk_fma_f32 v[2:3], v[32:33], v[88:89], v[2:3] op_sel:[0,1,0] op_sel_hi:[0,0,1]
	v_pk_fma_f32 v[4:5], v[32:33], v[86:87], v[4:5] op_sel:[0,1,0] op_sel_hi:[0,0,1]
	v_pk_fma_f32 v[6:7], v[32:33], v[84:85], v[6:7] op_sel:[0,1,0] op_sel_hi:[0,0,1]
	s_waitcnt lgkmcnt(7)
	v_lshlrev_b32_e32 v32, 16, v34
	ds_read_u16 v34, v116 offset:16384
	v_pk_fma_f32 v[0:1], v[32:33], v[150:151], v[0:1] op_sel:[0,1,0] op_sel_hi:[0,0,1]
	v_pk_fma_f32 v[2:3], v[32:33], v[148:149], v[2:3] op_sel:[0,1,0] op_sel_hi:[0,0,1]
	v_pk_fma_f32 v[4:5], v[32:33], v[146:147], v[4:5] op_sel:[0,1,0] op_sel_hi:[0,0,1]
	v_pk_fma_f32 v[6:7], v[32:33], v[144:145], v[6:7] op_sel:[0,1,0] op_sel_hi:[0,0,1]
	s_waitcnt lgkmcnt(7)
	v_lshlrev_b32_e32 v32, 16, v35
	ds_read_u16 v35, v116 offset:17408
	v_pk_fma_f32 v[0:1], v[32:33], v[92:93], v[0:1] op_sel:[0,1,0] op_sel_hi:[0,0,1]
	v_pk_fma_f32 v[2:3], v[32:33], v[90:91], v[2:3] op_sel:[0,1,0] op_sel_hi:[0,0,1]
	v_pk_fma_f32 v[4:5], v[32:33], v[88:89], v[4:5] op_sel:[0,1,0] op_sel_hi:[0,0,1]
	v_pk_fma_f32 v[6:7], v[32:33], v[86:87], v[6:7] op_sel:[0,1,0] op_sel_hi:[0,0,1]
	s_waitcnt lgkmcnt(7)
	v_lshlrev_b32_e32 v32, 16, v36
	ds_read_u16 v36, v116 offset:18432
	v_pk_fma_f32 v[0:1], v[32:33], v[152:153], v[0:1] op_sel:[0,1,0] op_sel_hi:[0,0,1]
	v_pk_fma_f32 v[2:3], v[32:33], v[150:151], v[2:3] op_sel:[0,1,0] op_sel_hi:[0,0,1]
	v_pk_fma_f32 v[4:5], v[32:33], v[148:149], v[4:5] op_sel:[0,1,0] op_sel_hi:[0,0,1]
	v_pk_fma_f32 v[6:7], v[32:33], v[146:147], v[6:7] op_sel:[0,1,0] op_sel_hi:[0,0,1]
	s_waitcnt lgkmcnt(7)
	v_lshlrev_b32_e32 v32, 16, v37
	ds_read_u16 v37, v116 offset:19456
	v_pk_fma_f32 v[0:1], v[32:33], v[94:95], v[0:1] op_sel:[0,1,0] op_sel_hi:[0,0,1]
	v_pk_fma_f32 v[2:3], v[32:33], v[92:93], v[2:3] op_sel:[0,1,0] op_sel_hi:[0,0,1]
	v_pk_fma_f32 v[4:5], v[32:33], v[90:91], v[4:5] op_sel:[0,1,0] op_sel_hi:[0,0,1]
	v_pk_fma_f32 v[6:7], v[32:33], v[88:89], v[6:7] op_sel:[0,1,0] op_sel_hi:[0,0,1]
	s_waitcnt lgkmcnt(7)
	v_lshlrev_b32_e32 v32, 16, v38
	ds_read_u16 v38, v116 offset:20480
	v_pk_fma_f32 v[0:1], v[32:33], v[154:155], v[0:1] op_sel:[0,1,0] op_sel_hi:[0,0,1]
	v_pk_fma_f32 v[2:3], v[32:33], v[152:153], v[2:3] op_sel:[0,1,0] op_sel_hi:[0,0,1]
	v_pk_fma_f32 v[4:5], v[32:33], v[150:151], v[4:5] op_sel:[0,1,0] op_sel_hi:[0,0,1]
	v_pk_fma_f32 v[6:7], v[32:33], v[148:149], v[6:7] op_sel:[0,1,0] op_sel_hi:[0,0,1]
	s_waitcnt lgkmcnt(7)
	v_lshlrev_b32_e32 v32, 16, v39
	ds_read_u16 v39, v116 offset:21504
	v_pk_fma_f32 v[0:1], v[32:33], v[96:97], v[0:1] op_sel:[0,1,0] op_sel_hi:[0,0,1]
	v_pk_fma_f32 v[2:3], v[32:33], v[94:95], v[2:3] op_sel:[0,1,0] op_sel_hi:[0,0,1]
	v_pk_fma_f32 v[4:5], v[32:33], v[92:93], v[4:5] op_sel:[0,1,0] op_sel_hi:[0,0,1]
	v_pk_fma_f32 v[6:7], v[32:33], v[90:91], v[6:7] op_sel:[0,1,0] op_sel_hi:[0,0,1]
	s_waitcnt lgkmcnt(7)
	v_lshlrev_b32_e32 v32, 16, v40
	ds_read_u16 v40, v116 offset:22528
	v_pk_fma_f32 v[0:1], v[32:33], v[156:157], v[0:1] op_sel:[0,1,0] op_sel_hi:[0,0,1]
	v_pk_fma_f32 v[2:3], v[32:33], v[154:155], v[2:3] op_sel:[0,1,0] op_sel_hi:[0,0,1]
	v_pk_fma_f32 v[4:5], v[32:33], v[152:153], v[4:5] op_sel:[0,1,0] op_sel_hi:[0,0,1]
	v_pk_fma_f32 v[6:7], v[32:33], v[150:151], v[6:7] op_sel:[0,1,0] op_sel_hi:[0,0,1]
	s_waitcnt lgkmcnt(7)
; __device__ __forceinline__ void phase_mixer0(const Params& p, LAS unsigned char* lds) {
;     ...
;             float acc[8];
; #pragma unroll
;             for (int t = 0; t < 8; ++t) acc[t] = bias;
; #pragma unroll
;             for (int j = 0; j < 38; ++j) {
;                 const float v = __uint_as_float((unsigned)ub[j * 512 + tid] << 16);
; #pragma unroll
;                 for (int t = 0; t < 8; ++t) { if (j - t >= 0 && j - t <= 30) acc[t] += v * wb[j - t]; }
;             }
; #pragma unroll
;             for (int t = 0; t < 8; ++t) cb[t * 512 + tid] = acc[t];
	v_lshlrev_b32_e32 v32, 16, v41
	ds_read_u16 v41, v116 offset:23552
	v_pk_fma_f32 v[0:1], v[32:33], v[98:99], v[0:1] op_sel:[0,1,0] op_sel_hi:[0,0,1]
	v_pk_fma_f32 v[2:3], v[32:33], v[96:97], v[2:3] op_sel:[0,1,0] op_sel_hi:[0,0,1]
	v_pk_fma_f32 v[4:5], v[32:33], v[94:95], v[4:5] op_sel:[0,1,0] op_sel_hi:[0,0,1]
	v_pk_fma_f32 v[6:7], v[32:33], v[92:93], v[6:7] op_sel:[0,1,0] op_sel_hi:[0,0,1]
	s_waitcnt lgkmcnt(7)
	v_lshlrev_b32_e32 v32, 16, v34
	ds_read_u16 v34, v116 offset:24576
	v_pk_fma_f32 v[0:1], v[32:33], v[158:159], v[0:1] op_sel:[0,1,0] op_sel_hi:[0,0,1]
	v_pk_fma_f32 v[2:3], v[32:33], v[156:157], v[2:3] op_sel:[0,1,0] op_sel_hi:[0,0,1]
	v_pk_fma_f32 v[4:5], v[32:33], v[154:155], v[4:5] op_sel:[0,1,0] op_sel_hi:[0,0,1]
	v_pk_fma_f32 v[6:7], v[32:33], v[152:153], v[6:7] op_sel:[0,1,0] op_sel_hi:[0,0,1]
	s_waitcnt lgkmcnt(7)
	v_lshlrev_b32_e32 v32, 16, v35
	ds_read_u16 v35, v116 offset:25600
	v_pk_fma_f32 v[0:1], v[32:33], v[100:101], v[0:1] op_sel:[0,1,0] op_sel_hi:[0,0,1]
	v_pk_fma_f32 v[2:3], v[32:33], v[98:99], v[2:3] op_sel:[0,1,0] op_sel_hi:[0,0,1]
	v_pk_fma_f32 v[4:5], v[32:33], v[96:97], v[4:5] op_sel:[0,1,0] op_sel_hi:[0,0,1]
	v_pk_fma_f32 v[6:7], v[32:33], v[94:95], v[6:7] op_sel:[0,1,0] op_sel_hi:[0,0,1]
	s_waitcnt lgkmcnt(7)
	v_lshlrev_b32_e32 v32, 16, v36
	ds_read_u16 v36, v116 offset:26624
	v_pk_fma_f32 v[0:1], v[32:33], v[160:161], v[0:1] op_sel:[0,1,0] op_sel_hi:[0,0,1]
	v_pk_fma_f32 v[2:3], v[32:33], v[158:159], v[2:3] op_sel:[0,1,0] op_sel_hi:[0,0,1]
	v_pk_fma_f32 v[4:5], v[32:33], v[156:157], v[4:5] op_sel:[0,1,0] op_sel_hi:[0,0,1]
	v_pk_fma_f32 v[6:7], v[32:33], v[154:155], v[6:7] op_sel:[0,1,0] op_sel_hi:[0,0,1]
	s_waitcnt lgkmcnt(7)
	v_lshlrev_b32_e32 v32, 16, v37
	ds_read_u16 v37, v116 offset:27648
	v_pk_fma_f32 v[0:1], v[32:33], v[102:103], v[0:1] op_sel:[0,1,0] op_sel_hi:[0,0,1]
	v_pk_fma_f32 v[2:3], v[32:33], v[100:101], v[2:3] op_sel:[0,1,0] op_sel_hi:[0,0,1]
	v_pk_fma_f32 v[4:5], v[32:33], v[98:99], v[4:5] op_sel:[0,1,0] op_sel_hi:[0,0,1]
	v_pk_fma_f32 v[6:7], v[32:33], v[96:97], v[6:7] op_sel:[0,1,0] op_sel_hi:[0,0,1]
	s_waitcnt lgkmcnt(7)
	v_lshlrev_b32_e32 v32, 16, v38
	ds_read_u16 v38, v116 offset:28672
	v_pk_fma_f32 v[0:1], v[32:33], v[162:163], v[0:1] op_sel:[0,1,0] op_sel_hi:[0,0,1]
	v_pk_fma_f32 v[2:3], v[32:33], v[160:161], v[2:3] op_sel:[0,1,0] op_sel_hi:[0,0,1]
	v_pk_fma_f32 v[4:5], v[32:33], v[158:159], v[4:5] op_sel:[0,1,0] op_sel_hi:[0,0,1]
	v_pk_fma_f32 v[6:7], v[32:33], v[156:157], v[6:7] op_sel:[0,1,0] op_sel_hi:[0,0,1]
	s_waitcnt lgkmcnt(7)
	v_lshlrev_b32_e32 v32, 16, v39
	ds_read_u16 v39, v116 offset:29696
	v_pk_fma_f32 v[0:1], v[32:33], v[104:105], v[0:1] op_sel:[0,1,0] op_sel_hi:[0,0,1]
	v_pk_fma_f32 v[2:3], v[32:33], v[102:103], v[2:3] op_sel:[0,1,0] op_sel_hi:[0,0,1]
	v_pk_fma_f32 v[4:5], v[32:33], v[100:101], v[4:5] op_sel:[0,1,0] op_sel_hi:[0,0,1]
	v_pk_fma_f32 v[6:7], v[32:33], v[98:99], v[6:7] op_sel:[0,1,0] op_sel_hi:[0,0,1]
	s_waitcnt lgkmcnt(7)
	v_lshlrev_b32_e32 v32, 16, v40
	ds_read_u16 v40, v116 offset:30720
	v_pk_fma_f32 v[0:1], v[32:33], v[164:165], v[0:1] op_sel:[0,1,0] op_sel_hi:[0,0,1]
	v_pk_fma_f32 v[2:3], v[32:33], v[162:163], v[2:3] op_sel:[0,1,0] op_sel_hi:[0,0,1]
	v_pk_fma_f32 v[4:5], v[32:33], v[160:161], v[4:5] op_sel:[0,1,0] op_sel_hi:[0,0,1]
	v_pk_fma_f32 v[6:7], v[32:33], v[158:159], v[6:7] op_sel:[0,1,0] op_sel_hi:[0,0,1]
	s_waitcnt lgkmcnt(7)
	v_lshlrev_b32_e32 v32, 16, v41
	ds_read_u16 v41, v116 offset:31744
	v_pk_fma_f32 v[0:1], v[32:33], v[106:107], v[0:1] op_sel:[0,1,0] op_sel_hi:[0,0,1]
	v_pk_fma_f32 v[2:3], v[32:33], v[104:105], v[2:3] op_sel:[0,1,0] op_sel_hi:[0,0,1]
	v_pk_fma_f32 v[4:5], v[32:33], v[102:103], v[4:5] op_sel:[0,1,0] op_sel_hi:[0,0,1]
	v_pk_fma_f32 v[6:7], v[32:33], v[100:101], v[6:7] op_sel:[0,1,0] op_sel_hi:[0,0,1]
	s_waitcnt lgkmcnt(7)
	v_lshlrev_b32_e32 v32, 16, v34
	ds_read_u16 v34, v116 offset:32768
	v_pk_fma_f32 v[0:1], v[32:33], v[166:167], v[0:1] op_sel:[0,1,0] op_sel_hi:[0,0,1]
	v_pk_fma_f32 v[2:3], v[32:33], v[164:165], v[2:3] op_sel:[0,1,0] op_sel_hi:[0,0,1]
	v_pk_fma_f32 v[4:5], v[32:33], v[162:163], v[4:5] op_sel:[0,1,0] op_sel_hi:[0,0,1]
	v_pk_fma_f32 v[6:7], v[32:33], v[160:161], v[6:7] op_sel:[0,1,0] op_sel_hi:[0,0,1]
	s_waitcnt lgkmcnt(7)
; __device__ __forceinline__ void phase_mixer0(const Params& p, LAS unsigned char* lds) {
;     ...
;             float acc[8];
; #pragma unroll
;             for (int t = 0; t < 8; ++t) acc[t] = bias;
; #pragma unroll
;             for (int j = 0; j < 38; ++j) {
;                 const float v = __uint_as_float((unsigned)ub[j * 512 + tid] << 16);
; #pragma unroll
;                 for (int t = 0; t < 8; ++t) { if (j - t >= 0 && j - t <= 30) acc[t] += v * wb[j - t]; }
;             }
; #pragma unroll
;             for (int t = 0; t < 8; ++t) cb[t * 512 + tid] = acc[t];
;         }
;         __syncthreads();
	v_lshlrev_b32_e32 v32, 16, v35
	ds_read_u16 v35, v116 offset:33792
	v_pk_fma_f32 v[0:1], v[32:33], v[108:109], v[0:1] op_sel:[0,1,0] op_sel_hi:[0,0,1]
	v_pk_fma_f32 v[2:3], v[32:33], v[106:107], v[2:3] op_sel:[0,1,0] op_sel_hi:[0,0,1]
	v_pk_fma_f32 v[4:5], v[32:33], v[104:105], v[4:5] op_sel:[0,1,0] op_sel_hi:[0,0,1]
	v_pk_fma_f32 v[6:7], v[32:33], v[102:103], v[6:7] op_sel:[0,1,0] op_sel_hi:[0,0,1]
	s_waitcnt lgkmcnt(7)
	v_lshlrev_b32_e32 v32, 16, v36
	ds_read_u16 v36, v116 offset:34816
	v_pk_fma_f32 v[0:1], v[32:33], v[168:169], v[0:1] op_sel:[0,1,0] op_sel_hi:[0,0,1]
	v_pk_fma_f32 v[2:3], v[32:33], v[166:167], v[2:3] op_sel:[0,1,0] op_sel_hi:[0,0,1]
	v_pk_fma_f32 v[4:5], v[32:33], v[164:165], v[4:5] op_sel:[0,1,0] op_sel_hi:[0,0,1]
	v_pk_fma_f32 v[6:7], v[32:33], v[162:163], v[6:7] op_sel:[0,1,0] op_sel_hi:[0,0,1]
	s_waitcnt lgkmcnt(7)
	v_lshlrev_b32_e32 v32, 16, v37
	ds_read_u16 v37, v116 offset:35840
	v_pk_fma_f32 v[0:1], v[32:33], v[110:111], v[0:1] op_sel:[0,1,0] op_sel_hi:[0,0,1]
	v_pk_fma_f32 v[2:3], v[32:33], v[108:109], v[2:3] op_sel:[0,1,0] op_sel_hi:[0,0,1]
	v_pk_fma_f32 v[4:5], v[32:33], v[106:107], v[4:5] op_sel:[0,1,0] op_sel_hi:[0,0,1]
	v_pk_fma_f32 v[6:7], v[32:33], v[104:105], v[6:7] op_sel:[0,1,0] op_sel_hi:[0,0,1]
	s_waitcnt lgkmcnt(7)
	v_lshlrev_b32_e32 v32, 16, v38
	ds_read_u16 v38, v116 offset:36864
	v_pk_fma_f32 v[0:1], v[32:33], v[170:171], v[0:1] op_sel:[0,1,0] op_sel_hi:[0,0,1]
	v_pk_fma_f32 v[2:3], v[32:33], v[168:169], v[2:3] op_sel:[0,1,0] op_sel_hi:[0,0,1]
	v_pk_fma_f32 v[4:5], v[32:33], v[166:167], v[4:5] op_sel:[0,1,0] op_sel_hi:[0,0,1]
	v_pk_fma_f32 v[6:7], v[32:33], v[164:165], v[6:7] op_sel:[0,1,0] op_sel_hi:[0,0,1]
	s_waitcnt lgkmcnt(7)
	v_lshlrev_b32_e32 v32, 16, v39
	ds_read_u16 v39, v116 offset:37888
	v_pk_fma_f32 v[0:1], v[32:33], v[112:113], v[0:1] op_sel:[0,1,0] op_sel_hi:[0,0,1]
	v_pk_fma_f32 v[2:3], v[32:33], v[110:111], v[2:3] op_sel:[0,1,0] op_sel_hi:[0,0,1]
	v_pk_fma_f32 v[4:5], v[32:33], v[108:109], v[4:5] op_sel:[0,1,0] op_sel_hi:[0,0,1]
	v_pk_fma_f32 v[6:7], v[32:33], v[106:107], v[6:7] op_sel:[0,1,0] op_sel_hi:[0,0,1]
	s_waitcnt lgkmcnt(7)
	v_lshlrev_b32_e32 v32, 16, v40
	v_pk_fma_f32 v[0:1], v[32:33], v[172:173], v[0:1] op_sel:[0,1,0] op_sel_hi:[0,0,1]
	v_pk_fma_f32 v[2:3], v[32:33], v[170:171], v[2:3] op_sel:[0,1,0] op_sel_hi:[0,0,1]
	v_pk_fma_f32 v[4:5], v[32:33], v[168:169], v[4:5] op_sel:[0,1,0] op_sel_hi:[0,0,1]
	v_pk_fma_f32 v[6:7], v[32:33], v[166:167], v[6:7] op_sel:[0,1,0] op_sel_hi:[0,0,1]
	s_waitcnt lgkmcnt(6)
	v_lshlrev_b32_e32 v32, 16, v41
	v_fmac_f32_e32 v1, v32, v114
	v_pk_fma_f32 v[2:3], v[32:33], v[112:113], v[2:3] op_sel:[0,1,0] op_sel_hi:[0,0,1]
	v_pk_fma_f32 v[4:5], v[32:33], v[110:111], v[4:5] op_sel:[0,1,0] op_sel_hi:[0,0,1]
	v_pk_fma_f32 v[6:7], v[32:33], v[108:109], v[6:7] op_sel:[0,1,0] op_sel_hi:[0,0,1]
	s_waitcnt lgkmcnt(5)
	v_lshlrev_b32_e32 v32, 16, v34
	v_pk_fma_f32 v[2:3], v[32:33], v[172:173], v[2:3] op_sel:[0,1,0] op_sel_hi:[0,0,1]
	v_pk_fma_f32 v[4:5], v[32:33], v[170:171], v[4:5] op_sel:[0,1,0] op_sel_hi:[0,0,1]
	v_pk_fma_f32 v[6:7], v[32:33], v[168:169], v[6:7] op_sel:[0,1,0] op_sel_hi:[0,0,1]
	s_waitcnt lgkmcnt(4)
	v_lshlrev_b32_e32 v32, 16, v35
	v_fmac_f32_e32 v3, v32, v114
	v_pk_fma_f32 v[4:5], v[32:33], v[112:113], v[4:5] op_sel:[0,1,0] op_sel_hi:[0,0,1]
	v_pk_fma_f32 v[6:7], v[32:33], v[110:111], v[6:7] op_sel:[0,1,0] op_sel_hi:[0,0,1]
	s_waitcnt lgkmcnt(3)
	v_lshlrev_b32_e32 v32, 16, v36
	v_pk_fma_f32 v[4:5], v[32:33], v[172:173], v[4:5] op_sel:[0,1,0] op_sel_hi:[0,0,1]
	v_pk_fma_f32 v[6:7], v[32:33], v[170:171], v[6:7] op_sel:[0,1,0] op_sel_hi:[0,0,1]
	s_waitcnt lgkmcnt(2)
	v_lshlrev_b32_e32 v32, 16, v37
	v_fmac_f32_e32 v5, v32, v114
	v_pk_fma_f32 v[6:7], v[32:33], v[112:113], v[6:7] op_sel:[0,1,0] op_sel_hi:[0,0,1]
	s_waitcnt lgkmcnt(1)
	v_lshlrev_b32_e32 v32, 16, v38
	v_pk_fma_f32 v[6:7], v[32:33], v[172:173], v[6:7] op_sel:[0,1,0] op_sel_hi:[0,0,1]
	s_waitcnt lgkmcnt(0)
	v_lshlrev_b32_e32 v32, 16, v39
	v_fmac_f32_e32 v7, v32, v114
	ds_write2st64_b32 v117, v0, v1 offset0:0 offset1:8
	ds_write2st64_b32 v117, v2, v3 offset0:16 offset1:24
	ds_write2st64_b32 v117, v4, v5 offset0:32 offset1:40
	ds_write2st64_b32 v117, v6, v7 offset0:48 offset1:56

; #define LAS __attribute__((address_space(3)))
; __device__ __forceinline__ v4u pack8(const float (&f)[8]) { v4u w; w.x = pk2(f[0], f[1]); w.y = pk2(f[2], f[3]); w.z = pk2(f[4], f[5]); w.w = pk2(f[6], f[7]); return w; }
; __device__ __forceinline__ float sigmoidf_fast(float x) { return __builtin_amdgcn_rcpf(1.0f + __expf(-x)); }
; __device__ __forceinline__ void phase_mixer0(const Params& p, LAS unsigned char* lds) {
;     ...
;             float g8[8], b8[8]; load8f(lng + c8, g8); load8f(lnb + c8, b8);
;             for (int i = 0; i < 4; ++i) {
;                 const int t = wave * 4 + i;
;                 if (t < nout) {
;                     const f32x4 a = *(const LAS f32x4*)(cb + t * 512 + c8), b = *(const LAS f32x4*)(cb + t * 512 + c8 + 4);
;                     float x[8] = {a[0], a[1], a[2], a[3], b[0], b[1], b[2], b[3]};
;                     float s = 0.f;
; #pragma unroll
;                     for (int q = 0; q < 8; ++q) s += x[q];
;                     const float mean = wave_sum(s) * (1.f / 512.f);
;                     float s2 = 0.f;
; #pragma unroll
;                     for (int q = 0; q < 8; ++q) { x[q] -= mean; s2 += x[q] * x[q]; }
;                     const float rstd = __builtin_amdgcn_rsqf(wave_sum(s2) * (1.f / 512.f) + EPS);
; #pragma unroll
;                     for (int q = 0; q < 8; ++q) { const float y = x[q] * rstd * g8[q] + b8[q]; x[q] = y * sigmoidf_fast(y); }
;                     *(v4u*)(Y + (size_t)(rowbase + t) * D + 512 + c8) = pack8(x);
;                 }
;             }
;         }
;         if (wave * 4 < nout) {
;             float w0[8], w1[8], w2[8]; load8f(cwa + c8, w0); load8f(cwa + 512 + c8, w1); load8f(cwa + 1024 + c8, w2);
;             float um2[8], um1[8];
; #pragma unroll
;             for (int h = 0; h < 2; ++h) {
;                 const int tt = t0 + wave * 4 - 2 + h; float u[8];
;                 if (tt >= 0) unpack8(*(const v4u*)(Z + (rowbase + (tt - t0)) * NZ1 + 512 + c8), u);
;                 else if (samp) load8f(st_a + ((size_t)seq * 2 + (2 + tt)) * 512 + c8, u);
.Lmx0_s34:
	s_cmp_ge_i32 s82, s56
	s_cbranch_scc1 .LBB0_235
	global_load_dwordx4 v[142:145], v[56:57], off
	global_load_dwordx4 v[146:149], v[56:57], off offset:16
	global_load_dwordx4 v[150:153], v[58:59], off
	global_load_dwordx4 v[154:157], v[58:59], off offset:16
	global_load_dwordx4 v[158:161], v[60:61], off
	global_load_dwordx4 v[162:165], v[60:61], off offset:16
	global_load_dwordx4 v[166:169], v[60:61], off offset:2048
	global_load_dwordx4 v[170:173], v[60:61], off offset:2064
	global_load_dwordx4 v[174:177], v[62:63], off
	global_load_dwordx4 v[178:181], v[62:63], off offset:16
	s_add_u32 s0, s42, s82
	s_addc_u32 s1, s43, 0
	s_cmpk_gt_i32 s8, 0x1ff
	s_cselect_b32 s80, 0, s53
	s_add_i32 s80, s80, s82
	s_mul_i32 s12, s0, 0xc00
	s_mul_hi_u32 s13, s0, 0xc00
	s_mul_i32 s14, s1, 0xc00
	s_add_i32 s13, s13, s14
	v_lshl_add_u64 v[48:49], v[74:75], 0, s[12:13]
	global_load_dwordx4 v[206:209], v[48:49], off
	global_load_dwordx4 v[190:193], v[48:49], off offset:1024
	s_add_u32 s12, s12, 0xc00
	s_addc_u32 s13, s13, 0
	v_lshl_add_u64 v[48:49], v[74:75], 0, s[12:13]
	global_load_dwordx4 v[210:213], v[48:49], off
	global_load_dwordx4 v[194:197], v[48:49], off offset:1024
	s_add_u32 s12, s12, 0xc00
	s_addc_u32 s13, s13, 0
	v_lshl_add_u64 v[48:49], v[74:75], 0, s[12:13]
	global_load_dwordx4 v[214:217], v[48:49], off
	global_load_dwordx4 v[198:201], v[48:49], off offset:1024
	s_add_u32 s12, s12, 0xc00
	s_addc_u32 s13, s13, 0
	v_lshl_add_u64 v[48:49], v[74:75], 0, s[12:13]
	global_load_dwordx4 v[218:221], v[48:49], off
	global_load_dwordx4 v[202:205], v[48:49], off offset:1024
	s_sub_u32 s12, s12, 0x2400
	s_subb_u32 s13, s13, 0
	s_cmp_lt_i32 s80, 2
	s_cselect_b32 s9, 0, 0x1800
	s_cselect_b32 s14, 0, 0xc00
	s_sub_u32 s6, s12, s9
	s_subb_u32 s7, s13, 0
	v_lshl_add_u64 v[48:49], v[74:75], 0, s[6:7]
	global_load_dwordx4 v[182:185], v[48:49], off offset:1024
	s_sub_u32 s6, s12, s14
	s_subb_u32 s7, s13, 0
	v_lshl_add_u64 v[48:49], v[74:75], 0, s[6:7]
	global_load_dwordx4 v[186:189], v[48:49], off offset:1024
.Lmx0_s34_c:
	s_add_u32 s0, s42, s82
	s_addc_u32 s1, s43, 0
	s_cmpk_gt_i32 s8, 0x1ff
	s_cselect_b32 s80, 0, s53
	s_add_i32 s80, s80, s82
	s_waitcnt vmcnt(0)
	v_mbcnt_lo_u32_b32 v46, -1, 0
	v_mbcnt_hi_u32_b32 v46, -1, v46
	v_xor_b32_e32 v40, 1, v46
	v_xor_b32_e32 v41, 2, v46
	v_xor_b32_e32 v42, 4, v46
	v_xor_b32_e32 v43, 8, v46
	v_xor_b32_e32 v44, 16, v46
	v_xor_b32_e32 v45, 32, v46
	v_lshlrev_b32_e32 v40, 2, v40
	v_lshlrev_b32_e32 v41, 2, v41
	v_lshlrev_b32_e32 v42, 2, v42
	v_lshlrev_b32_e32 v43, 2, v43
	v_lshlrev_b32_e32 v44, 2, v44
	v_lshlrev_b32_e32 v45, 2, v45
	v_add_u32_e32 v47, s83, v118
	v_add_u32_e32 v47, 0xf800, v47
	ds_read_b128 v[0:3], v47
	ds_read_b128 v[4:7], v47 offset:16
	ds_read_b128 v[8:11], v47 offset:2048
	ds_read_b128 v[12:15], v47 offset:2064
	ds_read_b128 v[16:19], v47 offset:4096
	ds_read_b128 v[20:23], v47 offset:4112
	ds_read_b128 v[24:27], v47 offset:6144
	ds_read_b128 v[28:31], v47 offset:6160
	s_waitcnt lgkmcnt(0)
	v_add_f32_e32 v32, 0, v0
	v_add_f32_e32 v33, 0, v8
	v_add_f32_e32 v34, 0, v16
	v_add_f32_e32 v35, 0, v24
	v_add_f32_e32 v32, v1, v32
	v_add_f32_e32 v33, v9, v33
	v_add_f32_e32 v34, v17, v34
	v_add_f32_e32 v35, v25, v35
	v_add_f32_e32 v32, v2, v32
	v_add_f32_e32 v33, v10, v33
	v_add_f32_e32 v34, v18, v34
	v_add_f32_e32 v35, v26, v35
	v_add_f32_e32 v32, v3, v32
	v_add_f32_e32 v33, v11, v33
	v_add_f32_e32 v34, v19, v34
	v_add_f32_e32 v35, v27, v35
	v_add_f32_e32 v32, v4, v32
	v_add_f32_e32 v33, v12, v33
	v_add_f32_e32 v34, v20, v34
	v_add_f32_e32 v35, v28, v35
	v_add_f32_e32 v32, v5, v32
	v_add_f32_e32 v33, v13, v33
	v_add_f32_e32 v34, v21, v34
	v_add_f32_e32 v35, v29, v35
	v_add_f32_e32 v32, v6, v32
	v_add_f32_e32 v33, v14, v33
	v_add_f32_e32 v34, v22, v34
	v_add_f32_e32 v35, v30, v35
	v_add_f32_e32 v32, v7, v32
	v_add_f32_e32 v33, v15, v33
	v_add_f32_e32 v34, v23, v34
	v_add_f32_e32 v35, v31, v35
	ds_bpermute_b32 v36, v40, v32
	ds_bpermute_b32 v37, v40, v33
	ds_bpermute_b32 v38, v40, v34
	ds_bpermute_b32 v39, v40, v35
	s_waitcnt lgkmcnt(0)
	v_add_f32_e32 v32, v32, v36
	v_add_f32_e32 v33, v33, v37
	v_add_f32_e32 v34, v34, v38
	v_add_f32_e32 v35, v35, v39
	ds_bpermute_b32 v36, v41, v32
	ds_bpermute_b32 v37, v41, v33
	ds_bpermute_b32 v38, v41, v34
	ds_bpermute_b32 v39, v41, v35
	s_waitcnt lgkmcnt(0)
	v_add_f32_e32 v32, v32, v36
	v_add_f32_e32 v33, v33, v37
	v_add_f32_e32 v34, v34, v38
	v_add_f32_e32 v35, v35, v39
	ds_bpermute_b32 v36, v42, v32
	ds_bpermute_b32 v37, v42, v33
	ds_bpermute_b32 v38, v42, v34
	ds_bpermute_b32 v39, v42, v35
	s_waitcnt lgkmcnt(0)
	v_add_f32_e32 v32, v32, v36
	v_add_f32_e32 v33, v33, v37
	v_add_f32_e32 v34, v34, v38
	v_add_f32_e32 v35, v35, v39
	ds_bpermute_b32 v36, v43, v32
	ds_bpermute_b32 v37, v43, v33
	ds_bpermute_b32 v38, v43, v34
	ds_bpermute_b32 v39, v43, v35
	s_waitcnt lgkmcnt(0)
	v_add_f32_e32 v32, v32, v36
	v_add_f32_e32 v33, v33, v37
	v_add_f32_e32 v34, v34, v38
	v_add_f32_e32 v35, v35, v39
	ds_bpermute_b32 v36, v44, v32
	ds_bpermute_b32 v37, v44, v33
	ds_bpermute_b32 v38, v44, v34
	ds_bpermute_b32 v39, v44, v35
	s_waitcnt lgkmcnt(0)
	v_add_f32_e32 v32, v32, v36
	v_add_f32_e32 v33, v33, v37
	v_add_f32_e32 v34, v34, v38
	v_add_f32_e32 v35, v35, v39
	ds_bpermute_b32 v36, v45, v32
	ds_bpermute_b32 v37, v45, v33
	ds_bpermute_b32 v38, v45, v34
	ds_bpermute_b32 v39, v45, v35
	s_waitcnt lgkmcnt(0)
; __device__ __forceinline__ float sigmoidf_fast(float x) { return __builtin_amdgcn_rcpf(1.0f + __expf(-x)); }
; __device__ __forceinline__ void phase_mixer0(const Params& p, LAS unsigned char* lds) {
;     ...
;                     float s = 0.f;
; #pragma unroll
;                     for (int q = 0; q < 8; ++q) s += x[q];
;                     const float mean = wave_sum(s) * (1.f / 512.f);
;                     float s2 = 0.f;
; #pragma unroll
;                     for (int q = 0; q < 8; ++q) { x[q] -= mean; s2 += x[q] * x[q]; }
;                     const float rstd = __builtin_amdgcn_rsqf(wave_sum(s2) * (1.f / 512.f) + EPS);
; #pragma unroll
;                     for (int q = 0; q < 8; ++q) { const float y = x[q] * rstd * g8[q] + b8[q]; x[q] = y * sigmoidf_fast(y); }
	v_add_f32_e32 v32, v32, v36
	v_add_f32_e32 v33, v33, v37
	v_add_f32_e32 v34, v34, v38
	v_add_f32_e32 v35, v35, v39
	v_fmac_f32_e32 v0, 0xbb000000, v32
	v_fmac_f32_e32 v8, 0xbb000000, v33
	v_fmac_f32_e32 v16, 0xbb000000, v34
	v_fmac_f32_e32 v24, 0xbb000000, v35
	v_fmac_f32_e32 v1, 0xbb000000, v32
	v_fmac_f32_e32 v9, 0xbb000000, v33
	v_fmac_f32_e32 v17, 0xbb000000, v34
	v_fmac_f32_e32 v25, 0xbb000000, v35
	v_fmac_f32_e32 v2, 0xbb000000, v32
	v_fmac_f32_e32 v10, 0xbb000000, v33
	v_fmac_f32_e32 v18, 0xbb000000, v34
	v_fmac_f32_e32 v26, 0xbb000000, v35
	v_fmac_f32_e32 v3, 0xbb000000, v32
	v_fmac_f32_e32 v11, 0xbb000000, v33
	v_fmac_f32_e32 v19, 0xbb000000, v34
	v_fmac_f32_e32 v27, 0xbb000000, v35
	v_fmac_f32_e32 v4, 0xbb000000, v32
	v_fmac_f32_e32 v12, 0xbb000000, v33
	v_fmac_f32_e32 v20, 0xbb000000, v34
	v_fmac_f32_e32 v28, 0xbb000000, v35
	v_fmac_f32_e32 v5, 0xbb000000, v32
	v_fmac_f32_e32 v13, 0xbb000000, v33
	v_fmac_f32_e32 v21, 0xbb000000, v34
	v_fmac_f32_e32 v29, 0xbb000000, v35
	v_fmac_f32_e32 v6, 0xbb000000, v32
	v_fmac_f32_e32 v14, 0xbb000000, v33
	v_fmac_f32_e32 v22, 0xbb000000, v34
	v_fmac_f32_e32 v30, 0xbb000000, v35
	v_fmac_f32_e32 v7, 0xbb000000, v32
	v_fmac_f32_e32 v15, 0xbb000000, v33
	v_fmac_f32_e32 v23, 0xbb000000, v34
	v_fmac_f32_e32 v31, 0xbb000000, v35
	v_mul_f32_e32 v124, v1, v1
	v_mul_f32_e32 v125, v9, v9
	v_mul_f32_e32 v126, v17, v17
	v_mul_f32_e32 v127, v25, v25
	v_fmac_f32_e32 v124, v0, v0
	v_fmac_f32_e32 v125, v8, v8
	v_fmac_f32_e32 v126, v16, v16
	v_fmac_f32_e32 v127, v24, v24
	v_fmac_f32_e32 v124, v2, v2
	v_fmac_f32_e32 v125, v10, v10
	v_fmac_f32_e32 v126, v18, v18
	v_fmac_f32_e32 v127, v26, v26
	v_fmac_f32_e32 v124, v3, v3
	v_fmac_f32_e32 v125, v11, v11
	v_fmac_f32_e32 v126, v19, v19
	v_fmac_f32_e32 v127, v27, v27
	v_fmac_f32_e32 v124, v4, v4
	v_fmac_f32_e32 v125, v12, v12
	v_fmac_f32_e32 v126, v20, v20
	v_fmac_f32_e32 v127, v28, v28
	v_fmac_f32_e32 v124, v5, v5
	v_fmac_f32_e32 v125, v13, v13
	v_fmac_f32_e32 v126, v21, v21
	v_fmac_f32_e32 v127, v29, v29
	v_fmac_f32_e32 v124, v6, v6
	v_fmac_f32_e32 v125, v14, v14
	v_fmac_f32_e32 v126, v22, v22
	v_fmac_f32_e32 v127, v30, v30
	v_fmac_f32_e32 v124, v7, v7
	v_fmac_f32_e32 v125, v15, v15
	v_fmac_f32_e32 v126, v23, v23
	v_fmac_f32_e32 v127, v31, v31
	ds_bpermute_b32 v36, v40, v124
	ds_bpermute_b32 v37, v40, v125
	ds_bpermute_b32 v38, v40, v126
	ds_bpermute_b32 v39, v40, v127
	s_waitcnt lgkmcnt(0)
	v_add_f32_e32 v124, v124, v36
	v_add_f32_e32 v125, v125, v37
	v_add_f32_e32 v126, v126, v38
	v_add_f32_e32 v127, v127, v39
	ds_bpermute_b32 v36, v41, v124
	ds_bpermute_b32 v37, v41, v125
	ds_bpermute_b32 v38, v41, v126
	ds_bpermute_b32 v39, v41, v127
	s_waitcnt lgkmcnt(0)
	v_add_f32_e32 v124, v124, v36
	v_add_f32_e32 v125, v125, v37
	v_add_f32_e32 v126, v126, v38
	v_add_f32_e32 v127, v127, v39
	ds_bpermute_b32 v36, v42, v124
	ds_bpermute_b32 v37, v42, v125
	ds_bpermute_b32 v38, v42, v126
	ds_bpermute_b32 v39, v42, v127
	s_waitcnt lgkmcnt(0)
	v_add_f32_e32 v124, v124, v36
	v_add_f32_e32 v125, v125, v37
	v_add_f32_e32 v126, v126, v38
	v_add_f32_e32 v127, v127, v39
	ds_bpermute_b32 v36, v43, v124
	ds_bpermute_b32 v37, v43, v125
	ds_bpermute_b32 v38, v43, v126
	ds_bpermute_b32 v39, v43, v127
	s_waitcnt lgkmcnt(0)
	v_add_f32_e32 v124, v124, v36
	v_add_f32_e32 v125, v125, v37
	v_add_f32_e32 v126, v126, v38
	v_add_f32_e32 v127, v127, v39
	ds_bpermute_b32 v36, v44, v124
	ds_bpermute_b32 v37, v44, v125
	ds_bpermute_b32 v38, v44, v126
	ds_bpermute_b32 v39, v44, v127
	s_waitcnt lgkmcnt(0)
	v_add_f32_e32 v124, v124, v36
	v_add_f32_e32 v125, v125, v37
	v_add_f32_e32 v126, v126, v38
	v_add_f32_e32 v127, v127, v39
	ds_bpermute_b32 v36, v45, v124
	ds_bpermute_b32 v37, v45, v125
	ds_bpermute_b32 v38, v45, v126
	ds_bpermute_b32 v39, v45, v127
	s_waitcnt lgkmcnt(0)
	v_add_f32_e32 v124, v124, v36
	v_add_f32_e32 v125, v125, v37
	v_add_f32_e32 v126, v126, v38
	v_add_f32_e32 v127, v127, v39
	v_fmamk_f32 v124, v124, 0x3b000000, v120
	v_fmamk_f32 v125, v125, 0x3b000000, v120
	v_fmamk_f32 v126, v126, 0x3b000000, v120
	v_fmamk_f32 v127, v127, 0x3b000000, v120
	v_rsq_f32_e32 v124, v124
	v_rsq_f32_e32 v125, v125
	v_rsq_f32_e32 v126, v126
	v_rsq_f32_e32 v127, v127
	v_mul_f32_e32 v0, v0, v124
	v_mul_f32_e32 v8, v8, v125
	v_mul_f32_e32 v16, v16, v126
	v_mul_f32_e32 v24, v24, v127
	v_mul_f32_e32 v1, v1, v124
	v_mul_f32_e32 v9, v9, v125
	v_mul_f32_e32 v17, v17, v126
	v_mul_f32_e32 v25, v25, v127
	v_mul_f32_e32 v2, v2, v124
	v_mul_f32_e32 v10, v10, v125
	v_mul_f32_e32 v18, v18, v126
	v_mul_f32_e32 v26, v26, v127
	v_mul_f32_e32 v3, v3, v124
	v_mul_f32_e32 v11, v11, v125
	v_mul_f32_e32 v19, v19, v126
	v_mul_f32_e32 v27, v27, v127
	v_mul_f32_e32 v4, v4, v124
	v_mul_f32_e32 v12, v12, v125
	v_mul_f32_e32 v20, v20, v126
	v_mul_f32_e32 v28, v28, v127
	v_mul_f32_e32 v5, v5, v124
	v_mul_f32_e32 v13, v13, v125
	v_mul_f32_e32 v21, v21, v126
	v_mul_f32_e32 v29, v29, v127
	v_mul_f32_e32 v6, v6, v124
	v_mul_f32_e32 v14, v14, v125
	v_mul_f32_e32 v22, v22, v126
	v_mul_f32_e32 v30, v30, v127
	v_mul_f32_e32 v7, v7, v124
	v_mul_f32_e32 v15, v15, v125
	v_mul_f32_e32 v23, v23, v126
	v_mul_f32_e32 v31, v31, v127
	v_fma_f32 v0, v142, v0, v150
	v_fma_f32 v8, v142, v8, v150
	v_fma_f32 v16, v142, v16, v150
	v_fma_f32 v24, v142, v24, v150
	v_fma_f32 v1, v143, v1, v151
	v_fma_f32 v9, v143, v9, v151
	v_fma_f32 v17, v143, v17, v151
	v_fma_f32 v25, v143, v25, v151
	v_fma_f32 v2, v144, v2, v152
	v_fma_f32 v10, v144, v10, v152
	v_fma_f32 v18, v144, v18, v152
	v_fma_f32 v26, v144, v26, v152
	v_fma_f32 v3, v145, v3, v153
	v_fma_f32 v11, v145, v11, v153
	v_fma_f32 v19, v145, v19, v153
	v_fma_f32 v27, v145, v27, v153
	v_fma_f32 v4, v146, v4, v154
; __device__ __forceinline__ v4u pack8(const float (&f)[8]) { v4u w; w.x = pk2(f[0], f[1]); w.y = pk2(f[2], f[3]); w.z = pk2(f[4], f[5]); w.w = pk2(f[6], f[7]); return w; }
; __device__ __forceinline__ float sigmoidf_fast(float x) { return __builtin_amdgcn_rcpf(1.0f + __expf(-x)); }
; __device__ __forceinline__ void phase_mixer0(const Params& p, LAS unsigned char* lds) {
;     ...
;                     for (int q = 0; q < 8; ++q) { const float y = x[q] * rstd * g8[q] + b8[q]; x[q] = y * sigmoidf_fast(y); }
;                     *(v4u*)(Y + (size_t)(rowbase + t) * D + 512 + c8) = pack8(x);
;     ...
;             for (int h = 0; h < 2; ++h) {
;                 const int tt = t0 + wave * 4 - 2 + h; float u[8];
;                 if (tt >= 0) unpack8(*(const v4u*)(Z + (rowbase + (tt - t0)) * NZ1 + 512 + c8), u);
;                 else if (samp) load8f(st_a + ((size_t)seq * 2 + (2 + tt)) * 512 + c8, u);
;                 else {
; #pragma unroll
;                     for (int q = 0; q < 8; ++q) u[q] = 0.f; }
	v_fma_f32 v12, v146, v12, v154
	v_fma_f32 v20, v146, v20, v154
	v_fma_f32 v28, v146, v28, v154
	v_fma_f32 v5, v147, v5, v155
	v_fma_f32 v13, v147, v13, v155
	v_fma_f32 v21, v147, v21, v155
	v_fma_f32 v29, v147, v29, v155
	v_fma_f32 v6, v148, v6, v156
	v_fma_f32 v14, v148, v14, v156
	v_fma_f32 v22, v148, v22, v156
	v_fma_f32 v30, v148, v30, v156
	v_fma_f32 v7, v149, v7, v157
	v_fma_f32 v15, v149, v15, v157
	v_fma_f32 v23, v149, v23, v157
	v_fma_f32 v31, v149, v31, v157
	v_mul_f32_e32 v128, 0xbfb8aa3b, v0
	v_mul_f32_e32 v129, 0xbfb8aa3b, v1
	v_mul_f32_e32 v130, 0xbfb8aa3b, v2
	v_mul_f32_e32 v131, 0xbfb8aa3b, v3
	v_mul_f32_e32 v132, 0xbfb8aa3b, v4
	v_mul_f32_e32 v133, 0xbfb8aa3b, v5
	v_mul_f32_e32 v134, 0xbfb8aa3b, v6
	v_mul_f32_e32 v135, 0xbfb8aa3b, v7
	v_exp_f32_e32 v128, v128
	v_exp_f32_e32 v129, v129
	v_exp_f32_e32 v130, v130
	v_exp_f32_e32 v131, v131
	v_exp_f32_e32 v132, v132
	v_exp_f32_e32 v133, v133
	v_exp_f32_e32 v134, v134
	v_exp_f32_e32 v135, v135
	v_add_f32_e32 v128, 1.0, v128
	v_add_f32_e32 v129, 1.0, v129
	v_add_f32_e32 v130, 1.0, v130
	v_add_f32_e32 v131, 1.0, v131
	v_add_f32_e32 v132, 1.0, v132
	v_add_f32_e32 v133, 1.0, v133
	v_add_f32_e32 v134, 1.0, v134
	v_add_f32_e32 v135, 1.0, v135
	v_rcp_f32_e32 v128, v128
	v_rcp_f32_e32 v129, v129
	v_rcp_f32_e32 v130, v130
	v_rcp_f32_e32 v131, v131
	v_rcp_f32_e32 v132, v132
	v_rcp_f32_e32 v133, v133
	v_rcp_f32_e32 v134, v134
	v_rcp_f32_e32 v135, v135
	v_mul_f32_e32 v0, v0, v128
	v_mul_f32_e32 v1, v1, v129
	v_mul_f32_e32 v2, v2, v130
	v_mul_f32_e32 v3, v3, v131
	v_mul_f32_e32 v4, v4, v132
	v_mul_f32_e32 v5, v5, v133
	v_mul_f32_e32 v6, v6, v134
	v_mul_f32_e32 v7, v7, v135
	v_cvt_pk_bf16_f32 v222, v0, v1
	v_cvt_pk_bf16_f32 v223, v2, v3
	v_cvt_pk_bf16_f32 v224, v4, v5
	v_cvt_pk_bf16_f32 v225, v6, v7
	s_add_u32 s6, s0, 0
	s_addc_u32 s7, s1, 0
	s_lshl_b64 s[6:7], s[6:7], 11
	v_lshl_add_u64 v[48:49], v[66:67], 0, s[6:7]
	global_store_dwordx4 v[48:49], v[222:225], off offset:1024
	v_mul_f32_e32 v128, 0xbfb8aa3b, v8
	v_mul_f32_e32 v129, 0xbfb8aa3b, v9
	v_mul_f32_e32 v130, 0xbfb8aa3b, v10
	v_mul_f32_e32 v131, 0xbfb8aa3b, v11
	v_mul_f32_e32 v132, 0xbfb8aa3b, v12
	v_mul_f32_e32 v133, 0xbfb8aa3b, v13
	v_mul_f32_e32 v134, 0xbfb8aa3b, v14
	v_mul_f32_e32 v135, 0xbfb8aa3b, v15
	v_exp_f32_e32 v128, v128
	v_exp_f32_e32 v129, v129
	v_exp_f32_e32 v130, v130
	v_exp_f32_e32 v131, v131
	v_exp_f32_e32 v132, v132
	v_exp_f32_e32 v133, v133
	v_exp_f32_e32 v134, v134
	v_exp_f32_e32 v135, v135
	v_add_f32_e32 v128, 1.0, v128
	v_add_f32_e32 v129, 1.0, v129
	v_add_f32_e32 v130, 1.0, v130
	v_add_f32_e32 v131, 1.0, v131
	v_add_f32_e32 v132, 1.0, v132
	v_add_f32_e32 v133, 1.0, v133
	v_add_f32_e32 v134, 1.0, v134
	v_add_f32_e32 v135, 1.0, v135
	v_rcp_f32_e32 v128, v128
	v_rcp_f32_e32 v129, v129
	v_rcp_f32_e32 v130, v130
	v_rcp_f32_e32 v131, v131
	v_rcp_f32_e32 v132, v132
	v_rcp_f32_e32 v133, v133
	v_rcp_f32_e32 v134, v134
	v_rcp_f32_e32 v135, v135
	v_mul_f32_e32 v8, v8, v128
	v_mul_f32_e32 v9, v9, v129
	v_mul_f32_e32 v10, v10, v130
	v_mul_f32_e32 v11, v11, v131
	v_mul_f32_e32 v12, v12, v132
	v_mul_f32_e32 v13, v13, v133
	v_mul_f32_e32 v14, v14, v134
	v_mul_f32_e32 v15, v15, v135
	v_cvt_pk_bf16_f32 v226, v8, v9
	v_cvt_pk_bf16_f32 v227, v10, v11
	v_cvt_pk_bf16_f32 v228, v12, v13
	v_cvt_pk_bf16_f32 v229, v14, v15
	s_add_u32 s6, s0, 1
	s_addc_u32 s7, s1, 0
	s_lshl_b64 s[6:7], s[6:7], 11
	v_lshl_add_u64 v[48:49], v[66:67], 0, s[6:7]
	global_store_dwordx4 v[48:49], v[226:229], off offset:1024
	v_mul_f32_e32 v128, 0xbfb8aa3b, v16
	v_mul_f32_e32 v129, 0xbfb8aa3b, v17
	v_mul_f32_e32 v130, 0xbfb8aa3b, v18
	v_mul_f32_e32 v131, 0xbfb8aa3b, v19
	v_mul_f32_e32 v132, 0xbfb8aa3b, v20
	v_mul_f32_e32 v133, 0xbfb8aa3b, v21
	v_mul_f32_e32 v134, 0xbfb8aa3b, v22
	v_mul_f32_e32 v135, 0xbfb8aa3b, v23
	v_exp_f32_e32 v128, v128
	v_exp_f32_e32 v129, v129
	v_exp_f32_e32 v130, v130
	v_exp_f32_e32 v131, v131
	v_exp_f32_e32 v132, v132
	v_exp_f32_e32 v133, v133
	v_exp_f32_e32 v134, v134
	v_exp_f32_e32 v135, v135
	v_add_f32_e32 v128, 1.0, v128
	v_add_f32_e32 v129, 1.0, v129
	v_add_f32_e32 v130, 1.0, v130
	v_add_f32_e32 v131, 1.0, v131
	v_add_f32_e32 v132, 1.0, v132
	v_add_f32_e32 v133, 1.0, v133
	v_add_f32_e32 v134, 1.0, v134
	v_add_f32_e32 v135, 1.0, v135
	v_rcp_f32_e32 v128, v128
	v_rcp_f32_e32 v129, v129
	v_rcp_f32_e32 v130, v130
	v_rcp_f32_e32 v131, v131
	v_rcp_f32_e32 v132, v132
	v_rcp_f32_e32 v133, v133
	v_rcp_f32_e32 v134, v134
	v_rcp_f32_e32 v135, v135
	v_mul_f32_e32 v16, v16, v128
	v_mul_f32_e32 v17, v17, v129
	v_mul_f32_e32 v18, v18, v130
	v_mul_f32_e32 v19, v19, v131
	v_mul_f32_e32 v20, v20, v132
	v_mul_f32_e32 v21, v21, v133
	v_mul_f32_e32 v22, v22, v134
	v_mul_f32_e32 v23, v23, v135
	v_cvt_pk_bf16_f32 v230, v16, v17
	v_cvt_pk_bf16_f32 v231, v18, v19
	v_cvt_pk_bf16_f32 v232, v20, v21
	v_cvt_pk_bf16_f32 v233, v22, v23
	s_add_u32 s6, s0, 2
	s_addc_u32 s7, s1, 0
	s_lshl_b64 s[6:7], s[6:7], 11
	v_lshl_add_u64 v[48:49], v[66:67], 0, s[6:7]
	global_store_dwordx4 v[48:49], v[230:233], off offset:1024
	v_mul_f32_e32 v128, 0xbfb8aa3b, v24
	v_mul_f32_e32 v129, 0xbfb8aa3b, v25
	v_mul_f32_e32 v130, 0xbfb8aa3b, v26
	v_mul_f32_e32 v131, 0xbfb8aa3b, v27
	v_mul_f32_e32 v132, 0xbfb8aa3b, v28
	v_mul_f32_e32 v133, 0xbfb8aa3b, v29
	v_mul_f32_e32 v134, 0xbfb8aa3b, v30
	v_mul_f32_e32 v135, 0xbfb8aa3b, v31
	v_exp_f32_e32 v128, v128
	v_exp_f32_e32 v129, v129
	v_exp_f32_e32 v130, v130
	v_exp_f32_e32 v131, v131
	v_exp_f32_e32 v132, v132
	v_exp_f32_e32 v133, v133
	v_exp_f32_e32 v134, v134
	v_exp_f32_e32 v135, v135
	v_add_f32_e32 v128, 1.0, v128
	v_add_f32_e32 v129, 1.0, v129
	v_add_f32_e32 v130, 1.0, v130
	v_add_f32_e32 v131, 1.0, v131
	v_add_f32_e32 v132, 1.0, v132
	v_add_f32_e32 v133, 1.0, v133
	v_add_f32_e32 v134, 1.0, v134
	v_add_f32_e32 v135, 1.0, v135
	v_rcp_f32_e32 v128, v128
	v_rcp_f32_e32 v129, v129
	v_rcp_f32_e32 v130, v130
	v_rcp_f32_e32 v131, v131
	v_rcp_f32_e32 v132, v132
	v_rcp_f32_e32 v133, v133
	v_rcp_f32_e32 v134, v134
	v_rcp_f32_e32 v135, v135
	v_mul_f32_e32 v24, v24, v128
	v_mul_f32_e32 v25, v25, v129
	v_mul_f32_e32 v26, v26, v130
	v_mul_f32_e32 v27, v27, v131
	v_mul_f32_e32 v28, v28, v132
	v_mul_f32_e32 v29, v29, v133
	v_mul_f32_e32 v30, v30, v134
	v_mul_f32_e32 v31, v31, v135
	v_cvt_pk_bf16_f32 v234, v24, v25
	v_cvt_pk_bf16_f32 v235, v26, v27
	v_cvt_pk_bf16_f32 v236, v28, v29
	v_cvt_pk_bf16_f32 v237, v30, v31
	s_add_u32 s6, s0, 3
	s_addc_u32 s7, s1, 0
	s_lshl_b64 s[6:7], s[6:7], 11
	v_lshl_add_u64 v[48:49], v[66:67], 0, s[6:7]
	global_store_dwordx4 v[48:49], v[234:237], off offset:1024
	s_cmp_lt_i32 s80, 2
	s_cbranch_scc0 .Lmx0_hist_ok
	s_cmpk_gt_i32 s8, 0x1ff
	s_cbranch_scc0 .Lmx0_hist_zero
	s_add_i32 s6, s8, 0xfffffe00
	s_lshl_b32 s6, s6, 12
	s_mov_b32 s7, 0
	v_lshl_add_u64 v[48:49], v[64:65], 0, s[6:7]
	global_load_dwordx4 v[124:127], v[48:49], off
	global_load_dwordx4 v[128:131], v[48:49], off offset:16
	global_load_dwordx4 v[132:135], v[48:49], off offset:2048
	global_load_dwordx4 v[136:139], v[48:49], off offset:2064
	s_waitcnt vmcnt(0)
	s_branch .Lmx0_hist_done
; __device__ __forceinline__ v4u pack8(const float (&f)[8]) { v4u w; w.x = pk2(f[0], f[1]); w.y = pk2(f[2], f[3]); w.z = pk2(f[4], f[5]); w.w = pk2(f[6], f[7]); return w; }
; __device__ __forceinline__ void phase_mixer0(const Params& p, LAS unsigned char* lds) {
;     ...
;             for (int h = 0; h < 2; ++h) {
;                 const int tt = t0 + wave * 4 - 2 + h; float u[8];
;                 if (tt >= 0) unpack8(*(const v4u*)(Z + (rowbase + (tt - t0)) * NZ1 + 512 + c8), u);
;                 else if (samp) load8f(st_a + ((size_t)seq * 2 + (2 + tt)) * 512 + c8, u);
;                 else {
; #pragma unroll
;                     for (int q = 0; q < 8; ++q) u[q] = 0.f; }
; #pragma unroll
;                 for (int q = 0; q < 8; ++q) { if (h == 0) um2[q] = u[q]; else um1[q] = u[q]; }
;             }
; #pragma unroll
;             for (int i = 0; i < 4; ++i) {
;                 const int t = wave * 4 + i; const bf16* zr = Z + (rowbase + t) * NZ1;
;                 float gbv[8], u0[8], y[8]; unpack8(*(const v4u*)(zr + c8), gbv); unpack8(*(const v4u*)(zr + 512 + c8), u0);
; #pragma unroll
;                 for (int q = 0; q < 8; ++q) y[q] = gbv[q] * (w0[q] * um2[q] + w1[q] * um1[q] + w2[q] * u0[q]);
;                 *(v4u*)(Y + (size_t)(rowbase + t) * D + c8) = pack8(y);
;                 const int tt = t0 + t;
;                 if (!samp) { if (tt >= SEQ - 2) store8f(o_ca_p + ((size_t)seq * 2 + (tt - (SEQ - 2))) * 512 + c8, u0); }
;                 else if (t >= 6) store8f(o_ca_s + ((size_t)seq * 2 + (t - 6)) * 512 + c8, u0);
; #pragma unroll
;                 for (int q = 0; q < 8; ++q) { um2[q] = um1[q]; um1[q] = u0[q]; }
;             }
.Lmx0_hist_zero:
	v_mov_b32_e32 v124, 0
	v_mov_b32_e32 v125, 0
	v_mov_b32_e32 v126, 0
	v_mov_b32_e32 v127, 0
	v_mov_b32_e32 v128, 0
	v_mov_b32_e32 v129, 0
	v_mov_b32_e32 v130, 0
	v_mov_b32_e32 v131, 0
	v_mov_b32_e32 v132, 0
	v_mov_b32_e32 v133, 0
	v_mov_b32_e32 v134, 0
	v_mov_b32_e32 v135, 0
	v_mov_b32_e32 v136, 0
	v_mov_b32_e32 v137, 0
	v_mov_b32_e32 v138, 0
	v_mov_b32_e32 v139, 0
	s_branch .Lmx0_hist_done
.Lmx0_hist_ok:
	v_lshlrev_b32_e32 v124, 16, v182
	v_and_b32_e32 v125, 0xffff0000, v182
	v_lshlrev_b32_e32 v126, 16, v183
	v_and_b32_e32 v127, 0xffff0000, v183
	v_lshlrev_b32_e32 v128, 16, v184
	v_and_b32_e32 v129, 0xffff0000, v184
	v_lshlrev_b32_e32 v130, 16, v185
	v_and_b32_e32 v131, 0xffff0000, v185
	v_lshlrev_b32_e32 v132, 16, v186
	v_and_b32_e32 v133, 0xffff0000, v186
	v_lshlrev_b32_e32 v134, 16, v187
	v_and_b32_e32 v135, 0xffff0000, v187
	v_lshlrev_b32_e32 v136, 16, v188
	v_and_b32_e32 v137, 0xffff0000, v188
	v_lshlrev_b32_e32 v138, 16, v189
	v_and_b32_e32 v139, 0xffff0000, v189
.Lmx0_hist_done:
	v_lshlrev_b32_e32 v0, 16, v190
	v_and_b32_e32 v1, 0xffff0000, v190
	v_lshlrev_b32_e32 v2, 16, v191
	v_and_b32_e32 v3, 0xffff0000, v191
	v_lshlrev_b32_e32 v4, 16, v192
	v_and_b32_e32 v5, 0xffff0000, v192
	v_lshlrev_b32_e32 v6, 16, v193
	v_and_b32_e32 v7, 0xffff0000, v193
	v_lshlrev_b32_e32 v8, 16, v206
	v_and_b32_e32 v9, 0xffff0000, v206
	v_lshlrev_b32_e32 v10, 16, v207
	v_and_b32_e32 v11, 0xffff0000, v207
	v_lshlrev_b32_e32 v12, 16, v208
	v_and_b32_e32 v13, 0xffff0000, v208
	v_lshlrev_b32_e32 v14, 16, v209
	v_and_b32_e32 v15, 0xffff0000, v209
	v_mul_f32_e32 v16, v158, v124
	v_mul_f32_e32 v17, v159, v125
	v_mul_f32_e32 v18, v160, v126
	v_mul_f32_e32 v19, v161, v127
	v_mul_f32_e32 v20, v162, v128
	v_mul_f32_e32 v21, v163, v129
	v_mul_f32_e32 v22, v164, v130
	v_mul_f32_e32 v23, v165, v131
	v_fmac_f32_e32 v16, v166, v132
	v_fmac_f32_e32 v17, v167, v133
	v_fmac_f32_e32 v18, v168, v134
	v_fmac_f32_e32 v19, v169, v135
	v_fmac_f32_e32 v20, v170, v136
	v_fmac_f32_e32 v21, v171, v137
	v_fmac_f32_e32 v22, v172, v138
	v_fmac_f32_e32 v23, v173, v139
	v_fmac_f32_e32 v16, v174, v0
	v_fmac_f32_e32 v17, v175, v1
	v_fmac_f32_e32 v18, v176, v2
	v_fmac_f32_e32 v19, v177, v3
	v_fmac_f32_e32 v20, v178, v4
	v_fmac_f32_e32 v21, v179, v5
	v_fmac_f32_e32 v22, v180, v6
	v_fmac_f32_e32 v23, v181, v7
	v_mul_f32_e32 v16, v8, v16
	v_mul_f32_e32 v17, v9, v17
	v_mul_f32_e32 v18, v10, v18
	v_mul_f32_e32 v19, v11, v19
	v_mul_f32_e32 v20, v12, v20
	v_mul_f32_e32 v21, v13, v21
	v_mul_f32_e32 v22, v14, v22
	v_mul_f32_e32 v23, v15, v23
	v_cvt_pk_bf16_f32 v24, v16, v17
	v_cvt_pk_bf16_f32 v25, v18, v19
	v_cvt_pk_bf16_f32 v26, v20, v21
	v_cvt_pk_bf16_f32 v27, v22, v23
	s_add_u32 s6, s0, 0
	s_addc_u32 s7, s1, 0
	s_lshl_b64 s[6:7], s[6:7], 11
	v_lshl_add_u64 v[48:49], v[66:67], 0, s[6:7]
	global_store_dwordx4 v[48:49], v[24:27], off
	s_cmpk_gt_i32 s8, 0x1ff
	s_cbranch_scc1 .Lmx0_st_s0
	s_add_i32 s9, s80, 0
	s_cmpk_lt_i32 s9, 0x7fe
	s_cbranch_scc1 .Lmx0_st_n0
	s_lshl_b32 s6, s76, 1
	s_add_i32 s6, s6, s9
	s_sub_i32 s6, s6, 0x7fe
	s_lshl_b32 s6, s6, 11
	s_mov_b32 s7, 0
	v_lshl_add_u64 v[50:51], v[70:71], 0, s[6:7]
	s_branch .Lmx0_st_w0
.Lmx0_st_s0:
	s_add_i32 s9, s82, 0
	s_cmp_lt_i32 s9, 6
	s_cbranch_scc1 .Lmx0_st_n0
	s_add_i32 s6, s8, 0xfffffe00
	s_lshl_b32 s6, s6, 1
	s_add_i32 s6, s6, s9
	s_sub_i32 s6, s6, 6
	s_lshl_b32 s6, s6, 11
	s_mov_b32 s7, 0
	v_lshl_add_u64 v[50:51], v[72:73], 0, s[6:7]
.Lmx0_st_w0:
	global_store_dwordx4 v[50:51], v[0:3], off
	global_store_dwordx4 v[50:51], v[4:7], off offset:16
.Lmx0_st_n0:
	v_lshlrev_b32_e32 v124, 16, v194
	v_and_b32_e32 v125, 0xffff0000, v194
	v_lshlrev_b32_e32 v126, 16, v195
	v_and_b32_e32 v127, 0xffff0000, v195
	v_lshlrev_b32_e32 v128, 16, v196
	v_and_b32_e32 v129, 0xffff0000, v196
	v_lshlrev_b32_e32 v130, 16, v197
	v_and_b32_e32 v131, 0xffff0000, v197
	v_lshlrev_b32_e32 v8, 16, v210
	v_and_b32_e32 v9, 0xffff0000, v210
	v_lshlrev_b32_e32 v10, 16, v211
	v_and_b32_e32 v11, 0xffff0000, v211
	v_lshlrev_b32_e32 v12, 16, v212
	v_and_b32_e32 v13, 0xffff0000, v212
	v_lshlrev_b32_e32 v14, 16, v213
	v_and_b32_e32 v15, 0xffff0000, v213
	v_mul_f32_e32 v16, v158, v132
	v_mul_f32_e32 v17, v159, v133
	v_mul_f32_e32 v18, v160, v134
	v_mul_f32_e32 v19, v161, v135
	v_mul_f32_e32 v20, v162, v136
	v_mul_f32_e32 v21, v163, v137
	v_mul_f32_e32 v22, v164, v138
	v_mul_f32_e32 v23, v165, v139
	v_fmac_f32_e32 v16, v166, v0
	v_fmac_f32_e32 v17, v167, v1
	v_fmac_f32_e32 v18, v168, v2
	v_fmac_f32_e32 v19, v169, v3
	v_fmac_f32_e32 v20, v170, v4
	v_fmac_f32_e32 v21, v171, v5
	v_fmac_f32_e32 v22, v172, v6
	v_fmac_f32_e32 v23, v173, v7
	v_fmac_f32_e32 v16, v174, v124
	v_fmac_f32_e32 v17, v175, v125
	v_fmac_f32_e32 v18, v176, v126
	v_fmac_f32_e32 v19, v177, v127
	v_fmac_f32_e32 v20, v178, v128
	v_fmac_f32_e32 v21, v179, v129
	v_fmac_f32_e32 v22, v180, v130
	v_fmac_f32_e32 v23, v181, v131
	v_mul_f32_e32 v16, v8, v16
	v_mul_f32_e32 v17, v9, v17
	v_mul_f32_e32 v18, v10, v18
	v_mul_f32_e32 v19, v11, v19
	v_mul_f32_e32 v20, v12, v20
	v_mul_f32_e32 v21, v13, v21
	v_mul_f32_e32 v22, v14, v22
	v_mul_f32_e32 v23, v15, v23
	v_cvt_pk_bf16_f32 v28, v16, v17
	v_cvt_pk_bf16_f32 v29, v18, v19
	v_cvt_pk_bf16_f32 v30, v20, v21
	v_cvt_pk_bf16_f32 v31, v22, v23
	s_add_u32 s6, s0, 1
	s_addc_u32 s7, s1, 0
	s_lshl_b64 s[6:7], s[6:7], 11
	v_lshl_add_u64 v[48:49], v[66:67], 0, s[6:7]
	global_store_dwordx4 v[48:49], v[28:31], off
	s_cmpk_gt_i32 s8, 0x1ff
	s_cbranch_scc1 .Lmx0_st_s1
	s_add_i32 s9, s80, 1
	s_cmpk_lt_i32 s9, 0x7fe
	s_cbranch_scc1 .Lmx0_st_n1
	s_lshl_b32 s6, s76, 1
	s_add_i32 s6, s6, s9
	s_sub_i32 s6, s6, 0x7fe
	s_lshl_b32 s6, s6, 11
	s_mov_b32 s7, 0
	v_lshl_add_u64 v[50:51], v[70:71], 0, s[6:7]
	s_branch .Lmx0_st_w1
; __device__ __forceinline__ v4u pack8(const float (&f)[8]) { v4u w; w.x = pk2(f[0], f[1]); w.y = pk2(f[2], f[3]); w.z = pk2(f[4], f[5]); w.w = pk2(f[6], f[7]); return w; }
; __device__ __forceinline__ void phase_mixer0(const Params& p, LAS unsigned char* lds) {
;     ...
;             for (int i = 0; i < 4; ++i) {
;                 const int t = wave * 4 + i; const bf16* zr = Z + (rowbase + t) * NZ1;
;                 float gbv[8], u0[8], y[8]; unpack8(*(const v4u*)(zr + c8), gbv); unpack8(*(const v4u*)(zr + 512 + c8), u0);
; #pragma unroll
;                 for (int q = 0; q < 8; ++q) y[q] = gbv[q] * (w0[q] * um2[q] + w1[q] * um1[q] + w2[q] * u0[q]);
;                 *(v4u*)(Y + (size_t)(rowbase + t) * D + c8) = pack8(y);
;                 const int tt = t0 + t;
;                 if (!samp) { if (tt >= SEQ - 2) store8f(o_ca_p + ((size_t)seq * 2 + (tt - (SEQ - 2))) * 512 + c8, u0); }
;                 else if (t >= 6) store8f(o_ca_s + ((size_t)seq * 2 + (t - 6)) * 512 + c8, u0);
; #pragma unroll
;                 for (int q = 0; q < 8; ++q) { um2[q] = um1[q]; um1[q] = u0[q]; }
;             }
.Lmx0_st_s1:
	s_add_i32 s9, s82, 1
	s_cmp_lt_i32 s9, 6
	s_cbranch_scc1 .Lmx0_st_n1
	s_add_i32 s6, s8, 0xfffffe00
	s_lshl_b32 s6, s6, 1
	s_add_i32 s6, s6, s9
	s_sub_i32 s6, s6, 6
	s_lshl_b32 s6, s6, 11
	s_mov_b32 s7, 0
	v_lshl_add_u64 v[50:51], v[72:73], 0, s[6:7]
.Lmx0_st_w1:
	global_store_dwordx4 v[50:51], v[124:127], off
	global_store_dwordx4 v[50:51], v[128:131], off offset:16
.Lmx0_st_n1:
	v_lshlrev_b32_e32 v132, 16, v198
	v_and_b32_e32 v133, 0xffff0000, v198
	v_lshlrev_b32_e32 v134, 16, v199
	v_and_b32_e32 v135, 0xffff0000, v199
	v_lshlrev_b32_e32 v136, 16, v200
	v_and_b32_e32 v137, 0xffff0000, v200
	v_lshlrev_b32_e32 v138, 16, v201
	v_and_b32_e32 v139, 0xffff0000, v201
	v_lshlrev_b32_e32 v8, 16, v214
	v_and_b32_e32 v9, 0xffff0000, v214
	v_lshlrev_b32_e32 v10, 16, v215
	v_and_b32_e32 v11, 0xffff0000, v215
	v_lshlrev_b32_e32 v12, 16, v216
	v_and_b32_e32 v13, 0xffff0000, v216
	v_lshlrev_b32_e32 v14, 16, v217
	v_and_b32_e32 v15, 0xffff0000, v217
	v_mul_f32_e32 v16, v158, v0
	v_mul_f32_e32 v17, v159, v1
	v_mul_f32_e32 v18, v160, v2
	v_mul_f32_e32 v19, v161, v3
	v_mul_f32_e32 v20, v162, v4
	v_mul_f32_e32 v21, v163, v5
	v_mul_f32_e32 v22, v164, v6
	v_mul_f32_e32 v23, v165, v7
	v_fmac_f32_e32 v16, v166, v124
	v_fmac_f32_e32 v17, v167, v125
	v_fmac_f32_e32 v18, v168, v126
	v_fmac_f32_e32 v19, v169, v127
	v_fmac_f32_e32 v20, v170, v128
	v_fmac_f32_e32 v21, v171, v129
	v_fmac_f32_e32 v22, v172, v130
	v_fmac_f32_e32 v23, v173, v131
	v_fmac_f32_e32 v16, v174, v132
	v_fmac_f32_e32 v17, v175, v133
	v_fmac_f32_e32 v18, v176, v134
	v_fmac_f32_e32 v19, v177, v135
	v_fmac_f32_e32 v20, v178, v136
	v_fmac_f32_e32 v21, v179, v137
	v_fmac_f32_e32 v22, v180, v138
	v_fmac_f32_e32 v23, v181, v139
	v_mul_f32_e32 v16, v8, v16
	v_mul_f32_e32 v17, v9, v17
	v_mul_f32_e32 v18, v10, v18
	v_mul_f32_e32 v19, v11, v19
	v_mul_f32_e32 v20, v12, v20
	v_mul_f32_e32 v21, v13, v21
	v_mul_f32_e32 v22, v14, v22
	v_mul_f32_e32 v23, v15, v23
	v_cvt_pk_bf16_f32 v32, v16, v17
	v_cvt_pk_bf16_f32 v33, v18, v19
	v_cvt_pk_bf16_f32 v34, v20, v21
	v_cvt_pk_bf16_f32 v35, v22, v23
	s_add_u32 s6, s0, 2
	s_addc_u32 s7, s1, 0
	s_lshl_b64 s[6:7], s[6:7], 11
	v_lshl_add_u64 v[48:49], v[66:67], 0, s[6:7]
	global_store_dwordx4 v[48:49], v[32:35], off
	s_cmpk_gt_i32 s8, 0x1ff
	s_cbranch_scc1 .Lmx0_st_s2
	s_add_i32 s9, s80, 2
	s_cmpk_lt_i32 s9, 0x7fe
	s_cbranch_scc1 .Lmx0_st_n2
	s_lshl_b32 s6, s76, 1
	s_add_i32 s6, s6, s9
	s_sub_i32 s6, s6, 0x7fe
	s_lshl_b32 s6, s6, 11
	s_mov_b32 s7, 0
	v_lshl_add_u64 v[50:51], v[70:71], 0, s[6:7]
	s_branch .Lmx0_st_w2
.Lmx0_st_s2:
	s_add_i32 s9, s82, 2
	s_cmp_lt_i32 s9, 6
	s_cbranch_scc1 .Lmx0_st_n2
	s_add_i32 s6, s8, 0xfffffe00
	s_lshl_b32 s6, s6, 1
	s_add_i32 s6, s6, s9
	s_sub_i32 s6, s6, 6
	s_lshl_b32 s6, s6, 11
	s_mov_b32 s7, 0
	v_lshl_add_u64 v[50:51], v[72:73], 0, s[6:7]
.Lmx0_st_w2:
	global_store_dwordx4 v[50:51], v[132:135], off
	global_store_dwordx4 v[50:51], v[136:139], off offset:16
.Lmx0_st_n2:
	v_lshlrev_b32_e32 v0, 16, v202
	v_and_b32_e32 v1, 0xffff0000, v202
	v_lshlrev_b32_e32 v2, 16, v203
	v_and_b32_e32 v3, 0xffff0000, v203
	v_lshlrev_b32_e32 v4, 16, v204
	v_and_b32_e32 v5, 0xffff0000, v204
	v_lshlrev_b32_e32 v6, 16, v205
	v_and_b32_e32 v7, 0xffff0000, v205
	v_lshlrev_b32_e32 v8, 16, v218
	v_and_b32_e32 v9, 0xffff0000, v218
	v_lshlrev_b32_e32 v10, 16, v219
	v_and_b32_e32 v11, 0xffff0000, v219
	v_lshlrev_b32_e32 v12, 16, v220
	v_and_b32_e32 v13, 0xffff0000, v220
	v_lshlrev_b32_e32 v14, 16, v221
	v_and_b32_e32 v15, 0xffff0000, v221
	v_mul_f32_e32 v16, v158, v124
	v_mul_f32_e32 v17, v159, v125
	v_mul_f32_e32 v18, v160, v126
	v_mul_f32_e32 v19, v161, v127
	v_mul_f32_e32 v20, v162, v128
	v_mul_f32_e32 v21, v163, v129
	v_mul_f32_e32 v22, v164, v130
	v_mul_f32_e32 v23, v165, v131
	v_fmac_f32_e32 v16, v166, v132
	v_fmac_f32_e32 v17, v167, v133
	v_fmac_f32_e32 v18, v168, v134
	v_fmac_f32_e32 v19, v169, v135
	v_fmac_f32_e32 v20, v170, v136
	v_fmac_f32_e32 v21, v171, v137
	v_fmac_f32_e32 v22, v172, v138
	v_fmac_f32_e32 v23, v173, v139
	v_fmac_f32_e32 v16, v174, v0
	v_fmac_f32_e32 v17, v175, v1
	v_fmac_f32_e32 v18, v176, v2
	v_fmac_f32_e32 v19, v177, v3
	v_fmac_f32_e32 v20, v178, v4
	v_fmac_f32_e32 v21, v179, v5
	v_fmac_f32_e32 v22, v180, v6
	v_fmac_f32_e32 v23, v181, v7
	v_mul_f32_e32 v16, v8, v16
	v_mul_f32_e32 v17, v9, v17
	v_mul_f32_e32 v18, v10, v18
	v_mul_f32_e32 v19, v11, v19
	v_mul_f32_e32 v20, v12, v20
	v_mul_f32_e32 v21, v13, v21
	v_mul_f32_e32 v22, v14, v22
	v_mul_f32_e32 v23, v15, v23
	v_cvt_pk_bf16_f32 v36, v16, v17
	v_cvt_pk_bf16_f32 v37, v18, v19
	v_cvt_pk_bf16_f32 v38, v20, v21
	v_cvt_pk_bf16_f32 v39, v22, v23
	s_add_u32 s6, s0, 3
	s_addc_u32 s7, s1, 0
	s_lshl_b64 s[6:7], s[6:7], 11
	v_lshl_add_u64 v[48:49], v[66:67], 0, s[6:7]
	global_store_dwordx4 v[48:49], v[36:39], off
	s_cmpk_gt_i32 s8, 0x1ff
	s_cbranch_scc1 .Lmx0_st_s3
	s_add_i32 s9, s80, 3
	s_cmpk_lt_i32 s9, 0x7fe
	s_cbranch_scc1 .Lmx0_st_n3
	s_lshl_b32 s6, s76, 1
	s_add_i32 s6, s6, s9
	s_sub_i32 s6, s6, 0x7fe
	s_lshl_b32 s6, s6, 11
	s_mov_b32 s7, 0
	v_lshl_add_u64 v[50:51], v[70:71], 0, s[6:7]
	s_branch .Lmx0_st_w3
.Lmx0_st_s3:
	s_add_i32 s9, s82, 3
	s_cmp_lt_i32 s9, 6
	s_cbranch_scc1 .Lmx0_st_n3
	s_add_i32 s6, s8, 0xfffffe00
	s_lshl_b32 s6, s6, 1
	s_add_i32 s6, s6, s9
	s_sub_i32 s6, s6, 6
	s_lshl_b32 s6, s6, 11
	s_mov_b32 s7, 0
	v_lshl_add_u64 v[50:51], v[72:73], 0, s[6:7]

; __device__ __forceinline__ void phase_mixer0(const Params& p, LAS unsigned char* lds) {
;     ...
; #pragma unroll
;                 for (int q = 0; q < 8; ++q) { um2[q] = um1[q]; um1[q] = u0[q]; }
;             }
;         }
;         __syncthreads();
;     }
.Lmx0_st_n3:
	s_branch .LBB0_235
.LBB0_312:
	s_mov_b32 s97, s20

; __device__ __forceinline__ void phase_final(const Params& p) {
;     int tid_ = threadIdx.x; asm volatile("" : "+v"(tid_)); const int tid = tid_, lane = tid & 63, wave = tid >> 6;
;     const int gw = blockIdx.x * 8 + wave, NGW = gridDim.x * 8;
;     const float* ss4 = (const float*)(p.ws + WS_SS) + 4 * (size_t)M; const float* gf = p.in[24];
;     f32x4 g4[4];
; #pragma unroll
;     for (int j = 0; j < 4; ++j) g4[j] = *((const f32x4*)gf + lane + 64 * j);
;     const bf16* XB = (const bf16*)(p.ws + WS_XB);
;     for (int m = gw; m < MP; m += NGW) {
;         const float rs = __builtin_amdgcn_rsqf(ss4[m] * (1.f / 1024.f) + EPS);
;         const unsigned long long* x8 = (const unsigned long long*)(XB + (size_t)m * D) + lane;
;         f32x4* xr = (f32x4*)(p.out + (size_t)m * D) + lane;
; #pragma unroll
;         for (int j = 0; j < 4; ++j) { const unsigned long long w = x8[64 * j]; const unsigned lo = (unsigned)w, hi = (unsigned)(w >> 32);
;             const f32x4 v = (f32x4){__uint_as_float(lo << 16), __uint_as_float(lo & 0xffff0000u), __uint_as_float(hi << 16), __uint_as_float(hi & 0xffff0000u)};
;             xr[64 * j] = v * rs * g4[j]; }
;     }
.LBB0_1384:
	s_cmp_gt_i32 s74, 14
	s_cselect_b64 s[0:1], -1, 0
	s_xor_b64 s[2:3], s[2:3], -1
	s_or_b64 s[0:1], s[0:1], s[2:3]
	s_and_b64 vcc, exec, s[0:1]
	s_cbranch_vccnz .LBB0_1391
	s_waitcnt vmcnt(0)
	v_mov_b32_e32 v0, v238
	s_lshl_b32 s12, s33, 3
	v_ashrrev_i32_e32 v1, 6, v0
	v_add_u32_e32 v16, s12, v1
	s_movk_i32 s0, 0x4000
	s_lshl_b32 s2, s10, 3
	v_cmp_gt_i32_e32 vcc, s0, v16
	s_and_saveexec_b64 s[0:1], vcc
	s_cbranch_execz .LBB0_1388
	v_and_b32_e32 v22, 63, v0
	v_lshlrev_b32_e32 v24, 4, v22
	s_waitcnt lgkmcnt(0)
	global_load_dwordx4 v[0:3], v24, s[68:69]
	global_load_dwordx4 v[4:7], v24, s[68:69] offset:1024
	global_load_dwordx4 v[8:11], v24, s[68:69] offset:2048
	global_load_dwordx4 v[12:15], v24, s[68:69] offset:3072
	s_cmpk_lg_u32 s2, 0x800
	s_cbranch_scc1 .Lfin_generic
	s_add_u32 s4, s72, 0x44000
	s_addc_u32 s5, s73, 0
	s_add_u32 s6, s72, 0x2e00000
	s_addc_u32 s7, s73, 0
	v_lshlrev_b32_e32 v17, 2, v16
	v_lshlrev_b32_e32 v18, 11, v16
	v_lshl_or_b32 v18, v22, 3, v18
	v_lshlrev_b32_e32 v19, 12, v16
	v_or_b32_e32 v19, v19, v24
	v_mov_b32_e32 v23, 0x358637bd
	global_load_dword v32, v17, s[4:5]
	v_add_u32_e32 v20, 0x2000, v17
	global_load_dword v33, v20, s[4:5]
	v_add_u32_e32 v20, 0x4000, v17
	global_load_dword v34, v20, s[4:5]
	v_add_u32_e32 v20, 0x6000, v17
	global_load_dword v35, v20, s[4:5]
	v_add_u32_e32 v20, 0x8000, v17
	global_load_dword v36, v20, s[4:5]
	v_add_u32_e32 v20, 0xa000, v17
	global_load_dword v37, v20, s[4:5]
	v_add_u32_e32 v20, 0xc000, v17
	global_load_dword v38, v20, s[4:5]
	v_add_u32_e32 v20, 0xe000, v17
	global_load_dword v39, v20, s[4:5]
	global_load_dwordx2 v[40:41], v18, s[6:7]
	global_load_dwordx2 v[42:43], v18, s[6:7] offset:512
	global_load_dwordx2 v[44:45], v18, s[6:7] offset:1024
	global_load_dwordx2 v[46:47], v18, s[6:7] offset:1536
	v_add_u32_e32 v21, 0x400000, v18
	global_load_dwordx2 v[48:49], v21, s[6:7]
	global_load_dwordx2 v[50:51], v21, s[6:7] offset:512
	global_load_dwordx2 v[52:53], v21, s[6:7] offset:1024
	global_load_dwordx2 v[54:55], v21, s[6:7] offset:1536
	v_add_u32_e32 v21, 0x800000, v18
	global_load_dwordx2 v[56:57], v21, s[6:7]
	global_load_dwordx2 v[58:59], v21, s[6:7] offset:512
	global_load_dwordx2 v[60:61], v21, s[6:7] offset:1024
	global_load_dwordx2 v[62:63], v21, s[6:7] offset:1536
	v_add_u32_e32 v21, 0xc00000, v18
	global_load_dwordx2 v[64:65], v21, s[6:7]
	global_load_dwordx2 v[66:67], v21, s[6:7] offset:512
	global_load_dwordx2 v[68:69], v21, s[6:7] offset:1024
	global_load_dwordx2 v[70:71], v21, s[6:7] offset:1536
	v_add_u32_e32 v21, 0x1000000, v18
	global_load_dwordx2 v[72:73], v21, s[6:7]
	global_load_dwordx2 v[74:75], v21, s[6:7] offset:512
	global_load_dwordx2 v[76:77], v21, s[6:7] offset:1024
	global_load_dwordx2 v[78:79], v21, s[6:7] offset:1536
	v_add_u32_e32 v21, 0x1400000, v18
	global_load_dwordx2 v[80:81], v21, s[6:7]
	global_load_dwordx2 v[82:83], v21, s[6:7] offset:512
	global_load_dwordx2 v[84:85], v21, s[6:7] offset:1024
	global_load_dwordx2 v[86:87], v21, s[6:7] offset:1536
	v_add_u32_e32 v21, 0x1800000, v18
	global_load_dwordx2 v[88:89], v21, s[6:7]
	global_load_dwordx2 v[90:91], v21, s[6:7] offset:512
	global_load_dwordx2 v[92:93], v21, s[6:7] offset:1024
	global_load_dwordx2 v[94:95], v21, s[6:7] offset:1536
	v_add_u32_e32 v21, 0x1c00000, v18
	global_load_dwordx2 v[96:97], v21, s[6:7]
	global_load_dwordx2 v[98:99], v21, s[6:7] offset:512
	global_load_dwordx2 v[100:101], v21, s[6:7] offset:1024
	global_load_dwordx2 v[102:103], v21, s[6:7] offset:1536
	s_waitcnt vmcnt(31)
	v_fmamk_f32 v26, v32, 0x3a800000, v23
	v_rsq_f32_e32 v30, v26
	v_lshlrev_b32_e32 v104, 16, v40
	v_and_b32_e32 v105, 0xffff0000, v40
	v_lshlrev_b32_e32 v106, 16, v41
	v_and_b32_e32 v107, 0xffff0000, v41
	v_pk_mul_f32 v[108:109], v[30:31], v[104:105] op_sel_hi:[0,1]
	v_pk_mul_f32 v[110:111], v[30:31], v[106:107] op_sel_hi:[0,1]
	v_pk_mul_f32 v[114:115], v[2:3], v[110:111]
	v_pk_mul_f32 v[112:113], v[0:1], v[108:109]
	global_store_dwordx4 v19, v[112:115], s[70:71]
	s_waitcnt vmcnt(31)
	v_lshlrev_b32_e32 v104, 16, v42
	v_and_b32_e32 v105, 0xffff0000, v42
	v_lshlrev_b32_e32 v106, 16, v43
	v_and_b32_e32 v107, 0xffff0000, v43
	v_pk_mul_f32 v[108:109], v[30:31], v[104:105] op_sel_hi:[0,1]
	v_pk_mul_f32 v[110:111], v[30:31], v[106:107] op_sel_hi:[0,1]
	v_pk_mul_f32 v[118:119], v[6:7], v[110:111]
	v_pk_mul_f32 v[116:117], v[4:5], v[108:109]
	global_store_dwordx4 v19, v[116:119], s[70:71] offset:1024
	s_waitcnt vmcnt(31)
	v_lshlrev_b32_e32 v104, 16, v44
	v_and_b32_e32 v105, 0xffff0000, v44
	v_lshlrev_b32_e32 v106, 16, v45
	v_and_b32_e32 v107, 0xffff0000, v45
	v_pk_mul_f32 v[108:109], v[30:31], v[104:105] op_sel_hi:[0,1]
	v_pk_mul_f32 v[110:111], v[30:31], v[106:107] op_sel_hi:[0,1]
	v_pk_mul_f32 v[122:123], v[10:11], v[110:111]
	v_pk_mul_f32 v[120:121], v[8:9], v[108:109]
	global_store_dwordx4 v19, v[120:123], s[70:71] offset:2048
	s_waitcnt vmcnt(31)
	v_lshlrev_b32_e32 v104, 16, v46
	v_and_b32_e32 v105, 0xffff0000, v46
	v_lshlrev_b32_e32 v106, 16, v47
	v_and_b32_e32 v107, 0xffff0000, v47
	v_pk_mul_f32 v[108:109], v[30:31], v[104:105] op_sel_hi:[0,1]
	v_pk_mul_f32 v[110:111], v[30:31], v[106:107] op_sel_hi:[0,1]
	v_pk_mul_f32 v[126:127], v[14:15], v[110:111]
	v_pk_mul_f32 v[124:125], v[12:13], v[108:109]
	global_store_dwordx4 v19, v[124:127], s[70:71] offset:3072
	v_add_u32_e32 v25, 0x800000, v19
	s_waitcnt vmcnt(31)
	v_fmamk_f32 v26, v33, 0x3a800000, v23
	v_rsq_f32_e32 v30, v26
	v_lshlrev_b32_e32 v104, 16, v48
	v_and_b32_e32 v105, 0xffff0000, v48
	v_lshlrev_b32_e32 v106, 16, v49
	v_and_b32_e32 v107, 0xffff0000, v49
	v_pk_mul_f32 v[108:109], v[30:31], v[104:105] op_sel_hi:[0,1]
	v_pk_mul_f32 v[110:111], v[30:31], v[106:107] op_sel_hi:[0,1]
	v_pk_mul_f32 v[114:115], v[2:3], v[110:111]
	v_pk_mul_f32 v[112:113], v[0:1], v[108:109]
	global_store_dwordx4 v25, v[112:115], s[70:71]
	s_waitcnt vmcnt(31)
; __device__ __forceinline__ void phase_final(const Params& p) {
;     ...
;     for (int m = gw; m < MP; m += NGW) {
;         const float rs = __builtin_amdgcn_rsqf(ss4[m] * (1.f / 1024.f) + EPS);
;         const unsigned long long* x8 = (const unsigned long long*)(XB + (size_t)m * D) + lane;
;         f32x4* xr = (f32x4*)(p.out + (size_t)m * D) + lane;
; #pragma unroll
;         for (int j = 0; j < 4; ++j) { const unsigned long long w = x8[64 * j]; const unsigned lo = (unsigned)w, hi = (unsigned)(w >> 32);
;             const f32x4 v = (f32x4){__uint_as_float(lo << 16), __uint_as_float(lo & 0xffff0000u), __uint_as_float(hi << 16), __uint_as_float(hi & 0xffff0000u)};
;             xr[64 * j] = v * rs * g4[j]; }
;     }
	v_lshlrev_b32_e32 v104, 16, v50
	v_and_b32_e32 v105, 0xffff0000, v50
	v_lshlrev_b32_e32 v106, 16, v51
	v_and_b32_e32 v107, 0xffff0000, v51
	v_pk_mul_f32 v[108:109], v[30:31], v[104:105] op_sel_hi:[0,1]
	v_pk_mul_f32 v[110:111], v[30:31], v[106:107] op_sel_hi:[0,1]
	v_pk_mul_f32 v[118:119], v[6:7], v[110:111]
	v_pk_mul_f32 v[116:117], v[4:5], v[108:109]
	global_store_dwordx4 v25, v[116:119], s[70:71] offset:1024
	s_waitcnt vmcnt(31)
	v_lshlrev_b32_e32 v104, 16, v52
	v_and_b32_e32 v105, 0xffff0000, v52
	v_lshlrev_b32_e32 v106, 16, v53
	v_and_b32_e32 v107, 0xffff0000, v53
	v_pk_mul_f32 v[108:109], v[30:31], v[104:105] op_sel_hi:[0,1]
	v_pk_mul_f32 v[110:111], v[30:31], v[106:107] op_sel_hi:[0,1]
	v_pk_mul_f32 v[122:123], v[10:11], v[110:111]
	v_pk_mul_f32 v[120:121], v[8:9], v[108:109]
	global_store_dwordx4 v25, v[120:123], s[70:71] offset:2048
	s_waitcnt vmcnt(31)
	v_lshlrev_b32_e32 v104, 16, v54
	v_and_b32_e32 v105, 0xffff0000, v54
	v_lshlrev_b32_e32 v106, 16, v55
	v_and_b32_e32 v107, 0xffff0000, v55
	v_pk_mul_f32 v[108:109], v[30:31], v[104:105] op_sel_hi:[0,1]
	v_pk_mul_f32 v[110:111], v[30:31], v[106:107] op_sel_hi:[0,1]
	v_pk_mul_f32 v[126:127], v[14:15], v[110:111]
	v_pk_mul_f32 v[124:125], v[12:13], v[108:109]
	global_store_dwordx4 v25, v[124:127], s[70:71] offset:3072
	v_add_u32_e32 v25, 0x1000000, v19
	s_waitcnt vmcnt(31)
	v_fmamk_f32 v26, v34, 0x3a800000, v23
	v_rsq_f32_e32 v30, v26
	v_lshlrev_b32_e32 v104, 16, v56
	v_and_b32_e32 v105, 0xffff0000, v56
	v_lshlrev_b32_e32 v106, 16, v57
	v_and_b32_e32 v107, 0xffff0000, v57
	v_pk_mul_f32 v[108:109], v[30:31], v[104:105] op_sel_hi:[0,1]
	v_pk_mul_f32 v[110:111], v[30:31], v[106:107] op_sel_hi:[0,1]
	v_pk_mul_f32 v[114:115], v[2:3], v[110:111]
	v_pk_mul_f32 v[112:113], v[0:1], v[108:109]
	global_store_dwordx4 v25, v[112:115], s[70:71]
	s_waitcnt vmcnt(31)
	v_lshlrev_b32_e32 v104, 16, v58
	v_and_b32_e32 v105, 0xffff0000, v58
	v_lshlrev_b32_e32 v106, 16, v59
	v_and_b32_e32 v107, 0xffff0000, v59
	v_pk_mul_f32 v[108:109], v[30:31], v[104:105] op_sel_hi:[0,1]
	v_pk_mul_f32 v[110:111], v[30:31], v[106:107] op_sel_hi:[0,1]
	v_pk_mul_f32 v[118:119], v[6:7], v[110:111]
	v_pk_mul_f32 v[116:117], v[4:5], v[108:109]
	global_store_dwordx4 v25, v[116:119], s[70:71] offset:1024
	s_waitcnt vmcnt(31)
	v_lshlrev_b32_e32 v104, 16, v60
	v_and_b32_e32 v105, 0xffff0000, v60
	v_lshlrev_b32_e32 v106, 16, v61
	v_and_b32_e32 v107, 0xffff0000, v61
	v_pk_mul_f32 v[108:109], v[30:31], v[104:105] op_sel_hi:[0,1]
	v_pk_mul_f32 v[110:111], v[30:31], v[106:107] op_sel_hi:[0,1]
	v_pk_mul_f32 v[122:123], v[10:11], v[110:111]
	v_pk_mul_f32 v[120:121], v[8:9], v[108:109]
	global_store_dwordx4 v25, v[120:123], s[70:71] offset:2048
	s_waitcnt vmcnt(31)
	v_lshlrev_b32_e32 v104, 16, v62
	v_and_b32_e32 v105, 0xffff0000, v62
	v_lshlrev_b32_e32 v106, 16, v63
	v_and_b32_e32 v107, 0xffff0000, v63
	v_pk_mul_f32 v[108:109], v[30:31], v[104:105] op_sel_hi:[0,1]
	v_pk_mul_f32 v[110:111], v[30:31], v[106:107] op_sel_hi:[0,1]
	v_pk_mul_f32 v[126:127], v[14:15], v[110:111]
	v_pk_mul_f32 v[124:125], v[12:13], v[108:109]
	global_store_dwordx4 v25, v[124:127], s[70:71] offset:3072
	v_add_u32_e32 v25, 0x1800000, v19
	s_waitcnt vmcnt(31)
	v_fmamk_f32 v26, v35, 0x3a800000, v23
	v_rsq_f32_e32 v30, v26
	v_lshlrev_b32_e32 v104, 16, v64
	v_and_b32_e32 v105, 0xffff0000, v64
	v_lshlrev_b32_e32 v106, 16, v65
	v_and_b32_e32 v107, 0xffff0000, v65
	v_pk_mul_f32 v[108:109], v[30:31], v[104:105] op_sel_hi:[0,1]
	v_pk_mul_f32 v[110:111], v[30:31], v[106:107] op_sel_hi:[0,1]
	v_pk_mul_f32 v[114:115], v[2:3], v[110:111]
	v_pk_mul_f32 v[112:113], v[0:1], v[108:109]
	global_store_dwordx4 v25, v[112:115], s[70:71]
	s_waitcnt vmcnt(31)
	v_lshlrev_b32_e32 v104, 16, v66
	v_and_b32_e32 v105, 0xffff0000, v66
	v_lshlrev_b32_e32 v106, 16, v67
	v_and_b32_e32 v107, 0xffff0000, v67
	v_pk_mul_f32 v[108:109], v[30:31], v[104:105] op_sel_hi:[0,1]
	v_pk_mul_f32 v[110:111], v[30:31], v[106:107] op_sel_hi:[0,1]
	v_pk_mul_f32 v[118:119], v[6:7], v[110:111]
	v_pk_mul_f32 v[116:117], v[4:5], v[108:109]
	global_store_dwordx4 v25, v[116:119], s[70:71] offset:1024
	s_waitcnt vmcnt(31)
	v_lshlrev_b32_e32 v104, 16, v68
	v_and_b32_e32 v105, 0xffff0000, v68
	v_lshlrev_b32_e32 v106, 16, v69
	v_and_b32_e32 v107, 0xffff0000, v69
	v_pk_mul_f32 v[108:109], v[30:31], v[104:105] op_sel_hi:[0,1]
	v_pk_mul_f32 v[110:111], v[30:31], v[106:107] op_sel_hi:[0,1]
	v_pk_mul_f32 v[122:123], v[10:11], v[110:111]
	v_pk_mul_f32 v[120:121], v[8:9], v[108:109]
	global_store_dwordx4 v25, v[120:123], s[70:71] offset:2048
	s_waitcnt vmcnt(31)
	v_lshlrev_b32_e32 v104, 16, v70
	v_and_b32_e32 v105, 0xffff0000, v70
	v_lshlrev_b32_e32 v106, 16, v71
	v_and_b32_e32 v107, 0xffff0000, v71
	v_pk_mul_f32 v[108:109], v[30:31], v[104:105] op_sel_hi:[0,1]
	v_pk_mul_f32 v[110:111], v[30:31], v[106:107] op_sel_hi:[0,1]
	v_pk_mul_f32 v[126:127], v[14:15], v[110:111]
	v_pk_mul_f32 v[124:125], v[12:13], v[108:109]
	global_store_dwordx4 v25, v[124:127], s[70:71] offset:3072
	v_add_u32_e32 v25, 0x2000000, v19
	s_waitcnt vmcnt(31)
	v_fmamk_f32 v26, v36, 0x3a800000, v23
	v_rsq_f32_e32 v30, v26
	v_lshlrev_b32_e32 v104, 16, v72
	v_and_b32_e32 v105, 0xffff0000, v72
	v_lshlrev_b32_e32 v106, 16, v73
	v_and_b32_e32 v107, 0xffff0000, v73
	v_pk_mul_f32 v[108:109], v[30:31], v[104:105] op_sel_hi:[0,1]
	v_pk_mul_f32 v[110:111], v[30:31], v[106:107] op_sel_hi:[0,1]
	v_pk_mul_f32 v[114:115], v[2:3], v[110:111]
	v_pk_mul_f32 v[112:113], v[0:1], v[108:109]
	global_store_dwordx4 v25, v[112:115], s[70:71]
	s_waitcnt vmcnt(31)
; __device__ __forceinline__ void phase_final(const Params& p) {
;     ...
;     for (int m = gw; m < MP; m += NGW) {
;         const float rs = __builtin_amdgcn_rsqf(ss4[m] * (1.f / 1024.f) + EPS);
;         const unsigned long long* x8 = (const unsigned long long*)(XB + (size_t)m * D) + lane;
;         f32x4* xr = (f32x4*)(p.out + (size_t)m * D) + lane;
; #pragma unroll
;         for (int j = 0; j < 4; ++j) { const unsigned long long w = x8[64 * j]; const unsigned lo = (unsigned)w, hi = (unsigned)(w >> 32);
;             const f32x4 v = (f32x4){__uint_as_float(lo << 16), __uint_as_float(lo & 0xffff0000u), __uint_as_float(hi << 16), __uint_as_float(hi & 0xffff0000u)};
;             xr[64 * j] = v * rs * g4[j]; }
;     }
	v_lshlrev_b32_e32 v104, 16, v74
	v_and_b32_e32 v105, 0xffff0000, v74
	v_lshlrev_b32_e32 v106, 16, v75
	v_and_b32_e32 v107, 0xffff0000, v75
	v_pk_mul_f32 v[108:109], v[30:31], v[104:105] op_sel_hi:[0,1]
	v_pk_mul_f32 v[110:111], v[30:31], v[106:107] op_sel_hi:[0,1]
	v_pk_mul_f32 v[118:119], v[6:7], v[110:111]
	v_pk_mul_f32 v[116:117], v[4:5], v[108:109]
	global_store_dwordx4 v25, v[116:119], s[70:71] offset:1024
	s_waitcnt vmcnt(31)
	v_lshlrev_b32_e32 v104, 16, v76
	v_and_b32_e32 v105, 0xffff0000, v76
	v_lshlrev_b32_e32 v106, 16, v77
	v_and_b32_e32 v107, 0xffff0000, v77
	v_pk_mul_f32 v[108:109], v[30:31], v[104:105] op_sel_hi:[0,1]
	v_pk_mul_f32 v[110:111], v[30:31], v[106:107] op_sel_hi:[0,1]
	v_pk_mul_f32 v[122:123], v[10:11], v[110:111]
	v_pk_mul_f32 v[120:121], v[8:9], v[108:109]
	global_store_dwordx4 v25, v[120:123], s[70:71] offset:2048
	s_waitcnt vmcnt(31)
	v_lshlrev_b32_e32 v104, 16, v78
	v_and_b32_e32 v105, 0xffff0000, v78
	v_lshlrev_b32_e32 v106, 16, v79
	v_and_b32_e32 v107, 0xffff0000, v79
	v_pk_mul_f32 v[108:109], v[30:31], v[104:105] op_sel_hi:[0,1]
	v_pk_mul_f32 v[110:111], v[30:31], v[106:107] op_sel_hi:[0,1]
	v_pk_mul_f32 v[126:127], v[14:15], v[110:111]
	v_pk_mul_f32 v[124:125], v[12:13], v[108:109]
	global_store_dwordx4 v25, v[124:127], s[70:71] offset:3072
	v_add_u32_e32 v25, 0x2800000, v19
	s_waitcnt vmcnt(31)
	v_fmamk_f32 v26, v37, 0x3a800000, v23
	v_rsq_f32_e32 v30, v26
	v_lshlrev_b32_e32 v104, 16, v80
	v_and_b32_e32 v105, 0xffff0000, v80
	v_lshlrev_b32_e32 v106, 16, v81
	v_and_b32_e32 v107, 0xffff0000, v81
	v_pk_mul_f32 v[108:109], v[30:31], v[104:105] op_sel_hi:[0,1]
	v_pk_mul_f32 v[110:111], v[30:31], v[106:107] op_sel_hi:[0,1]
	v_pk_mul_f32 v[114:115], v[2:3], v[110:111]
	v_pk_mul_f32 v[112:113], v[0:1], v[108:109]
	global_store_dwordx4 v25, v[112:115], s[70:71]
	s_waitcnt vmcnt(31)
	v_lshlrev_b32_e32 v104, 16, v82
	v_and_b32_e32 v105, 0xffff0000, v82
	v_lshlrev_b32_e32 v106, 16, v83
	v_and_b32_e32 v107, 0xffff0000, v83
	v_pk_mul_f32 v[108:109], v[30:31], v[104:105] op_sel_hi:[0,1]
	v_pk_mul_f32 v[110:111], v[30:31], v[106:107] op_sel_hi:[0,1]
	v_pk_mul_f32 v[118:119], v[6:7], v[110:111]
	v_pk_mul_f32 v[116:117], v[4:5], v[108:109]
	global_store_dwordx4 v25, v[116:119], s[70:71] offset:1024
	s_waitcnt vmcnt(31)
	v_lshlrev_b32_e32 v104, 16, v84
	v_and_b32_e32 v105, 0xffff0000, v84
	v_lshlrev_b32_e32 v106, 16, v85
	v_and_b32_e32 v107, 0xffff0000, v85
	v_pk_mul_f32 v[108:109], v[30:31], v[104:105] op_sel_hi:[0,1]
	v_pk_mul_f32 v[110:111], v[30:31], v[106:107] op_sel_hi:[0,1]
	v_pk_mul_f32 v[122:123], v[10:11], v[110:111]
	v_pk_mul_f32 v[120:121], v[8:9], v[108:109]
	global_store_dwordx4 v25, v[120:123], s[70:71] offset:2048
	s_waitcnt vmcnt(31)
	v_lshlrev_b32_e32 v104, 16, v86
	v_and_b32_e32 v105, 0xffff0000, v86
	v_lshlrev_b32_e32 v106, 16, v87
	v_and_b32_e32 v107, 0xffff0000, v87
	v_pk_mul_f32 v[108:109], v[30:31], v[104:105] op_sel_hi:[0,1]
	v_pk_mul_f32 v[110:111], v[30:31], v[106:107] op_sel_hi:[0,1]
	v_pk_mul_f32 v[126:127], v[14:15], v[110:111]
	v_pk_mul_f32 v[124:125], v[12:13], v[108:109]
	global_store_dwordx4 v25, v[124:127], s[70:71] offset:3072
	v_add_u32_e32 v25, 0x3000000, v19
	s_waitcnt vmcnt(31)
	v_fmamk_f32 v26, v38, 0x3a800000, v23
	v_rsq_f32_e32 v30, v26
	v_lshlrev_b32_e32 v104, 16, v88
	v_and_b32_e32 v105, 0xffff0000, v88
	v_lshlrev_b32_e32 v106, 16, v89
	v_and_b32_e32 v107, 0xffff0000, v89
	v_pk_mul_f32 v[108:109], v[30:31], v[104:105] op_sel_hi:[0,1]
	v_pk_mul_f32 v[110:111], v[30:31], v[106:107] op_sel_hi:[0,1]
	v_pk_mul_f32 v[114:115], v[2:3], v[110:111]
	v_pk_mul_f32 v[112:113], v[0:1], v[108:109]
	global_store_dwordx4 v25, v[112:115], s[70:71]
	s_waitcnt vmcnt(31)
	v_lshlrev_b32_e32 v104, 16, v90
	v_and_b32_e32 v105, 0xffff0000, v90
	v_lshlrev_b32_e32 v106, 16, v91
	v_and_b32_e32 v107, 0xffff0000, v91
	v_pk_mul_f32 v[108:109], v[30:31], v[104:105] op_sel_hi:[0,1]
	v_pk_mul_f32 v[110:111], v[30:31], v[106:107] op_sel_hi:[0,1]
	v_pk_mul_f32 v[118:119], v[6:7], v[110:111]
	v_pk_mul_f32 v[116:117], v[4:5], v[108:109]
	global_store_dwordx4 v25, v[116:119], s[70:71] offset:1024
	s_waitcnt vmcnt(31)
	v_lshlrev_b32_e32 v104, 16, v92
	v_and_b32_e32 v105, 0xffff0000, v92
	v_lshlrev_b32_e32 v106, 16, v93
	v_and_b32_e32 v107, 0xffff0000, v93
	v_pk_mul_f32 v[108:109], v[30:31], v[104:105] op_sel_hi:[0,1]
	v_pk_mul_f32 v[110:111], v[30:31], v[106:107] op_sel_hi:[0,1]
	v_pk_mul_f32 v[122:123], v[10:11], v[110:111]
	v_pk_mul_f32 v[120:121], v[8:9], v[108:109]
	global_store_dwordx4 v25, v[120:123], s[70:71] offset:2048
	s_waitcnt vmcnt(31)
	v_lshlrev_b32_e32 v104, 16, v94
	v_and_b32_e32 v105, 0xffff0000, v94
	v_lshlrev_b32_e32 v106, 16, v95
	v_and_b32_e32 v107, 0xffff0000, v95
	v_pk_mul_f32 v[108:109], v[30:31], v[104:105] op_sel_hi:[0,1]
	v_pk_mul_f32 v[110:111], v[30:31], v[106:107] op_sel_hi:[0,1]
	v_pk_mul_f32 v[126:127], v[14:15], v[110:111]
	v_pk_mul_f32 v[124:125], v[12:13], v[108:109]
	global_store_dwordx4 v25, v[124:127], s[70:71] offset:3072
	v_add_u32_e32 v25, 0x3800000, v19
	s_waitcnt vmcnt(31)
	v_fmamk_f32 v26, v39, 0x3a800000, v23
	v_rsq_f32_e32 v30, v26
	v_lshlrev_b32_e32 v104, 16, v96
	v_and_b32_e32 v105, 0xffff0000, v96
	v_lshlrev_b32_e32 v106, 16, v97
	v_and_b32_e32 v107, 0xffff0000, v97
	v_pk_mul_f32 v[108:109], v[30:31], v[104:105] op_sel_hi:[0,1]
	v_pk_mul_f32 v[110:111], v[30:31], v[106:107] op_sel_hi:[0,1]
	v_pk_mul_f32 v[114:115], v[2:3], v[110:111]
	v_pk_mul_f32 v[112:113], v[0:1], v[108:109]
	global_store_dwordx4 v25, v[112:115], s[70:71]
	s_waitcnt vmcnt(31)
	v_lshlrev_b32_e32 v104, 16, v98
	v_and_b32_e32 v105, 0xffff0000, v98
	v_lshlrev_b32_e32 v106, 16, v99
	v_and_b32_e32 v107, 0xffff0000, v99
	v_pk_mul_f32 v[108:109], v[30:31], v[104:105] op_sel_hi:[0,1]
	v_pk_mul_f32 v[110:111], v[30:31], v[106:107] op_sel_hi:[0,1]
	v_pk_mul_f32 v[118:119], v[6:7], v[110:111]
	v_pk_mul_f32 v[116:117], v[4:5], v[108:109]
	global_store_dwordx4 v25, v[116:119], s[70:71] offset:1024
	s_waitcnt vmcnt(31)
	v_lshlrev_b32_e32 v104, 16, v100
	v_and_b32_e32 v105, 0xffff0000, v100
	v_lshlrev_b32_e32 v106, 16, v101
	v_and_b32_e32 v107, 0xffff0000, v101
	v_pk_mul_f32 v[108:109], v[30:31], v[104:105] op_sel_hi:[0,1]
	v_pk_mul_f32 v[110:111], v[30:31], v[106:107] op_sel_hi:[0,1]
	v_pk_mul_f32 v[122:123], v[10:11], v[110:111]
	v_pk_mul_f32 v[120:121], v[8:9], v[108:109]
	global_store_dwordx4 v25, v[120:123], s[70:71] offset:2048
	s_waitcnt vmcnt(31)
	v_lshlrev_b32_e32 v104, 16, v102
	v_and_b32_e32 v105, 0xffff0000, v102
	v_lshlrev_b32_e32 v106, 16, v103
	v_and_b32_e32 v107, 0xffff0000, v103
	v_pk_mul_f32 v[108:109], v[30:31], v[104:105] op_sel_hi:[0,1]
	v_pk_mul_f32 v[110:111], v[30:31], v[106:107] op_sel_hi:[0,1]
	v_pk_mul_f32 v[126:127], v[14:15], v[110:111]
	v_pk_mul_f32 v[124:125], v[12:13], v[108:109]
	global_store_dwordx4 v25, v[124:127], s[70:71] offset:3072
	s_branch .LBB0_1388
; __device__ __forceinline__ void phase_final(const Params& p) {
;     int tid_ = threadIdx.x; asm volatile("" : "+v"(tid_)); const int tid = tid_, lane = tid & 63, wave = tid >> 6;
;     const int gw = blockIdx.x * 8 + wave, NGW = gridDim.x * 8;
;     const float* ss4 = (const float*)(p.ws + WS_SS) + 4 * (size_t)M; const float* gf = p.in[24];
;     f32x4 g4[4];
; #pragma unroll
;     for (int j = 0; j < 4; ++j) g4[j] = *((const f32x4*)gf + lane + 64 * j);
;     const bf16* XB = (const bf16*)(p.ws + WS_XB);
;     for (int m = gw; m < MP; m += NGW) {
;         const float rs = __builtin_amdgcn_rsqf(ss4[m] * (1.f / 1024.f) + EPS);
;         const unsigned long long* x8 = (const unsigned long long*)(XB + (size_t)m * D) + lane;
;         f32x4* xr = (f32x4*)(p.out + (size_t)m * D) + lane;
.Lfin_generic:
	v_ashrrev_i32_e32 v17, 31, v16
	v_lshlrev_b64 v[20:21], 11, v[16:17]
	v_lshl_or_b32 v20, v22, 3, v20
	v_lshlrev_b64 v[22:23], 12, v[16:17]
	v_or_b32_e32 v22, v22, v24
	v_mov_b64_e32 v[18:19], 0x44000
	s_ashr_i32 s3, s2, 31
	v_lshl_add_u64 v[22:23], s[70:71], 0, v[22:23]
	s_mov_b64 s[8:9], 0xc00
	v_lshl_add_u64 v[18:19], v[16:17], 2, v[18:19]
	s_lshl_b64 s[4:5], s[2:3], 2
	s_lshl_b64 s[6:7], s[2:3], 11
	v_lshl_add_u64 v[22:23], v[22:23], 0, s[8:9]
	s_lshl_b64 s[8:9], s[2:3], 12
	s_mov_b64 s[10:11], 0
	v_mov_b32_e32 v17, 0x358637bd
	s_movk_i32 s3, 0x3fff

; template <bool FINAL>
; __device__ __forceinline__ void sample_fixup(const Params& p, int S, float* ss_s, const float* gf) {
;     int tid_ = threadIdx.x; asm volatile("" : "+v"(tid_)); const int tid = tid_, lane = tid & 63, wave = tid >> 6;
;     const int gw = blockIdx.x * 8 + wave, NGW = gridDim.x * 8;
;     const float* part = (const float*)(p.ws + WS_PART); bf16* XB = (bf16*)(p.ws + WS_XB) + (size_t)MP * D; float* xo = p.out + (size_t)MP * D;
;     for (int r = gw; r < MS; r += NGW) {
;         f32x4 v[4];
;         unsigned long long* o8 = (unsigned long long*)(XB + (size_t)r * D) + lane;
; #pragma unroll
;         for (int j = 0; j < 4; ++j) { const unsigned long long w = o8[64 * j]; const unsigned lo = (unsigned)w, hi = (unsigned)(w >> 32);
;             v[j] = (f32x4){__uint_as_float(lo << 16), __uint_as_float(lo & 0xffff0000u), __uint_as_float(hi << 16), __uint_as_float(hi & 0xffff0000u)}; }
;         for (int sp = 0; sp < S; ++sp) {
;             const unsigned long long* pr = (const unsigned long long*)((const bf16*)part + ((size_t)sp * MS + r) * D) + lane;
; #pragma unroll
;             for (int j = 0; j < 4; ++j) { const unsigned long long w = pr[64 * j]; const unsigned lo = (unsigned)w, hi = (unsigned)(w >> 32);
;                 v[j] += (f32x4){__uint_as_float(lo << 16), __uint_as_float(lo & 0xffff0000u), __uint_as_float(hi << 16), __uint_as_float(hi & 0xffff0000u)}; }
;         }
.LBB0_1388:
	s_or_b64 exec, exec, s[0:1]
	s_movk_i32 s0, 0x400
	v_ashrrev_i32_e32 v0, 6, v238
	v_add_u32_e32 v4, s12, v0
	v_cmp_gt_i32_e32 vcc, s0, v4
	s_and_saveexec_b64 s[0:1], vcc
	s_cbranch_execz .LBB0_1391
	v_mbcnt_lo_u32_b32 v0, -1, 0
	v_mbcnt_hi_u32_b32 v0, -1, v0
	v_and_b32_e32 v1, 64, v0
	v_add_u32_e32 v1, 64, v1
	v_xor_b32_e32 v2, 1, v0
	v_cmp_lt_i32_e32 vcc, v2, v1
	v_ashrrev_i32_e32 v5, 31, v4
	s_waitcnt lgkmcnt(0)
	v_and_b32_e32 v8, 63, v238
	v_cndmask_b32_e32 v2, v0, v2, vcc
	v_lshlrev_b32_e32 v30, 2, v2
	v_xor_b32_e32 v2, 2, v0
	v_cmp_lt_i32_e32 vcc, v2, v1
	s_mov_b64 s[0:1], 0xdb00000
	s_ashr_i32 s3, s2, 31
	v_cndmask_b32_e32 v2, v0, v2, vcc
	v_lshlrev_b32_e32 v31, 2, v2
	v_xor_b32_e32 v2, 4, v0
	v_cmp_lt_i32_e32 vcc, v2, v1
	s_lshl_b64 s[4:5], s[2:3], 11
	s_lshl_b64 s[6:7], s[2:3], 12
	v_cndmask_b32_e32 v2, v0, v2, vcc
	v_lshlrev_b32_e32 v32, 2, v2
	v_xor_b32_e32 v2, 8, v0
	v_cmp_lt_i32_e32 vcc, v2, v1
	s_mov_b64 s[8:9], 0
	s_mov_b32 s3, 0x200000
	v_cndmask_b32_e32 v2, v0, v2, vcc
	v_lshlrev_b32_e32 v33, 2, v2
	v_xor_b32_e32 v2, 16, v0
	v_cmp_lt_i32_e32 vcc, v2, v1
	s_mov_b32 s10, 0x400000
	s_mov_b32 s11, 0x600000
	v_cndmask_b32_e32 v2, v0, v2, vcc
	v_lshlrev_b32_e32 v34, 2, v2
	v_xor_b32_e32 v2, 32, v0
	v_cmp_lt_i32_e32 vcc, v2, v1
	v_mov_b32_e32 v1, 0
	s_mov_b32 s12, 0x800000
	v_cndmask_b32_e32 v0, v0, v2, vcc
	v_lshlrev_b64 v[2:3], 11, v[4:5]
	v_lshl_or_b32 v2, v8, 3, v2
	v_lshl_add_u64 v[2:3], s[72:73], 0, v[2:3]
	v_lshlrev_b32_e32 v35, 2, v0
	v_lshlrev_b32_e32 v0, 4, v8
	v_lshl_add_u64 v[8:9], v[2:3], 0, s[0:1]
	v_lshlrev_b64 v[2:3], 12, v[4:5]
	v_or_b32_e32 v2, v2, v0
	v_lshl_add_u64 v[6:7], s[68:69], 0, v[0:1]
	v_lshl_add_u64 v[0:1], s[70:71], 0, v[2:3]
	s_mov_b64 s[0:1], 0x4000000
	v_lshl_add_u64 v[10:11], v[0:1], 0, s[0:1]
	s_mov_b32 s13, 0xa00000
	s_mov_b32 s14, 0xc00000
	s_mov_b32 s15, 0xe00000
	v_mov_b32_e32 v5, 0x358637bd
	s_movk_i32 s16, 0x3ff
	global_load_dwordx4 v[164:167], v[6:7], off offset:1024
	global_load_dwordx4 v[168:171], v[6:7], off offset:2048
	global_load_dwordx4 v[172:175], v[6:7], off offset:3072
.LBB0_1390:
	v_add_co_u32_e64 v22, s[0:1], s3, v8
	v_add_co_u32_e32 v12, vcc, 0xf7300000, v8
	s_nop 0
	v_addc_co_u32_e64 v23, s[0:1], 0, v9, s[0:1]
	v_add_co_u32_e64 v24, s[0:1], s10, v8
	v_addc_co_u32_e32 v13, vcc, -1, v9, vcc
	s_nop 0
	v_addc_co_u32_e64 v25, s[0:1], 0, v9, s[0:1]
	v_add_co_u32_e64 v26, s[0:1], s11, v8
	global_load_dwordx2 v[14:15], v[8:9], off
	global_load_dwordx2 v[16:17], v[8:9], off offset:512
	global_load_dwordx2 v[18:19], v[8:9], off offset:1024
	global_load_dwordx2 v[20:21], v[8:9], off offset:1536
	v_addc_co_u32_e64 v27, s[0:1], 0, v9, s[0:1]
	v_add_co_u32_e64 v28, s[0:1], s12, v8
	global_load_dwordx4 v[0:3], v[6:7], off
	global_load_dwordx2 v[42:43], v[22:23], off
	global_load_dwordx2 v[44:45], v[22:23], off offset:512
	global_load_dwordx2 v[46:47], v[22:23], off offset:1024
	global_load_dwordx2 v[48:49], v[22:23], off offset:1536
	global_load_dwordx2 v[50:51], v[24:25], off
	global_load_dwordx2 v[52:53], v[24:25], off offset:512
	global_load_dwordx2 v[54:55], v[24:25], off offset:1024
	global_load_dwordx2 v[56:57], v[24:25], off offset:1536
	global_load_dwordx2 v[58:59], v[26:27], off
	v_addc_co_u32_e64 v29, s[0:1], 0, v9, s[0:1]
	v_add_co_u32_e64 v36, s[0:1], s13, v8
	v_add_co_u32_e32 v24, vcc, 0xf7301000, v8
	s_nop 0
	v_addc_co_u32_e64 v37, s[0:1], 0, v9, s[0:1]
	v_add_co_u32_e64 v38, s[0:1], s14, v8
	global_load_dwordx2 v[22:23], v[26:27], off offset:512
	s_nop 0
	v_addc_co_u32_e64 v39, s[0:1], 0, v9, s[0:1]
	v_add_co_u32_e64 v40, s[0:1], s15, v8
	v_addc_co_u32_e32 v25, vcc, -1, v9, vcc
	s_nop 0
	v_addc_co_u32_e64 v41, s[0:1], 0, v9, s[0:1]
	global_load_dwordx2 v[60:61], v[26:27], off offset:1024
	global_load_dwordx2 v[62:63], v[26:27], off offset:1536
	global_load_dwordx2 v[64:65], v[28:29], off
	global_load_dwordx2 v[66:67], v[28:29], off offset:512
	global_load_dwordx2 v[68:69], v[28:29], off offset:1024
	global_load_dwordx2 v[70:71], v[28:29], off offset:1536
	global_load_dwordx2 v[72:73], v[36:37], off
	global_load_dwordx2 v[74:75], v[36:37], off offset:512
	global_load_dwordx2 v[76:77], v[36:37], off offset:1024
	global_load_dwordx2 v[78:79], v[36:37], off offset:1536
	global_load_dwordx2 v[80:81], v[38:39], off
	global_load_dwordx2 v[82:83], v[38:39], off offset:512
	global_load_dwordx2 v[84:85], v[38:39], off offset:1024
	global_load_dwordx2 v[86:87], v[38:39], off offset:1536
	global_load_dwordx2 v[88:89], v[40:41], off
	global_load_dwordx2 v[26:27], v[40:41], off offset:512
	global_load_dwordx2 v[28:29], v[40:41], off offset:1024
	global_load_dwordx2 v[36:37], v[40:41], off offset:1536
	s_nop 0
	global_load_dwordx2 v[38:39], v[12:13], off
	global_load_dwordx2 v[40:41], v[24:25], off offset:-3584
	global_load_dwordx2 v[90:91], v[24:25], off offset:-3072
	global_load_dwordx2 v[92:93], v[24:25], off offset:-2560
	v_add_u32_e32 v4, s2, v4
	v_cmp_lt_i32_e32 vcc, s16, v4
	v_lshl_add_u64 v[8:9], v[8:9], 0, s[4:5]
	s_or_b64 s[8:9], vcc, s[8:9]
	s_waitcnt vmcnt(36)
	v_lshlrev_b32_e32 v12, 16, v14
	v_and_b32_e32 v13, 0xffff0000, v14
	v_lshlrev_b32_e32 v14, 16, v15
	v_and_b32_e32 v15, 0xffff0000, v15
	s_waitcnt vmcnt(35)
	v_lshlrev_b32_e32 v24, 16, v16
	v_and_b32_e32 v25, 0xffff0000, v16
	v_lshlrev_b32_e32 v16, 16, v17
	v_and_b32_e32 v17, 0xffff0000, v17
	s_waitcnt vmcnt(34)
	v_lshlrev_b32_e32 v94, 16, v18
	v_and_b32_e32 v95, 0xffff0000, v18
	v_lshlrev_b32_e32 v18, 16, v19
	v_and_b32_e32 v19, 0xffff0000, v19
	s_waitcnt vmcnt(33)
	v_lshlrev_b32_e32 v96, 16, v20
	v_and_b32_e32 v97, 0xffff0000, v20
	v_lshlrev_b32_e32 v20, 16, v21
	v_and_b32_e32 v21, 0xffff0000, v21
	s_waitcnt vmcnt(31)
; template <bool FINAL>
; __device__ __forceinline__ void sample_fixup(const Params& p, int S, float* ss_s, const float* gf) {
;     ...
;         for (int j = 0; j < 4; ++j) { const unsigned long long w = o8[64 * j]; const unsigned lo = (unsigned)w, hi = (unsigned)(w >> 32);
;             v[j] = (f32x4){__uint_as_float(lo << 16), __uint_as_float(lo & 0xffff0000u), __uint_as_float(hi << 16), __uint_as_float(hi & 0xffff0000u)}; }
;         for (int sp = 0; sp < S; ++sp) {
;             const unsigned long long* pr = (const unsigned long long*)((const bf16*)part + ((size_t)sp * MS + r) * D) + lane;
; #pragma unroll
;             for (int j = 0; j < 4; ++j) { const unsigned long long w = pr[64 * j]; const unsigned lo = (unsigned)w, hi = (unsigned)(w >> 32);
;                 v[j] += (f32x4){__uint_as_float(lo << 16), __uint_as_float(lo & 0xffff0000u), __uint_as_float(hi << 16), __uint_as_float(hi & 0xffff0000u)}; }
;         }
	v_lshlrev_b32_e32 v98, 16, v42
	v_and_b32_e32 v99, 0xffff0000, v42
	v_lshlrev_b32_e32 v42, 16, v43
	v_and_b32_e32 v43, 0xffff0000, v43
	s_waitcnt vmcnt(30)
	v_lshlrev_b32_e32 v100, 16, v44
	v_and_b32_e32 v101, 0xffff0000, v44
	v_lshlrev_b32_e32 v44, 16, v45
	v_and_b32_e32 v45, 0xffff0000, v45
	s_waitcnt vmcnt(29)
	v_lshlrev_b32_e32 v102, 16, v46
	v_and_b32_e32 v103, 0xffff0000, v46
	s_waitcnt vmcnt(3)
	v_lshlrev_b32_e32 v154, 16, v38
	v_and_b32_e32 v155, 0xffff0000, v38
	v_lshlrev_b32_e32 v38, 16, v39
	v_and_b32_e32 v39, 0xffff0000, v39
	s_waitcnt vmcnt(2)
	v_lshlrev_b32_e32 v156, 16, v40
	v_and_b32_e32 v157, 0xffff0000, v40
	v_lshlrev_b32_e32 v40, 16, v41
	v_and_b32_e32 v41, 0xffff0000, v41
	s_waitcnt vmcnt(1)
	v_lshlrev_b32_e32 v158, 16, v90
	v_and_b32_e32 v159, 0xffff0000, v90
	v_lshlrev_b32_e32 v90, 16, v91
	v_and_b32_e32 v91, 0xffff0000, v91
	s_waitcnt vmcnt(0)
	v_lshlrev_b32_e32 v160, 16, v92
	v_and_b32_e32 v161, 0xffff0000, v92
	v_lshlrev_b32_e32 v92, 16, v93
	v_and_b32_e32 v93, 0xffff0000, v93
	v_pk_add_f32 v[14:15], v[38:39], v[14:15]
	v_pk_add_f32 v[12:13], v[154:155], v[12:13]
	v_lshlrev_b32_e32 v46, 16, v47
	v_and_b32_e32 v47, 0xffff0000, v47
	v_lshlrev_b32_e32 v104, 16, v48
	v_and_b32_e32 v105, 0xffff0000, v48
	v_lshlrev_b32_e32 v48, 16, v49
	v_and_b32_e32 v49, 0xffff0000, v49
	v_lshlrev_b32_e32 v106, 16, v50
	v_and_b32_e32 v107, 0xffff0000, v50
	v_lshlrev_b32_e32 v50, 16, v51
	v_and_b32_e32 v51, 0xffff0000, v51
	v_pk_add_f32 v[16:17], v[40:41], v[16:17]
	v_pk_add_f32 v[24:25], v[156:157], v[24:25]
	v_pk_add_f32 v[18:19], v[90:91], v[18:19]
	v_pk_add_f32 v[20:21], v[92:93], v[20:21]
	v_pk_add_f32 v[12:13], v[12:13], v[98:99]
	v_pk_add_f32 v[14:15], v[14:15], v[42:43]
	v_lshlrev_b32_e32 v108, 16, v52
	v_and_b32_e32 v109, 0xffff0000, v52
	v_lshlrev_b32_e32 v52, 16, v53
	v_and_b32_e32 v53, 0xffff0000, v53
	v_lshlrev_b32_e32 v110, 16, v54
	v_and_b32_e32 v111, 0xffff0000, v54
	v_lshlrev_b32_e32 v54, 16, v55
	v_and_b32_e32 v55, 0xffff0000, v55
	v_lshlrev_b32_e32 v112, 16, v56
	v_and_b32_e32 v113, 0xffff0000, v56
	v_lshlrev_b32_e32 v56, 16, v57
	v_and_b32_e32 v57, 0xffff0000, v57
	v_lshlrev_b32_e32 v114, 16, v58
	v_and_b32_e32 v115, 0xffff0000, v58
	v_lshlrev_b32_e32 v58, 16, v59
	v_and_b32_e32 v59, 0xffff0000, v59
	v_pk_add_f32 v[38:39], v[158:159], v[94:95]
	v_pk_add_f32 v[40:41], v[160:161], v[96:97]
	v_pk_add_f32 v[24:25], v[24:25], v[100:101]
	v_pk_add_f32 v[16:17], v[16:17], v[44:45]
	v_pk_add_f32 v[18:19], v[18:19], v[46:47]
	v_pk_add_f32 v[20:21], v[20:21], v[48:49]
	v_pk_add_f32 v[14:15], v[14:15], v[50:51]
	v_pk_add_f32 v[12:13], v[12:13], v[106:107]
	v_lshlrev_b32_e32 v116, 16, v22
	v_and_b32_e32 v117, 0xffff0000, v22
	v_lshlrev_b32_e32 v22, 16, v23
	v_and_b32_e32 v23, 0xffff0000, v23
	v_lshlrev_b32_e32 v118, 16, v60
	v_and_b32_e32 v119, 0xffff0000, v60
	v_lshlrev_b32_e32 v60, 16, v61
	v_and_b32_e32 v61, 0xffff0000, v61
	v_lshlrev_b32_e32 v120, 16, v62
	v_and_b32_e32 v121, 0xffff0000, v62
	v_lshlrev_b32_e32 v62, 16, v63
	v_and_b32_e32 v63, 0xffff0000, v63
	v_lshlrev_b32_e32 v122, 16, v64
	v_and_b32_e32 v123, 0xffff0000, v64
	v_lshlrev_b32_e32 v64, 16, v65
	v_and_b32_e32 v65, 0xffff0000, v65
	v_pk_add_f32 v[38:39], v[38:39], v[102:103]
	v_pk_add_f32 v[40:41], v[40:41], v[104:105]
	v_pk_add_f32 v[16:17], v[16:17], v[52:53]
	v_pk_add_f32 v[24:25], v[24:25], v[108:109]
	v_pk_add_f32 v[18:19], v[18:19], v[54:55]
	v_pk_add_f32 v[20:21], v[20:21], v[56:57]
	v_pk_add_f32 v[12:13], v[12:13], v[114:115]
	v_pk_add_f32 v[14:15], v[14:15], v[58:59]
	v_lshlrev_b32_e32 v124, 16, v66
	v_and_b32_e32 v125, 0xffff0000, v66
	v_lshlrev_b32_e32 v66, 16, v67
	v_and_b32_e32 v67, 0xffff0000, v67
	v_lshlrev_b32_e32 v126, 16, v68
	v_and_b32_e32 v127, 0xffff0000, v68
	v_lshlrev_b32_e32 v68, 16, v69
	v_and_b32_e32 v69, 0xffff0000, v69
	v_lshlrev_b32_e32 v128, 16, v70
	v_and_b32_e32 v129, 0xffff0000, v70
	v_lshlrev_b32_e32 v70, 16, v71
	v_and_b32_e32 v71, 0xffff0000, v71
	v_lshlrev_b32_e32 v130, 16, v72
	v_and_b32_e32 v131, 0xffff0000, v72
	v_lshlrev_b32_e32 v72, 16, v73
	v_and_b32_e32 v73, 0xffff0000, v73
	v_pk_add_f32 v[38:39], v[38:39], v[110:111]
	v_pk_add_f32 v[40:41], v[40:41], v[112:113]
	v_pk_add_f32 v[24:25], v[24:25], v[116:117]
	v_pk_add_f32 v[16:17], v[16:17], v[22:23]
	v_pk_add_f32 v[18:19], v[18:19], v[60:61]
	v_pk_add_f32 v[20:21], v[20:21], v[62:63]
	v_pk_add_f32 v[14:15], v[14:15], v[64:65]
	v_pk_add_f32 v[12:13], v[12:13], v[122:123]
	v_lshlrev_b32_e32 v132, 16, v74
	v_and_b32_e32 v133, 0xffff0000, v74
	v_lshlrev_b32_e32 v74, 16, v75
	v_and_b32_e32 v75, 0xffff0000, v75
	v_lshlrev_b32_e32 v134, 16, v76
	v_and_b32_e32 v135, 0xffff0000, v76
	v_lshlrev_b32_e32 v76, 16, v77
	v_and_b32_e32 v77, 0xffff0000, v77
	v_lshlrev_b32_e32 v136, 16, v78
	v_and_b32_e32 v137, 0xffff0000, v78
	v_lshlrev_b32_e32 v78, 16, v79
	v_and_b32_e32 v79, 0xffff0000, v79
	v_lshlrev_b32_e32 v138, 16, v80
	v_and_b32_e32 v139, 0xffff0000, v80
	v_lshlrev_b32_e32 v80, 16, v81
	v_and_b32_e32 v81, 0xffff0000, v81
	v_pk_add_f32 v[22:23], v[38:39], v[118:119]
	v_pk_add_f32 v[38:39], v[40:41], v[120:121]
	v_pk_add_f32 v[16:17], v[16:17], v[66:67]
; __device__ __forceinline__ unsigned pk2(float lo, float hi) { return pg8::cvt_pk_bf16(lo, hi); }
; template <bool FINAL>
; __device__ __forceinline__ void sample_fixup(const Params& p, int S, float* ss_s, const float* gf) {
;     ...
;         float s = 0.f;
; #pragma unroll
;         for (int j = 0; j < 4; ++j) s += (v[j][0] * v[j][0] + v[j][1] * v[j][1]) + (v[j][2] * v[j][2] + v[j][3] * v[j][3]);
;         s = wave_sum(s);
;         if (!FINAL) {
; #pragma unroll
;             for (int j = 0; j < 4; ++j) o8[64 * j] = (unsigned long long)pk2(v[j][0], v[j][1]) | ((unsigned long long)pk2(v[j][2], v[j][3]) << 32);
;             if (lane == 0) ss_s[r] = s;
;         } else {
;             const float rs = __builtin_amdgcn_rsqf(s * (1.f / 1024.f) + EPS);
; #pragma unroll
;             for (int j = 0; j < 4; ++j) *((f32x4*)(xo + (size_t)r * D) + lane + 64 * j) = v[j] * rs * *((const f32x4*)gf + lane + 64 * j);
	v_pk_add_f32 v[24:25], v[24:25], v[124:125]
	v_pk_add_f32 v[18:19], v[18:19], v[68:69]
	v_pk_add_f32 v[20:21], v[20:21], v[70:71]
	v_pk_add_f32 v[12:13], v[12:13], v[130:131]
	v_pk_add_f32 v[14:15], v[14:15], v[72:73]
	v_lshlrev_b32_e32 v140, 16, v82
	v_and_b32_e32 v141, 0xffff0000, v82
	v_lshlrev_b32_e32 v82, 16, v83
	v_and_b32_e32 v83, 0xffff0000, v83
	v_lshlrev_b32_e32 v142, 16, v84
	v_and_b32_e32 v143, 0xffff0000, v84
	v_lshlrev_b32_e32 v84, 16, v85
	v_and_b32_e32 v85, 0xffff0000, v85
	v_lshlrev_b32_e32 v144, 16, v86
	v_and_b32_e32 v145, 0xffff0000, v86
	v_lshlrev_b32_e32 v86, 16, v87
	v_and_b32_e32 v87, 0xffff0000, v87
	v_lshlrev_b32_e32 v146, 16, v88
	v_and_b32_e32 v147, 0xffff0000, v88
	v_lshlrev_b32_e32 v88, 16, v89
	v_and_b32_e32 v89, 0xffff0000, v89
	v_pk_add_f32 v[38:39], v[38:39], v[128:129]
	v_pk_add_f32 v[24:25], v[24:25], v[132:133]
	v_pk_add_f32 v[16:17], v[16:17], v[74:75]
	v_pk_add_f32 v[18:19], v[18:19], v[76:77]
	v_pk_add_f32 v[20:21], v[20:21], v[78:79]
	v_pk_add_f32 v[14:15], v[14:15], v[80:81]
	v_pk_add_f32 v[12:13], v[12:13], v[138:139]
	v_lshlrev_b32_e32 v148, 16, v26
	v_and_b32_e32 v149, 0xffff0000, v26
	v_lshlrev_b32_e32 v26, 16, v27
	v_and_b32_e32 v27, 0xffff0000, v27
	v_lshlrev_b32_e32 v150, 16, v28
	v_and_b32_e32 v151, 0xffff0000, v28
	v_lshlrev_b32_e32 v28, 16, v29
	v_and_b32_e32 v29, 0xffff0000, v29
	v_lshlrev_b32_e32 v152, 16, v36
	v_and_b32_e32 v153, 0xffff0000, v36
	v_lshlrev_b32_e32 v36, 16, v37
	v_and_b32_e32 v37, 0xffff0000, v37
	v_pk_add_f32 v[22:23], v[22:23], v[126:127]
	v_pk_add_f32 v[38:39], v[38:39], v[136:137]
	v_pk_add_f32 v[16:17], v[16:17], v[82:83]
	v_pk_add_f32 v[24:25], v[24:25], v[140:141]
	v_pk_add_f32 v[18:19], v[18:19], v[84:85]
	v_pk_add_f32 v[20:21], v[20:21], v[86:87]
	v_pk_add_f32 v[12:13], v[12:13], v[146:147]
	v_pk_add_f32 v[14:15], v[14:15], v[88:89]
	v_pk_add_f32 v[22:23], v[22:23], v[134:135]
	v_pk_add_f32 v[38:39], v[38:39], v[144:145]
	v_pk_add_f32 v[24:25], v[24:25], v[148:149]
	v_pk_add_f32 v[16:17], v[16:17], v[26:27]
	v_pk_add_f32 v[18:19], v[18:19], v[28:29]
	v_pk_add_f32 v[20:21], v[20:21], v[36:37]
	v_pk_mul_f32 v[28:29], v[14:15], v[14:15]
	v_pk_mul_f32 v[36:37], v[12:13], v[12:13]
	v_pk_add_f32 v[22:23], v[22:23], v[142:143]
	v_pk_add_f32 v[26:27], v[38:39], v[152:153]
	v_pk_mov_b32 v[38:39], v[36:37], v[28:29] op_sel:[1,0]
	v_mov_b32_e32 v37, v29
	v_pk_mul_f32 v[28:29], v[16:17], v[16:17]
	v_pk_mul_f32 v[40:41], v[24:25], v[24:25]
	v_pk_add_f32 v[22:23], v[22:23], v[150:151]
	v_pk_add_f32 v[36:37], v[38:39], v[36:37]
	v_pk_mov_b32 v[38:39], v[40:41], v[28:29] op_sel:[1,0]
	v_mov_b32_e32 v41, v29
	v_mul_f32_e32 v45, v26, v26
	v_mul_f32_e32 v42, v23, v23
	v_mul_f32_e32 v44, v19, v19
	v_pk_add_f32 v[38:39], v[38:39], v[40:41]
	v_mul_f32_e32 v46, v27, v27
	v_mul_f32_e32 v47, v20, v20
	v_mul_f32_e32 v48, v21, v21
	v_pk_fma_f32 v[28:29], v[22:23], v[22:23], v[42:43] op_sel_hi:[1,1,0]
	v_pk_fma_f32 v[42:43], v[18:19], v[18:19], v[44:45] op_sel_hi:[1,1,0]
	v_pk_add_f32 v[36:37], v[36:37], v[36:37] op_sel:[0,1] op_sel_hi:[1,0]
	v_pk_add_f32 v[38:39], v[38:39], v[38:39] op_sel:[0,1] op_sel_hi:[1,0]
	v_mov_b32_e32 v29, v47
	v_mov_b32_e32 v43, v48
	v_mov_b32_e32 v37, v45
	v_mov_b32_e32 v39, v46
	v_pk_add_f32 v[28:29], v[28:29], v[42:43]
	v_pk_add_f32 v[36:37], v[36:37], v[38:39]
	s_nop 0
	v_pk_add_f32 v[28:29], v[36:37], v[28:29]
	s_nop 0
	v_add_f32_e32 v28, v28, v29
	ds_bpermute_b32 v29, v30, v28
	s_waitcnt lgkmcnt(0)
	v_add_f32_e32 v28, v28, v29
	ds_bpermute_b32 v29, v31, v28
	s_waitcnt lgkmcnt(0)
	v_add_f32_e32 v28, v28, v29
	ds_bpermute_b32 v29, v32, v28
	s_waitcnt lgkmcnt(0)
	v_add_f32_e32 v28, v28, v29
	ds_bpermute_b32 v29, v33, v28
	s_waitcnt lgkmcnt(0)
	v_add_f32_e32 v28, v28, v29
	ds_bpermute_b32 v29, v34, v28
	s_waitcnt lgkmcnt(0)
	v_add_f32_e32 v28, v28, v29
	ds_bpermute_b32 v29, v35, v28
	s_waitcnt lgkmcnt(0)
	v_add_f32_e32 v28, v28, v29
	v_fmamk_f32 v28, v28, 0x3a800000, v5
	v_rsq_f32_e32 v28, v28
	s_nop 0
	v_pk_mul_f32 v[12:13], v[12:13], v[28:29] op_sel_hi:[1,0]
	v_pk_mul_f32 v[14:15], v[14:15], v[28:29] op_sel_hi:[1,0]
	v_pk_mul_f32 v[0:1], v[0:1], v[12:13]
	v_pk_mul_f32 v[2:3], v[2:3], v[14:15]
	global_store_dwordx4 v[10:11], v[0:3], off
	v_pk_mul_f32 v[12:13], v[16:17], v[28:29] op_sel_hi:[1,0]
	v_pk_mul_f32 v[14:15], v[24:25], v[28:29] op_sel_hi:[1,0]
	v_pk_mul_f32 v[178:179], v[166:167], v[12:13]
	v_pk_mul_f32 v[176:177], v[164:165], v[14:15]
	global_store_dwordx4 v[10:11], v[176:179], off offset:1024
	v_pk_mul_f32 v[12:13], v[18:19], v[28:29] op_sel_hi:[1,0]
	v_pk_mul_f32 v[14:15], v[22:23], v[28:29] op_sel_hi:[1,0]
	v_pk_mul_f32 v[182:183], v[170:171], v[12:13]
	v_pk_mul_f32 v[180:181], v[168:169], v[14:15]
	global_store_dwordx4 v[10:11], v[180:183], off offset:2048
	v_pk_mul_f32 v[12:13], v[20:21], v[28:29] op_sel_hi:[1,0]
	v_pk_mul_f32 v[14:15], v[26:27], v[28:29] op_sel_hi:[1,0]
	v_pk_mul_f32 v[186:187], v[174:175], v[12:13]
	v_pk_mul_f32 v[184:185], v[172:173], v[14:15]
	global_store_dwordx4 v[10:11], v[184:187], off offset:3072
	v_lshl_add_u64 v[10:11], v[10:11], 0, s[6:7]
	s_andn2_b64 exec, exec, s[8:9]
	s_cbranch_execnz .LBB0_1390
